# trailing s_barrier of every GEMM MFMA segment moved two MFMAs up, tail MFMAs under s_setprio 3 (was one MFMA up)
# baseline (speedup 1.0000x reference)
; #define PG8_STAGE(bufoff, gbase, voff) do { _Pragma("unroll") for (int _i = 0; _i < 2; ++_i) \
;         __builtin_amdgcn_global_load_lds((const unsigned*)((const char*)(gbase) + (voff)[_i]), (PG8_LAS unsigned*)(lds + (bufoff) + ldsw + _i * 8192), 16, 0, 0); } while (0)
; #define PG8_LDA(dst, b, h) do { _Pragma("unroll") for (int m = 0; m < 4; ++m) _Pragma("unroll") for (int k = 0; k < 2; ++k) dst[m][k] = *(const PG8_LAS bf16x8*)(lds + PG8_SA(b, h) + aoff + m * 2048 + k * 1024); } while (0)
; #define PG8_LDB(dst, b, h) do { _Pragma("unroll") for (int n = 0; n < 2; ++n) _Pragma("unroll") for (int k = 0; k < 2; ++k) dst[n][k] = *(const PG8_LAS bf16x8*)(lds + PG8_SB(b, h) + boff + n * 2048 + k * 1024); } while (0)
; #define PG8_MMA(ai, bj, At, Bt) do { __builtin_amdgcn_s_setprio(1); _Pragma("unroll") for (int m = 0; m < 4; ++m) _Pragma("unroll") for (int n = 0; n < 2; ++n) _Pragma("unroll") for (int k = 0; k < 2; ++k) \
;         acc[ai][bj][m][n] = __builtin_amdgcn_mfma_f32_16x16x32_bf16(Bt[n][k], At[m][k], acc[ai][bj][m][n], 0, 0, 0); __builtin_amdgcn_s_setprio(0); } while (0)
; #define PG8_WAIT_V(n) asm volatile("s_waitcnt vmcnt(" #n ")" ::: "memory")
; #define PG8_WAIT_L(n) asm volatile("s_waitcnt lgkmcnt(" #n ")" ::: "memory")
; #define PG8_BAR __builtin_amdgcn_s_barrier()
; #define PG8_SCHED __builtin_amdgcn_sched_barrier(0)
; template <class Epi, class Sched, bool ALIGN_EPI = false, bool SP2 = false>
; __device__ __forceinline__ void gemm_phase(PG8_LAS unsigned char* lds, const Gemm g, const Sched& S, const Epi& E) {
;     ...
;             PG8_LDB(B0, 0, 0); PG8_LDB(B1, 0, 1); PG8_SCHED; PG8_LDA(At, 0, 0); PG8_STAGE(PG8_SA(1, 1), a1 + hstep, voffA);
;             PG8_WAIT_V(8); PG8_WAIT_L(0); PG8_BAR; PG8_MMA(0, 0, At, B0); PG8_MMA(0, 1, At, B1); PG8_BAR; PG8_SCHED;
;             PG8_LDA(At, 0, 1); PG8_STAGE(PG8_SB(0, 0), b2, voffB); PG8_STAGE(PG8_SB(0, 1), b2 + hstep, voffB); PG8_STAGE(PG8_SA(0, 0), a2, voffA);
;             PG8_WAIT_V(8); PG8_WAIT_L(0); PG8_BAR; PG8_MMA(1, 0, At, B0); PG8_MMA(1, 1, At, B1); PG8_BAR; PG8_SCHED;
.LBB0_141:
	ds_read_b128 v[130:133], v196
	ds_read_b128 v[134:137], v196 offset:1024
	ds_read_b128 v[138:141], v196 offset:2048
	ds_read_b128 v[142:145], v196 offset:3072
	s_waitcnt lgkmcnt(0)
	ds_read_b128 v[170:173], v197
	ds_read_b128 v[174:177], v197 offset:1024
	ds_read_b128 v[178:181], v197 offset:2048
	ds_read_b128 v[182:185], v197 offset:3072
	s_add_u32 s18, s84, 0xfffc0080
	s_addc_u32 s19, s85, -1
	s_cmp_eq_u32 vcc_lo, 12
	s_cselect_b32 s87, s7, s19
	s_cselect_b32 s86, s9, s18
	s_cselect_b32 s31, s10, s75
	s_cselect_b32 s30, s69, s73
	v_lshl_add_u64 v[190:191], s[84:85], 0, v[162:163]
	s_add_i32 m0, s91, 0xc000
	ds_read_b128 v[186:189], v198
	ds_read_b128 v[202:205], v198 offset:1024
	ds_read_b128 v[208:211], v198 offset:2048
	ds_read_b128 v[212:215], v198 offset:3072
	ds_read_b128 v[216:219], v198 offset:4096
	ds_read_b128 v[220:223], v198 offset:5120
	ds_read_b128 v[224:227], v198 offset:6144
	ds_read_b128 v[228:231], v198 offset:7168
	global_load_lds_dwordx4 v[190:191], off
	v_lshl_add_u64 v[190:191], s[84:85], 0, v[164:165]
	s_add_i32 m0, s91, 0xe000
	s_nop 0
	global_load_lds_dwordx4 v[190:191], off
	s_waitcnt vmcnt(8)
	s_waitcnt lgkmcnt(0)
	s_setprio 1
	s_barrier
	s_waitcnt lgkmcnt(0)
	v_mfma_f32_16x16x32_bf16 v[126:129], v[130:133], v[186:189], v[126:129]
	v_mfma_f32_16x16x32_bf16 v[122:125], v[138:141], v[186:189], v[122:125]
	v_mfma_f32_16x16x32_bf16 v[110:113], v[130:133], v[208:211], v[110:113]
	v_mfma_f32_16x16x32_bf16 v[106:109], v[138:141], v[208:211], v[106:109]
	v_mfma_f32_16x16x32_bf16 v[94:97], v[130:133], v[216:219], v[94:97]
	v_mfma_f32_16x16x32_bf16 v[90:93], v[138:141], v[216:219], v[90:93]
	v_mfma_f32_16x16x32_bf16 v[78:81], v[130:133], v[224:227], v[78:81]
	v_mfma_f32_16x16x32_bf16 v[74:77], v[138:141], v[224:227], v[74:77]
	v_mfma_f32_16x16x32_bf16 v[126:129], v[134:137], v[202:205], v[126:129]
	v_mfma_f32_16x16x32_bf16 v[122:125], v[142:145], v[202:205], v[122:125]
	v_mfma_f32_16x16x32_bf16 v[110:113], v[134:137], v[212:215], v[110:113]
	v_mfma_f32_16x16x32_bf16 v[106:109], v[142:145], v[212:215], v[106:109]
	v_mfma_f32_16x16x32_bf16 v[94:97], v[134:137], v[220:223], v[94:97]
	v_mfma_f32_16x16x32_bf16 v[90:93], v[142:145], v[220:223], v[90:93]
	v_mfma_f32_16x16x32_bf16 v[78:81], v[134:137], v[228:231], v[78:81]
	v_mfma_f32_16x16x32_bf16 v[74:77], v[142:145], v[228:231], v[74:77]
	s_setprio 0
	s_setprio 1
	v_mfma_f32_16x16x32_bf16 v[118:121], v[170:173], v[186:189], v[118:121]
	v_mfma_f32_16x16x32_bf16 v[114:117], v[178:181], v[186:189], v[114:117]
	v_mfma_f32_16x16x32_bf16 v[102:105], v[170:173], v[208:211], v[102:105]
	v_mfma_f32_16x16x32_bf16 v[98:101], v[178:181], v[208:211], v[98:101]
	v_mfma_f32_16x16x32_bf16 v[86:89], v[170:173], v[216:219], v[86:89]
	v_mfma_f32_16x16x32_bf16 v[82:85], v[178:181], v[216:219], v[82:85]
	v_mfma_f32_16x16x32_bf16 v[70:73], v[170:173], v[224:227], v[70:73]
	v_mfma_f32_16x16x32_bf16 v[66:69], v[178:181], v[224:227], v[66:69]
	v_mfma_f32_16x16x32_bf16 v[118:121], v[174:177], v[202:205], v[118:121]
	v_mfma_f32_16x16x32_bf16 v[114:117], v[182:185], v[202:205], v[114:117]
	v_mfma_f32_16x16x32_bf16 v[102:105], v[174:177], v[212:215], v[102:105]
	v_mfma_f32_16x16x32_bf16 v[98:101], v[182:185], v[212:215], v[98:101]
	v_mfma_f32_16x16x32_bf16 v[86:89], v[174:177], v[220:223], v[86:89]
	v_mfma_f32_16x16x32_bf16 v[82:85], v[182:185], v[220:223], v[82:85]
	s_setprio 3
	s_barrier
	v_mfma_f32_16x16x32_bf16 v[70:73], v[174:177], v[228:231], v[70:73]
	v_mfma_f32_16x16x32_bf16 v[66:69], v[182:185], v[228:231], v[66:69]
	s_setprio 0
	s_add_i32 s18, s58, s88
	v_lshl_add_u64 v[190:191], s[30:31], 0, v[148:149]
	s_mov_b32 m0, s18
	ds_read_b128 v[186:189], v198 offset:16384
	ds_read_b128 v[202:205], v198 offset:17408
	ds_read_b128 v[208:211], v198 offset:18432
	ds_read_b128 v[212:215], v198 offset:19456
	ds_read_b128 v[216:219], v198 offset:20480
	ds_read_b128 v[220:223], v198 offset:21504
	ds_read_b128 v[224:227], v198 offset:22528
	ds_read_b128 v[228:231], v198 offset:23552
	global_load_lds_dwordx4 v[190:191], off
	s_add_i32 m0, s18, 0x2000
	s_add_u32 s18, s30, 0x40000
	v_lshl_add_u64 v[232:233], s[30:31], 0, v[152:153]
	s_addc_u32 s19, s31, 0
	s_add_i32 vcc_hi, s59, s88
	global_load_lds_dwordx4 v[232:233], off
	v_lshl_add_u64 v[234:235], s[18:19], 0, v[148:149]
	s_mov_b32 m0, vcc_hi
	v_lshl_add_u64 v[238:239], s[86:87], 0, v[150:151]
	global_load_lds_dwordx4 v[234:235], off
	v_lshl_add_u64 v[234:235], s[18:19], 0, v[152:153]
	s_add_i32 m0, vcc_hi, 0x2000
	s_nop 0
	global_load_lds_dwordx4 v[234:235], off
	v_lshl_add_u64 v[234:235], s[86:87], 0, v[146:147]
	s_mov_b32 m0, s91
	s_nop 0
	global_load_lds_dwordx4 v[234:235], off
	s_mov_b32 m0, s92
	s_nop 0
	global_load_lds_dwordx4 v[238:239], off
	s_waitcnt vmcnt(8)
	s_waitcnt lgkmcnt(0)
	s_setprio 1
	s_barrier
; #define PG8_STAGE(bufoff, gbase, voff) do { _Pragma("unroll") for (int _i = 0; _i < 2; ++_i) \
;         __builtin_amdgcn_global_load_lds((const unsigned*)((const char*)(gbase) + (voff)[_i]), (PG8_LAS unsigned*)(lds + (bufoff) + ldsw + _i * 8192), 16, 0, 0); } while (0)
; #define PG8_LDA(dst, b, h) do { _Pragma("unroll") for (int m = 0; m < 4; ++m) _Pragma("unroll") for (int k = 0; k < 2; ++k) dst[m][k] = *(const PG8_LAS bf16x8*)(lds + PG8_SA(b, h) + aoff + m * 2048 + k * 1024); } while (0)
; #define PG8_LDB(dst, b, h) do { _Pragma("unroll") for (int n = 0; n < 2; ++n) _Pragma("unroll") for (int k = 0; k < 2; ++k) dst[n][k] = *(const PG8_LAS bf16x8*)(lds + PG8_SB(b, h) + boff + n * 2048 + k * 1024); } while (0)
; #define PG8_MMA(ai, bj, At, Bt) do { __builtin_amdgcn_s_setprio(1); _Pragma("unroll") for (int m = 0; m < 4; ++m) _Pragma("unroll") for (int n = 0; n < 2; ++n) _Pragma("unroll") for (int k = 0; k < 2; ++k) \
;         acc[ai][bj][m][n] = __builtin_amdgcn_mfma_f32_16x16x32_bf16(Bt[n][k], At[m][k], acc[ai][bj][m][n], 0, 0, 0); __builtin_amdgcn_s_setprio(0); } while (0)
; #define PG8_WAIT_V(n) asm volatile("s_waitcnt vmcnt(" #n ")" ::: "memory")
; #define PG8_WAIT_L(n) asm volatile("s_waitcnt lgkmcnt(" #n ")" ::: "memory")
; #define PG8_BAR __builtin_amdgcn_s_barrier()
; #define PG8_SCHED __builtin_amdgcn_sched_barrier(0)
; template <class Epi, class Sched, bool ALIGN_EPI = false, bool SP2 = false>
; __device__ __forceinline__ void gemm_phase(PG8_LAS unsigned char* lds, const Gemm g, const Sched& S, const Epi& E) {
;     ...
;             PG8_WAIT_V(8); PG8_WAIT_L(0); PG8_BAR; PG8_MMA(1, 0, At, B0); PG8_MMA(1, 1, At, B1); PG8_BAR; PG8_SCHED;
;             PG8_LDB(B0, 1, 0); PG8_LDB(B1, 1, 1); PG8_SCHED; PG8_LDA(At, 1, 0); PG8_STAGE(PG8_SA(0, 1), a2 + hstep, voffA);
;             PG8_WAIT_V(8); PG8_WAIT_L(0); PG8_BAR; PG8_MMA(0, 0, At, B0); PG8_MMA(0, 1, At, B1); PG8_BAR; PG8_SCHED;
	s_waitcnt lgkmcnt(0)
	v_mfma_f32_16x16x32_bf16 v[62:65], v[130:133], v[186:189], v[62:65]
	v_mfma_f32_16x16x32_bf16 v[58:61], v[138:141], v[186:189], v[58:61]
	v_mfma_f32_16x16x32_bf16 v[46:49], v[130:133], v[208:211], v[46:49]
	v_mfma_f32_16x16x32_bf16 v[42:45], v[138:141], v[208:211], v[42:45]
	v_mfma_f32_16x16x32_bf16 v[30:33], v[130:133], v[216:219], v[30:33]
	v_mfma_f32_16x16x32_bf16 v[26:29], v[138:141], v[216:219], v[26:29]
	v_mfma_f32_16x16x32_bf16 v[14:17], v[130:133], v[224:227], v[14:17]
	v_mfma_f32_16x16x32_bf16 v[10:13], v[138:141], v[224:227], v[10:13]
	v_mfma_f32_16x16x32_bf16 v[62:65], v[134:137], v[202:205], v[62:65]
	v_mfma_f32_16x16x32_bf16 v[58:61], v[142:145], v[202:205], v[58:61]
	v_mfma_f32_16x16x32_bf16 v[46:49], v[134:137], v[212:215], v[46:49]
	v_mfma_f32_16x16x32_bf16 v[42:45], v[142:145], v[212:215], v[42:45]
	v_mfma_f32_16x16x32_bf16 v[30:33], v[134:137], v[220:223], v[30:33]
	v_mfma_f32_16x16x32_bf16 v[26:29], v[142:145], v[220:223], v[26:29]
	v_mfma_f32_16x16x32_bf16 v[14:17], v[134:137], v[228:231], v[14:17]
	v_mfma_f32_16x16x32_bf16 v[10:13], v[142:145], v[228:231], v[10:13]
	s_setprio 0
	s_setprio 1
	v_mfma_f32_16x16x32_bf16 v[54:57], v[170:173], v[186:189], v[54:57]
	v_mfma_f32_16x16x32_bf16 v[50:53], v[178:181], v[186:189], v[50:53]
	v_mfma_f32_16x16x32_bf16 v[38:41], v[170:173], v[208:211], v[38:41]
	v_mfma_f32_16x16x32_bf16 v[34:37], v[178:181], v[208:211], v[34:37]
	v_mfma_f32_16x16x32_bf16 v[22:25], v[170:173], v[216:219], v[22:25]
	v_mfma_f32_16x16x32_bf16 v[18:21], v[178:181], v[216:219], v[18:21]
	v_mfma_f32_16x16x32_bf16 v[6:9], v[170:173], v[224:227], v[6:9]
	v_mfma_f32_16x16x32_bf16 v[2:5], v[178:181], v[224:227], v[2:5]
	v_mfma_f32_16x16x32_bf16 v[54:57], v[174:177], v[202:205], v[54:57]
	v_mfma_f32_16x16x32_bf16 v[50:53], v[182:185], v[202:205], v[50:53]
	v_mfma_f32_16x16x32_bf16 v[38:41], v[174:177], v[212:215], v[38:41]
	v_mfma_f32_16x16x32_bf16 v[34:37], v[182:185], v[212:215], v[34:37]
	v_mfma_f32_16x16x32_bf16 v[22:25], v[174:177], v[220:223], v[22:25]
	v_mfma_f32_16x16x32_bf16 v[18:21], v[182:185], v[220:223], v[18:21]
	s_setprio 3
	s_barrier
	v_mfma_f32_16x16x32_bf16 v[6:9], v[174:177], v[228:231], v[6:9]
	v_mfma_f32_16x16x32_bf16 v[2:5], v[182:185], v[228:231], v[2:5]
	s_setprio 0
	s_add_i32 vcc_hi, 0, 0x18000
	s_add_i32 s52, 0, 0x1c000
	v_add_u32_e32 v142, vcc_hi, v157
	v_add_u32_e32 v154, s52, v157
	ds_read_b128 v[130:133], v142
	ds_read_b128 v[134:137], v142 offset:1024
	ds_read_b128 v[138:141], v142 offset:2048
	ds_read_b128 v[142:145], v142 offset:3072
	ds_read_b128 v[170:173], v154
	ds_read_b128 v[174:177], v154 offset:1024
	ds_read_b128 v[178:181], v154 offset:2048
	ds_read_b128 v[182:185], v154 offset:3072
	s_add_u32 s18, s86, 0x40000
	s_addc_u32 s19, s87, 0
	s_mov_b32 m0, s93
	v_lshl_add_u64 v[240:241], s[18:19], 0, v[146:147]
	ds_read_b128 v[186:189], v198 offset:32768
	ds_read_b128 v[202:205], v198 offset:33792
	ds_read_b128 v[208:211], v198 offset:34816
	ds_read_b128 v[212:215], v198 offset:35840
	ds_read_b128 v[216:219], v198 offset:36864
	ds_read_b128 v[220:223], v198 offset:37888
	ds_read_b128 v[224:227], v198 offset:38912
	ds_read_b128 v[228:231], v198 offset:39936
	global_load_lds_dwordx4 v[240:241], off
	v_lshl_add_u64 v[240:241], s[18:19], 0, v[150:151]
	s_mov_b32 m0, s95
	s_nop 0
	global_load_lds_dwordx4 v[240:241], off
	s_waitcnt vmcnt(8)
	s_waitcnt lgkmcnt(0)
	s_setprio 1
	s_barrier
	s_waitcnt lgkmcnt(0)
	v_mfma_f32_16x16x32_bf16 v[126:129], v[130:133], v[186:189], v[126:129]
	v_mfma_f32_16x16x32_bf16 v[122:125], v[138:141], v[186:189], v[122:125]
	v_mfma_f32_16x16x32_bf16 v[110:113], v[130:133], v[208:211], v[110:113]
	v_mfma_f32_16x16x32_bf16 v[106:109], v[138:141], v[208:211], v[106:109]
	v_mfma_f32_16x16x32_bf16 v[94:97], v[130:133], v[216:219], v[94:97]
	v_mfma_f32_16x16x32_bf16 v[90:93], v[138:141], v[216:219], v[90:93]
	v_mfma_f32_16x16x32_bf16 v[78:81], v[130:133], v[224:227], v[78:81]
	v_mfma_f32_16x16x32_bf16 v[74:77], v[138:141], v[224:227], v[74:77]
	v_mfma_f32_16x16x32_bf16 v[126:129], v[134:137], v[202:205], v[126:129]
	v_mfma_f32_16x16x32_bf16 v[122:125], v[142:145], v[202:205], v[122:125]
	v_mfma_f32_16x16x32_bf16 v[110:113], v[134:137], v[212:215], v[110:113]
	v_mfma_f32_16x16x32_bf16 v[106:109], v[142:145], v[212:215], v[106:109]
	v_mfma_f32_16x16x32_bf16 v[94:97], v[134:137], v[220:223], v[94:97]
	v_mfma_f32_16x16x32_bf16 v[90:93], v[142:145], v[220:223], v[90:93]
	v_mfma_f32_16x16x32_bf16 v[78:81], v[134:137], v[228:231], v[78:81]
	v_mfma_f32_16x16x32_bf16 v[74:77], v[142:145], v[228:231], v[74:77]
	s_setprio 0
	s_setprio 1
	v_mfma_f32_16x16x32_bf16 v[118:121], v[170:173], v[186:189], v[118:121]
	v_mfma_f32_16x16x32_bf16 v[114:117], v[178:181], v[186:189], v[114:117]
	v_mfma_f32_16x16x32_bf16 v[102:105], v[170:173], v[208:211], v[102:105]
	v_mfma_f32_16x16x32_bf16 v[98:101], v[178:181], v[208:211], v[98:101]
	v_mfma_f32_16x16x32_bf16 v[86:89], v[170:173], v[216:219], v[86:89]
	v_mfma_f32_16x16x32_bf16 v[82:85], v[178:181], v[216:219], v[82:85]
	v_mfma_f32_16x16x32_bf16 v[70:73], v[170:173], v[224:227], v[70:73]
	v_mfma_f32_16x16x32_bf16 v[66:69], v[178:181], v[224:227], v[66:69]
	v_mfma_f32_16x16x32_bf16 v[118:121], v[174:177], v[202:205], v[118:121]
	v_mfma_f32_16x16x32_bf16 v[114:117], v[182:185], v[202:205], v[114:117]
	v_mfma_f32_16x16x32_bf16 v[102:105], v[174:177], v[212:215], v[102:105]
	v_mfma_f32_16x16x32_bf16 v[98:101], v[182:185], v[212:215], v[98:101]
	v_mfma_f32_16x16x32_bf16 v[86:89], v[174:177], v[220:223], v[86:89]
	v_mfma_f32_16x16x32_bf16 v[82:85], v[182:185], v[220:223], v[82:85]
	s_setprio 3
	s_barrier
; #define PG8_STAGE(bufoff, gbase, voff) do { _Pragma("unroll") for (int _i = 0; _i < 2; ++_i) \
;         __builtin_amdgcn_global_load_lds((const unsigned*)((const char*)(gbase) + (voff)[_i]), (PG8_LAS unsigned*)(lds + (bufoff) + ldsw + _i * 8192), 16, 0, 0); } while (0)
; #define PG8_LDA(dst, b, h) do { _Pragma("unroll") for (int m = 0; m < 4; ++m) _Pragma("unroll") for (int k = 0; k < 2; ++k) dst[m][k] = *(const PG8_LAS bf16x8*)(lds + PG8_SA(b, h) + aoff + m * 2048 + k * 1024); } while (0)
; #define PG8_MMA(ai, bj, At, Bt) do { __builtin_amdgcn_s_setprio(1); _Pragma("unroll") for (int m = 0; m < 4; ++m) _Pragma("unroll") for (int n = 0; n < 2; ++n) _Pragma("unroll") for (int k = 0; k < 2; ++k) \
;         acc[ai][bj][m][n] = __builtin_amdgcn_mfma_f32_16x16x32_bf16(Bt[n][k], At[m][k], acc[ai][bj][m][n], 0, 0, 0); __builtin_amdgcn_s_setprio(0); } while (0)
; #define PG8_WAIT_V(n) asm volatile("s_waitcnt vmcnt(" #n ")" ::: "memory")
; #define PG8_WAIT_L(n) asm volatile("s_waitcnt lgkmcnt(" #n ")" ::: "memory")
; #define PG8_BAR __builtin_amdgcn_s_barrier()
; #define PG8_SCHED __builtin_amdgcn_sched_barrier(0)
; template <class Epi, class Sched, bool ALIGN_EPI = false, bool SP2 = false>
; __device__ __forceinline__ void gemm_phase(PG8_LAS unsigned char* lds, const Gemm g, const Sched& S, const Epi& E) {
;     ...
;             PG8_LDA(At, 1, 1); PG8_STAGE(PG8_SB(1, 0), b3, voffB); PG8_STAGE(PG8_SB(1, 1), b3 + hstep, voffB); PG8_STAGE(PG8_SA(1, 0), a3, voffA);
;             PG8_WAIT_V(8); PG8_WAIT_L(0); PG8_BAR; PG8_MMA(1, 0, At, B0); PG8_MMA(1, 1, At, B1); PG8_BAR; PG8_SCHED;
	v_mfma_f32_16x16x32_bf16 v[70:73], v[174:177], v[228:231], v[70:73]
	v_mfma_f32_16x16x32_bf16 v[66:69], v[182:185], v[228:231], v[66:69]
	s_setprio 0
	s_add_i32 s18, vcc_hi, s88
	v_lshl_add_u64 v[190:191], v[190:191], 0, s[16:17]
	s_mov_b32 m0, s18
	ds_read_b128 v[186:189], v198 offset:49152
	ds_read_b128 v[202:205], v198 offset:50176
	ds_read_b128 v[208:211], v198 offset:51200
	ds_read_b128 v[212:215], v198 offset:52224
	ds_read_b128 v[216:219], v198 offset:53248
	ds_read_b128 v[220:223], v198 offset:54272
	ds_read_b128 v[224:227], v198 offset:55296
	ds_read_b128 v[228:231], v198 offset:56320
	global_load_lds_dwordx4 v[190:191], off
	s_add_i32 m0, s18, 0x2000
	s_add_u32 s18, s30, 0x40080
	v_lshl_add_u64 v[190:191], v[232:233], 0, s[16:17]
	s_addc_u32 s19, s31, 0
	s_add_i32 s30, s52, s88
	global_load_lds_dwordx4 v[190:191], off
	v_lshl_add_u64 v[190:191], s[18:19], 0, v[148:149]
	s_mov_b32 m0, s30
	s_nop 0
	global_load_lds_dwordx4 v[190:191], off
	v_lshl_add_u64 v[190:191], s[18:19], 0, v[152:153]
	s_add_i32 m0, s30, 0x2000
	s_nop 0
	global_load_lds_dwordx4 v[190:191], off
	v_lshl_add_u64 v[190:191], v[234:235], 0, s[16:17]
	s_mov_b32 m0, s24
	s_nop 0
	global_load_lds_dwordx4 v[190:191], off
	v_lshl_add_u64 v[190:191], v[238:239], 0, s[16:17]
	s_mov_b32 m0, s25
	s_nop 0
	global_load_lds_dwordx4 v[190:191], off
	s_waitcnt vmcnt(8)
	s_waitcnt lgkmcnt(0)
	s_setprio 1
	s_barrier
	s_waitcnt lgkmcnt(0)
	v_mfma_f32_16x16x32_bf16 v[62:65], v[130:133], v[186:189], v[62:65]
	v_mfma_f32_16x16x32_bf16 v[58:61], v[138:141], v[186:189], v[58:61]
	v_mfma_f32_16x16x32_bf16 v[46:49], v[130:133], v[208:211], v[46:49]
	v_mfma_f32_16x16x32_bf16 v[42:45], v[138:141], v[208:211], v[42:45]
	v_mfma_f32_16x16x32_bf16 v[30:33], v[130:133], v[216:219], v[30:33]
	v_mfma_f32_16x16x32_bf16 v[26:29], v[138:141], v[216:219], v[26:29]
	v_mfma_f32_16x16x32_bf16 v[14:17], v[130:133], v[224:227], v[14:17]
	v_mfma_f32_16x16x32_bf16 v[10:13], v[138:141], v[224:227], v[10:13]
	v_mfma_f32_16x16x32_bf16 v[62:65], v[134:137], v[202:205], v[62:65]
	v_mfma_f32_16x16x32_bf16 v[58:61], v[142:145], v[202:205], v[58:61]
	v_mfma_f32_16x16x32_bf16 v[46:49], v[134:137], v[212:215], v[46:49]
	v_mfma_f32_16x16x32_bf16 v[42:45], v[142:145], v[212:215], v[42:45]
	v_mfma_f32_16x16x32_bf16 v[30:33], v[134:137], v[220:223], v[30:33]
	v_mfma_f32_16x16x32_bf16 v[26:29], v[142:145], v[220:223], v[26:29]
	v_mfma_f32_16x16x32_bf16 v[14:17], v[134:137], v[228:231], v[14:17]
	v_mfma_f32_16x16x32_bf16 v[10:13], v[142:145], v[228:231], v[10:13]
	s_setprio 0
	s_setprio 1
	v_mfma_f32_16x16x32_bf16 v[54:57], v[170:173], v[186:189], v[54:57]
	v_mfma_f32_16x16x32_bf16 v[50:53], v[178:181], v[186:189], v[50:53]
	v_mfma_f32_16x16x32_bf16 v[38:41], v[170:173], v[208:211], v[38:41]
	v_mfma_f32_16x16x32_bf16 v[34:37], v[178:181], v[208:211], v[34:37]
	v_mfma_f32_16x16x32_bf16 v[22:25], v[170:173], v[216:219], v[22:25]
	v_mfma_f32_16x16x32_bf16 v[18:21], v[178:181], v[216:219], v[18:21]
	v_mfma_f32_16x16x32_bf16 v[6:9], v[170:173], v[224:227], v[6:9]
	v_mfma_f32_16x16x32_bf16 v[2:5], v[178:181], v[224:227], v[2:5]
	v_mfma_f32_16x16x32_bf16 v[54:57], v[174:177], v[202:205], v[54:57]
	v_mfma_f32_16x16x32_bf16 v[50:53], v[182:185], v[202:205], v[50:53]
	v_mfma_f32_16x16x32_bf16 v[38:41], v[174:177], v[212:215], v[38:41]
	v_mfma_f32_16x16x32_bf16 v[34:37], v[182:185], v[212:215], v[34:37]
	v_mfma_f32_16x16x32_bf16 v[22:25], v[174:177], v[220:223], v[22:25]
	v_mfma_f32_16x16x32_bf16 v[18:21], v[182:185], v[220:223], v[18:21]
	s_setprio 3
	s_barrier
	v_mfma_f32_16x16x32_bf16 v[6:9], v[174:177], v[228:231], v[6:9]
	v_mfma_f32_16x16x32_bf16 v[2:5], v[182:185], v[228:231], v[2:5]
	s_setprio 0
	s_add_i32 vcc_lo, vcc_lo, 2
	s_add_u32 s84, s84, 0x100
	s_addc_u32 s85, s85, 0
	s_add_u32 s73, s73, 0x100
	s_addc_u32 s75, s75, 0
	s_cmp_gt_u32 vcc_lo, 13
	s_cbranch_scc0 .LBB0_141
	s_and_b64 vcc, exec, s[26:27]
	s_cbranch_vccz .LBB0_144
	s_barrier

; #define PG8_STAGE(bufoff, gbase, voff) do { _Pragma("unroll") for (int _i = 0; _i < 2; ++_i) \
;         __builtin_amdgcn_global_load_lds((const unsigned*)((const char*)(gbase) + (voff)[_i]), (PG8_LAS unsigned*)(lds + (bufoff) + ldsw + _i * 8192), 16, 0, 0); } while (0)
; #define PG8_LDA(dst, b, h) do { _Pragma("unroll") for (int m = 0; m < 4; ++m) _Pragma("unroll") for (int k = 0; k < 2; ++k) dst[m][k] = *(const PG8_LAS bf16x8*)(lds + PG8_SA(b, h) + aoff + m * 2048 + k * 1024); } while (0)
; #define PG8_LDB(dst, b, h) do { _Pragma("unroll") for (int n = 0; n < 2; ++n) _Pragma("unroll") for (int k = 0; k < 2; ++k) dst[n][k] = *(const PG8_LAS bf16x8*)(lds + PG8_SB(b, h) + boff + n * 2048 + k * 1024); } while (0)
; #define PG8_MMA(ai, bj, At, Bt) do { __builtin_amdgcn_s_setprio(1); _Pragma("unroll") for (int m = 0; m < 4; ++m) _Pragma("unroll") for (int n = 0; n < 2; ++n) _Pragma("unroll") for (int k = 0; k < 2; ++k) \
;         acc[ai][bj][m][n] = __builtin_amdgcn_mfma_f32_16x16x32_bf16(Bt[n][k], At[m][k], acc[ai][bj][m][n], 0, 0, 0); __builtin_amdgcn_s_setprio(0); } while (0)
; #define PG8_WAIT_V(n) asm volatile("s_waitcnt vmcnt(" #n ")" ::: "memory")
; #define PG8_WAIT_L(n) asm volatile("s_waitcnt lgkmcnt(" #n ")" ::: "memory")
; #define PG8_BAR __builtin_amdgcn_s_barrier()
; #define PG8_SCHED __builtin_amdgcn_sched_barrier(0)
; template <class Epi, class Sched, bool ALIGN_EPI = false, bool SP2 = false>
; __device__ __forceinline__ void gemm_phase(PG8_LAS unsigned char* lds, const Gemm g, const Sched& S, const Epi& E) {
;     ...
;             PG8_LDB(B0, 0, 0); PG8_LDB(B1, 0, 1); PG8_SCHED; PG8_LDA(At, 0, 0); PG8_STAGE(PG8_SA(1, 1), a1 + hstep, voffA);
;             PG8_WAIT_V(8); PG8_WAIT_L(0); PG8_BAR; PG8_MMA(0, 0, At, B0); PG8_MMA(0, 1, At, B1); PG8_BAR; PG8_SCHED;
;             PG8_LDA(At, 0, 1); PG8_STAGE(PG8_SB(0, 0), b2, voffB); PG8_STAGE(PG8_SB(0, 1), b2 + hstep, voffB); PG8_STAGE(PG8_SA(0, 0), a2, voffA);
;             PG8_WAIT_V(8); PG8_WAIT_L(0); PG8_BAR; PG8_MMA(1, 0, At, B0); PG8_MMA(1, 1, At, B1); PG8_BAR; PG8_SCHED;
.LBB0_609:
	ds_read_b128 v[98:101], v239
	ds_read_b128 v[110:113], v239 offset:1024
	ds_read_b128 v[122:125], v239 offset:2048
	ds_read_b128 v[134:137], v239 offset:3072
	ds_read_b128 v[138:141], v240
	ds_read_b128 v[142:145], v240 offset:1024
	ds_read_b128 v[146:149], v240 offset:2048
	ds_read_b128 v[150:153], v240 offset:3072
	s_add_u32 s18, s40, 0xfffc0080
	s_addc_u32 s19, s41, -1
	s_cmp_eq_u32 s62, 12
	s_cselect_b32 s43, s27, s19
	s_cselect_b32 s42, s39, s18
	s_cselect_b32 s31, s17, s61
	s_cselect_b32 s30, s59, s60
	v_lshl_add_u64 v[208:209], s[40:41], 0, v[198:199]
	s_add_i32 m0, s45, 0xc000
	ds_read_b128 v[162:165], v241
	ds_read_b128 v[166:169], v241 offset:1024
	ds_read_b128 v[170:173], v241 offset:2048
	ds_read_b128 v[174:177], v241 offset:3072
	ds_read_b128 v[178:181], v241 offset:4096
	ds_read_b128 v[182:185], v241 offset:5120
	ds_read_b128 v[186:189], v241 offset:6144
	ds_read_b128 v[204:207], v241 offset:7168
	global_load_lds_dwordx4 v[208:209], off
	v_lshl_add_u64 v[208:209], s[40:41], 0, v[200:201]
	s_add_i32 m0, s45, 0xe000
	s_nop 0
	global_load_lds_dwordx4 v[208:209], off
	s_waitcnt vmcnt(8)
	s_waitcnt lgkmcnt(0)
	s_setprio 1
	s_barrier
	s_waitcnt lgkmcnt(0)
	v_mfma_f32_16x16x32_bf16 v[158:161], v[98:101], v[162:165], v[158:161]
	v_mfma_f32_16x16x32_bf16 v[154:157], v[122:125], v[162:165], v[154:157]
	v_mfma_f32_16x16x32_bf16 v[118:121], v[98:101], v[170:173], v[118:121]
	v_mfma_f32_16x16x32_bf16 v[114:117], v[122:125], v[170:173], v[114:117]
	v_mfma_f32_16x16x32_bf16 v[94:97], v[98:101], v[178:181], v[94:97]
	v_mfma_f32_16x16x32_bf16 v[90:93], v[122:125], v[178:181], v[90:93]
	v_mfma_f32_16x16x32_bf16 v[78:81], v[98:101], v[186:189], v[78:81]
	v_mfma_f32_16x16x32_bf16 v[74:77], v[122:125], v[186:189], v[74:77]
	v_mfma_f32_16x16x32_bf16 v[158:161], v[110:113], v[166:169], v[158:161]
	v_mfma_f32_16x16x32_bf16 v[154:157], v[134:137], v[166:169], v[154:157]
	v_mfma_f32_16x16x32_bf16 v[118:121], v[110:113], v[174:177], v[118:121]
	v_mfma_f32_16x16x32_bf16 v[114:117], v[134:137], v[174:177], v[114:117]
	v_mfma_f32_16x16x32_bf16 v[94:97], v[110:113], v[182:185], v[94:97]
	v_mfma_f32_16x16x32_bf16 v[90:93], v[134:137], v[182:185], v[90:93]
	v_mfma_f32_16x16x32_bf16 v[78:81], v[110:113], v[204:207], v[78:81]
	v_mfma_f32_16x16x32_bf16 v[74:77], v[134:137], v[204:207], v[74:77]
	s_setprio 0
	s_setprio 1
	v_mfma_f32_16x16x32_bf16 v[130:133], v[138:141], v[162:165], v[130:133]
	v_mfma_f32_16x16x32_bf16 v[126:129], v[146:149], v[162:165], v[126:129]
	v_mfma_f32_16x16x32_bf16 v[106:109], v[138:141], v[170:173], v[106:109]
	v_mfma_f32_16x16x32_bf16 v[102:105], v[146:149], v[170:173], v[102:105]
	v_mfma_f32_16x16x32_bf16 v[86:89], v[138:141], v[178:181], v[86:89]
	v_mfma_f32_16x16x32_bf16 v[82:85], v[146:149], v[178:181], v[82:85]
	v_mfma_f32_16x16x32_bf16 v[70:73], v[138:141], v[186:189], v[70:73]
	v_mfma_f32_16x16x32_bf16 v[66:69], v[146:149], v[186:189], v[66:69]
	v_mfma_f32_16x16x32_bf16 v[130:133], v[142:145], v[166:169], v[130:133]
	v_mfma_f32_16x16x32_bf16 v[126:129], v[150:153], v[166:169], v[126:129]
	v_mfma_f32_16x16x32_bf16 v[106:109], v[142:145], v[174:177], v[106:109]
	v_mfma_f32_16x16x32_bf16 v[102:105], v[150:153], v[174:177], v[102:105]
	v_mfma_f32_16x16x32_bf16 v[86:89], v[142:145], v[182:185], v[86:89]
	v_mfma_f32_16x16x32_bf16 v[82:85], v[150:153], v[182:185], v[82:85]
	s_setprio 3
	s_barrier
	v_mfma_f32_16x16x32_bf16 v[70:73], v[142:145], v[204:207], v[70:73]
	v_mfma_f32_16x16x32_bf16 v[66:69], v[150:153], v[204:207], v[66:69]
	s_setprio 0
	s_add_i32 s18, s56, s44
	v_lshl_add_u64 v[208:209], s[30:31], 0, v[192:193]
	s_mov_b32 m0, s18
	ds_read_b128 v[162:165], v241 offset:16384
	ds_read_b128 v[166:169], v241 offset:17408
	ds_read_b128 v[170:173], v241 offset:18432
	ds_read_b128 v[174:177], v241 offset:19456
	ds_read_b128 v[178:181], v241 offset:20480
	ds_read_b128 v[182:185], v241 offset:21504
	ds_read_b128 v[186:189], v241 offset:22528
	ds_read_b128 v[204:207], v241 offset:23552
	global_load_lds_dwordx4 v[208:209], off
	s_add_i32 m0, s18, 0x2000
	s_add_u32 s18, s30, 0x40000
	v_lshl_add_u64 v[210:211], s[30:31], 0, v[196:197]
	s_addc_u32 s19, s31, 0
	s_add_i32 s63, s57, s44
	global_load_lds_dwordx4 v[210:211], off
	v_lshl_add_u64 v[212:213], s[18:19], 0, v[192:193]
	s_mov_b32 m0, s63
	v_lshl_add_u64 v[214:215], s[42:43], 0, v[194:195]
	global_load_lds_dwordx4 v[212:213], off
	v_lshl_add_u64 v[212:213], s[18:19], 0, v[196:197]
	s_add_i32 m0, s63, 0x2000
	s_nop 0
	global_load_lds_dwordx4 v[212:213], off
	v_lshl_add_u64 v[212:213], s[42:43], 0, v[190:191]
	s_mov_b32 m0, s45
	s_nop 0
	global_load_lds_dwordx4 v[212:213], off
	s_mov_b32 m0, s46
	s_nop 0
	global_load_lds_dwordx4 v[214:215], off
	s_waitcnt vmcnt(8)
	s_waitcnt lgkmcnt(0)
	s_setprio 1
	s_barrier
; #define PG8_STAGE(bufoff, gbase, voff) do { _Pragma("unroll") for (int _i = 0; _i < 2; ++_i) \
;         __builtin_amdgcn_global_load_lds((const unsigned*)((const char*)(gbase) + (voff)[_i]), (PG8_LAS unsigned*)(lds + (bufoff) + ldsw + _i * 8192), 16, 0, 0); } while (0)
; #define PG8_LDA(dst, b, h) do { _Pragma("unroll") for (int m = 0; m < 4; ++m) _Pragma("unroll") for (int k = 0; k < 2; ++k) dst[m][k] = *(const PG8_LAS bf16x8*)(lds + PG8_SA(b, h) + aoff + m * 2048 + k * 1024); } while (0)
; #define PG8_LDB(dst, b, h) do { _Pragma("unroll") for (int n = 0; n < 2; ++n) _Pragma("unroll") for (int k = 0; k < 2; ++k) dst[n][k] = *(const PG8_LAS bf16x8*)(lds + PG8_SB(b, h) + boff + n * 2048 + k * 1024); } while (0)
; #define PG8_MMA(ai, bj, At, Bt) do { __builtin_amdgcn_s_setprio(1); _Pragma("unroll") for (int m = 0; m < 4; ++m) _Pragma("unroll") for (int n = 0; n < 2; ++n) _Pragma("unroll") for (int k = 0; k < 2; ++k) \
;         acc[ai][bj][m][n] = __builtin_amdgcn_mfma_f32_16x16x32_bf16(Bt[n][k], At[m][k], acc[ai][bj][m][n], 0, 0, 0); __builtin_amdgcn_s_setprio(0); } while (0)
; #define PG8_WAIT_V(n) asm volatile("s_waitcnt vmcnt(" #n ")" ::: "memory")
; #define PG8_WAIT_L(n) asm volatile("s_waitcnt lgkmcnt(" #n ")" ::: "memory")
; #define PG8_BAR __builtin_amdgcn_s_barrier()
; #define PG8_SCHED __builtin_amdgcn_sched_barrier(0)
; template <class Epi, class Sched, bool ALIGN_EPI = false, bool SP2 = false>
; __device__ __forceinline__ void gemm_phase(PG8_LAS unsigned char* lds, const Gemm g, const Sched& S, const Epi& E) {
;     ...
;             PG8_WAIT_V(8); PG8_WAIT_L(0); PG8_BAR; PG8_MMA(1, 0, At, B0); PG8_MMA(1, 1, At, B1); PG8_BAR; PG8_SCHED;
;             PG8_LDB(B0, 1, 0); PG8_LDB(B1, 1, 1); PG8_SCHED; PG8_LDA(At, 1, 0); PG8_STAGE(PG8_SA(0, 1), a2 + hstep, voffA);
;             PG8_WAIT_V(8); PG8_WAIT_L(0); PG8_BAR; PG8_MMA(0, 0, At, B0); PG8_MMA(0, 1, At, B1); PG8_BAR; PG8_SCHED;
	s_waitcnt lgkmcnt(0)
	v_mfma_f32_16x16x32_bf16 v[62:65], v[98:101], v[162:165], v[62:65]
	v_mfma_f32_16x16x32_bf16 v[58:61], v[122:125], v[162:165], v[58:61]
	v_mfma_f32_16x16x32_bf16 v[46:49], v[98:101], v[170:173], v[46:49]
	v_mfma_f32_16x16x32_bf16 v[42:45], v[122:125], v[170:173], v[42:45]
	v_mfma_f32_16x16x32_bf16 v[30:33], v[98:101], v[178:181], v[30:33]
	v_mfma_f32_16x16x32_bf16 v[26:29], v[122:125], v[178:181], v[26:29]
	v_mfma_f32_16x16x32_bf16 v[14:17], v[98:101], v[186:189], v[14:17]
	v_mfma_f32_16x16x32_bf16 v[10:13], v[122:125], v[186:189], v[10:13]
	v_mfma_f32_16x16x32_bf16 v[62:65], v[110:113], v[166:169], v[62:65]
	v_mfma_f32_16x16x32_bf16 v[58:61], v[134:137], v[166:169], v[58:61]
	v_mfma_f32_16x16x32_bf16 v[46:49], v[110:113], v[174:177], v[46:49]
	v_mfma_f32_16x16x32_bf16 v[42:45], v[134:137], v[174:177], v[42:45]
	v_mfma_f32_16x16x32_bf16 v[30:33], v[110:113], v[182:185], v[30:33]
	v_mfma_f32_16x16x32_bf16 v[26:29], v[134:137], v[182:185], v[26:29]
	v_mfma_f32_16x16x32_bf16 v[14:17], v[110:113], v[204:207], v[14:17]
	v_mfma_f32_16x16x32_bf16 v[10:13], v[134:137], v[204:207], v[10:13]
	s_setprio 0
	s_setprio 1
	v_mfma_f32_16x16x32_bf16 v[54:57], v[138:141], v[162:165], v[54:57]
	v_mfma_f32_16x16x32_bf16 v[50:53], v[146:149], v[162:165], v[50:53]
	v_mfma_f32_16x16x32_bf16 v[38:41], v[138:141], v[170:173], v[38:41]
	v_mfma_f32_16x16x32_bf16 v[34:37], v[146:149], v[170:173], v[34:37]
	v_mfma_f32_16x16x32_bf16 v[22:25], v[138:141], v[178:181], v[22:25]
	v_mfma_f32_16x16x32_bf16 v[18:21], v[146:149], v[178:181], v[18:21]
	v_mfma_f32_16x16x32_bf16 v[6:9], v[138:141], v[186:189], v[6:9]
	v_mfma_f32_16x16x32_bf16 v[2:5], v[146:149], v[186:189], v[2:5]
	v_mfma_f32_16x16x32_bf16 v[54:57], v[142:145], v[166:169], v[54:57]
	v_mfma_f32_16x16x32_bf16 v[50:53], v[150:153], v[166:169], v[50:53]
	v_mfma_f32_16x16x32_bf16 v[38:41], v[142:145], v[174:177], v[38:41]
	v_mfma_f32_16x16x32_bf16 v[34:37], v[150:153], v[174:177], v[34:37]
	v_mfma_f32_16x16x32_bf16 v[22:25], v[142:145], v[182:185], v[22:25]
	v_mfma_f32_16x16x32_bf16 v[18:21], v[150:153], v[182:185], v[18:21]
	s_setprio 3
	s_barrier
	v_mfma_f32_16x16x32_bf16 v[6:9], v[142:145], v[204:207], v[6:9]
	v_mfma_f32_16x16x32_bf16 v[2:5], v[150:153], v[204:207], v[2:5]
	s_setprio 0
	s_add_i32 s63, 0, 0x18000
	s_add_i32 s64, 0, 0x1c000
	v_add_u32_e32 v134, s63, v237
	v_add_u32_e32 v150, s64, v237
	ds_read_b128 v[98:101], v134
	ds_read_b128 v[110:113], v134 offset:1024
	ds_read_b128 v[122:125], v134 offset:2048
	ds_read_b128 v[134:137], v134 offset:3072
	ds_read_b128 v[138:141], v150
	ds_read_b128 v[142:145], v150 offset:1024
	ds_read_b128 v[146:149], v150 offset:2048
	ds_read_b128 v[150:153], v150 offset:3072
	s_add_u32 s18, s42, 0x40000
	s_addc_u32 s19, s43, 0
	s_mov_b32 m0, s47
	v_lshl_add_u64 v[216:217], s[18:19], 0, v[190:191]
	ds_read_b128 v[162:165], v241 offset:32768
	ds_read_b128 v[166:169], v241 offset:33792
	ds_read_b128 v[170:173], v241 offset:34816
	ds_read_b128 v[174:177], v241 offset:35840
	ds_read_b128 v[178:181], v241 offset:36864
	ds_read_b128 v[182:185], v241 offset:37888
	ds_read_b128 v[186:189], v241 offset:38912
	ds_read_b128 v[204:207], v241 offset:39936
	global_load_lds_dwordx4 v[216:217], off
	v_lshl_add_u64 v[216:217], s[18:19], 0, v[194:195]
	s_mov_b32 m0, s48
	s_nop 0
	global_load_lds_dwordx4 v[216:217], off
	s_waitcnt vmcnt(8)
	s_waitcnt lgkmcnt(0)
	s_setprio 1
	s_barrier
	s_waitcnt lgkmcnt(0)
	v_mfma_f32_16x16x32_bf16 v[158:161], v[98:101], v[162:165], v[158:161]
	v_mfma_f32_16x16x32_bf16 v[154:157], v[122:125], v[162:165], v[154:157]
	v_mfma_f32_16x16x32_bf16 v[118:121], v[98:101], v[170:173], v[118:121]
	v_mfma_f32_16x16x32_bf16 v[114:117], v[122:125], v[170:173], v[114:117]
	v_mfma_f32_16x16x32_bf16 v[94:97], v[98:101], v[178:181], v[94:97]
	v_mfma_f32_16x16x32_bf16 v[90:93], v[122:125], v[178:181], v[90:93]
	v_mfma_f32_16x16x32_bf16 v[78:81], v[98:101], v[186:189], v[78:81]
	v_mfma_f32_16x16x32_bf16 v[74:77], v[122:125], v[186:189], v[74:77]
	v_mfma_f32_16x16x32_bf16 v[158:161], v[110:113], v[166:169], v[158:161]
	v_mfma_f32_16x16x32_bf16 v[154:157], v[134:137], v[166:169], v[154:157]
	v_mfma_f32_16x16x32_bf16 v[118:121], v[110:113], v[174:177], v[118:121]
	v_mfma_f32_16x16x32_bf16 v[114:117], v[134:137], v[174:177], v[114:117]
	v_mfma_f32_16x16x32_bf16 v[94:97], v[110:113], v[182:185], v[94:97]
	v_mfma_f32_16x16x32_bf16 v[90:93], v[134:137], v[182:185], v[90:93]
	v_mfma_f32_16x16x32_bf16 v[78:81], v[110:113], v[204:207], v[78:81]
	v_mfma_f32_16x16x32_bf16 v[74:77], v[134:137], v[204:207], v[74:77]
	s_setprio 0
	s_setprio 1
	v_mfma_f32_16x16x32_bf16 v[130:133], v[138:141], v[162:165], v[130:133]
	v_mfma_f32_16x16x32_bf16 v[126:129], v[146:149], v[162:165], v[126:129]
	v_mfma_f32_16x16x32_bf16 v[106:109], v[138:141], v[170:173], v[106:109]
	v_mfma_f32_16x16x32_bf16 v[102:105], v[146:149], v[170:173], v[102:105]
	v_mfma_f32_16x16x32_bf16 v[86:89], v[138:141], v[178:181], v[86:89]
	v_mfma_f32_16x16x32_bf16 v[82:85], v[146:149], v[178:181], v[82:85]
	v_mfma_f32_16x16x32_bf16 v[70:73], v[138:141], v[186:189], v[70:73]
	v_mfma_f32_16x16x32_bf16 v[66:69], v[146:149], v[186:189], v[66:69]
	v_mfma_f32_16x16x32_bf16 v[130:133], v[142:145], v[166:169], v[130:133]
	v_mfma_f32_16x16x32_bf16 v[126:129], v[150:153], v[166:169], v[126:129]
	v_mfma_f32_16x16x32_bf16 v[106:109], v[142:145], v[174:177], v[106:109]
	v_mfma_f32_16x16x32_bf16 v[102:105], v[150:153], v[174:177], v[102:105]
	v_mfma_f32_16x16x32_bf16 v[86:89], v[142:145], v[182:185], v[86:89]
	v_mfma_f32_16x16x32_bf16 v[82:85], v[150:153], v[182:185], v[82:85]
	s_setprio 3
	s_barrier
; #define PG8_STAGE(bufoff, gbase, voff) do { _Pragma("unroll") for (int _i = 0; _i < 2; ++_i) \
;         __builtin_amdgcn_global_load_lds((const unsigned*)((const char*)(gbase) + (voff)[_i]), (PG8_LAS unsigned*)(lds + (bufoff) + ldsw + _i * 8192), 16, 0, 0); } while (0)
; #define PG8_LDA(dst, b, h) do { _Pragma("unroll") for (int m = 0; m < 4; ++m) _Pragma("unroll") for (int k = 0; k < 2; ++k) dst[m][k] = *(const PG8_LAS bf16x8*)(lds + PG8_SA(b, h) + aoff + m * 2048 + k * 1024); } while (0)
; #define PG8_MMA(ai, bj, At, Bt) do { __builtin_amdgcn_s_setprio(1); _Pragma("unroll") for (int m = 0; m < 4; ++m) _Pragma("unroll") for (int n = 0; n < 2; ++n) _Pragma("unroll") for (int k = 0; k < 2; ++k) \
;         acc[ai][bj][m][n] = __builtin_amdgcn_mfma_f32_16x16x32_bf16(Bt[n][k], At[m][k], acc[ai][bj][m][n], 0, 0, 0); __builtin_amdgcn_s_setprio(0); } while (0)
; #define PG8_WAIT_V(n) asm volatile("s_waitcnt vmcnt(" #n ")" ::: "memory")
; #define PG8_WAIT_L(n) asm volatile("s_waitcnt lgkmcnt(" #n ")" ::: "memory")
; #define PG8_BAR __builtin_amdgcn_s_barrier()
; #define PG8_SCHED __builtin_amdgcn_sched_barrier(0)
;     __device__ __forceinline__ void operator()(const f32x4 (&acc)[2][2][4][2], const Unit& u, int wr, int wc, int fr, int fq) const {
;     ...
;                 for (int bj = 0; bj < 2; ++bj) bva[ai][m][bj] = *(const u32x4*)(Xb + (size_t)(row0 + ai * HALF + m * 16) * DM + col0 + bj * HALF);
; template <class Epi, class Sched, bool ALIGN_EPI = false, bool SP2 = false>
; __device__ __forceinline__ void gemm_phase(PG8_LAS unsigned char* lds, const Gemm g, const Sched& S, const Epi& E) {
;     ...
;             PG8_LDA(At, 1, 1); PG8_STAGE(PG8_SB(1, 0), b3, voffB); PG8_STAGE(PG8_SB(1, 1), b3 + hstep, voffB); PG8_STAGE(PG8_SA(1, 0), a3, voffA);
;             PG8_WAIT_V(8); PG8_WAIT_L(0); PG8_BAR; PG8_MMA(1, 0, At, B0); PG8_MMA(1, 1, At, B1); PG8_BAR; PG8_SCHED;
	v_mfma_f32_16x16x32_bf16 v[70:73], v[142:145], v[204:207], v[70:73]
	v_mfma_f32_16x16x32_bf16 v[66:69], v[150:153], v[204:207], v[66:69]
	s_setprio 0
	s_add_i32 s18, s63, s44
	v_lshl_add_u64 v[208:209], v[208:209], 0, s[12:13]
	s_mov_b32 m0, s18
	ds_read_b128 v[162:165], v241 offset:49152
	ds_read_b128 v[166:169], v241 offset:50176
	ds_read_b128 v[170:173], v241 offset:51200
	ds_read_b128 v[174:177], v241 offset:52224
	ds_read_b128 v[178:181], v241 offset:53248
	ds_read_b128 v[182:185], v241 offset:54272
	ds_read_b128 v[186:189], v241 offset:55296
	ds_read_b128 v[204:207], v241 offset:56320
	global_load_lds_dwordx4 v[208:209], off
	s_add_i32 m0, s18, 0x2000
	s_add_u32 s18, s30, 0x40080
	v_lshl_add_u64 v[208:209], v[210:211], 0, s[12:13]
	s_addc_u32 s19, s31, 0
	s_add_i32 s30, s64, s44
	global_load_lds_dwordx4 v[208:209], off
	v_lshl_add_u64 v[208:209], s[18:19], 0, v[192:193]
	s_mov_b32 m0, s30
	s_nop 0
	global_load_lds_dwordx4 v[208:209], off
	v_lshl_add_u64 v[208:209], s[18:19], 0, v[196:197]
	s_add_i32 m0, s30, 0x2000
	s_nop 0
	global_load_lds_dwordx4 v[208:209], off
	v_lshl_add_u64 v[208:209], v[212:213], 0, s[12:13]
	s_mov_b32 m0, s52
	s_nop 0
	global_load_lds_dwordx4 v[208:209], off
	v_lshl_add_u64 v[208:209], v[214:215], 0, s[12:13]
	s_mov_b32 m0, s53
	s_nop 0
	global_load_lds_dwordx4 v[208:209], off
	s_waitcnt vmcnt(8)
	s_waitcnt lgkmcnt(0)
	s_setprio 1
	s_barrier
	s_waitcnt lgkmcnt(0)
	v_mfma_f32_16x16x32_bf16 v[62:65], v[98:101], v[162:165], v[62:65]
	v_mfma_f32_16x16x32_bf16 v[58:61], v[122:125], v[162:165], v[58:61]
	v_mfma_f32_16x16x32_bf16 v[46:49], v[98:101], v[170:173], v[46:49]
	v_mfma_f32_16x16x32_bf16 v[42:45], v[122:125], v[170:173], v[42:45]
	v_mfma_f32_16x16x32_bf16 v[30:33], v[98:101], v[178:181], v[30:33]
	v_mfma_f32_16x16x32_bf16 v[26:29], v[122:125], v[178:181], v[26:29]
	v_mfma_f32_16x16x32_bf16 v[14:17], v[98:101], v[186:189], v[14:17]
	v_mfma_f32_16x16x32_bf16 v[10:13], v[122:125], v[186:189], v[10:13]
	v_mfma_f32_16x16x32_bf16 v[62:65], v[110:113], v[166:169], v[62:65]
	v_mfma_f32_16x16x32_bf16 v[58:61], v[134:137], v[166:169], v[58:61]
	v_mfma_f32_16x16x32_bf16 v[46:49], v[110:113], v[174:177], v[46:49]
	v_mfma_f32_16x16x32_bf16 v[42:45], v[134:137], v[174:177], v[42:45]
	v_mfma_f32_16x16x32_bf16 v[30:33], v[110:113], v[182:185], v[30:33]
	v_mfma_f32_16x16x32_bf16 v[26:29], v[134:137], v[182:185], v[26:29]
	v_mfma_f32_16x16x32_bf16 v[14:17], v[110:113], v[204:207], v[14:17]
	v_mfma_f32_16x16x32_bf16 v[10:13], v[134:137], v[204:207], v[10:13]
	s_setprio 0
	s_setprio 1
	v_mfma_f32_16x16x32_bf16 v[54:57], v[138:141], v[162:165], v[54:57]
	v_mfma_f32_16x16x32_bf16 v[50:53], v[146:149], v[162:165], v[50:53]
	v_mfma_f32_16x16x32_bf16 v[38:41], v[138:141], v[170:173], v[38:41]
	v_mfma_f32_16x16x32_bf16 v[34:37], v[146:149], v[170:173], v[34:37]
	v_mfma_f32_16x16x32_bf16 v[22:25], v[138:141], v[178:181], v[22:25]
	v_mfma_f32_16x16x32_bf16 v[18:21], v[146:149], v[178:181], v[18:21]
	v_mfma_f32_16x16x32_bf16 v[6:9], v[138:141], v[186:189], v[6:9]
	v_mfma_f32_16x16x32_bf16 v[2:5], v[146:149], v[186:189], v[2:5]
	v_mfma_f32_16x16x32_bf16 v[54:57], v[142:145], v[166:169], v[54:57]
	v_mfma_f32_16x16x32_bf16 v[50:53], v[150:153], v[166:169], v[50:53]
	v_mfma_f32_16x16x32_bf16 v[38:41], v[142:145], v[174:177], v[38:41]
	v_mfma_f32_16x16x32_bf16 v[34:37], v[150:153], v[174:177], v[34:37]
	v_mfma_f32_16x16x32_bf16 v[22:25], v[142:145], v[182:185], v[22:25]
	v_mfma_f32_16x16x32_bf16 v[18:21], v[150:153], v[182:185], v[18:21]
	s_setprio 3
	s_barrier
	v_mfma_f32_16x16x32_bf16 v[6:9], v[142:145], v[204:207], v[6:9]
	v_mfma_f32_16x16x32_bf16 v[2:5], v[150:153], v[204:207], v[2:5]
	s_setprio 0
	s_add_i32 s62, s62, 2
	s_add_u32 s40, s40, 0x100
	s_addc_u32 s41, s41, 0
	s_add_u32 s60, s60, 0x100
	s_addc_u32 s61, s61, 0
	s_cmp_gt_u32 s62, 13
	s_cbranch_scc1 .Lrp_gen_p3
	s_cmp_lg_u32 s62, 12
	s_cbranch_scc1 .LBB0_609
	s_cmpk_lg_i32 s33, 0x100
	s_cbranch_scc1 .LBB0_609
	ds_read_b128 v[98:101], v239
	ds_read_b128 v[110:113], v239 offset:1024
	ds_read_b128 v[122:125], v239 offset:2048
	ds_read_b128 v[134:137], v239 offset:3072
	ds_read_b128 v[138:141], v240
	ds_read_b128 v[142:145], v240 offset:1024
	ds_read_b128 v[146:149], v240 offset:2048
	ds_read_b128 v[150:153], v240 offset:3072
	s_add_u32 s18, s40, 0xfffc0080
	s_addc_u32 s19, s41, -1
	s_cmp_eq_u32 s62, 12
	s_cselect_b32 s43, s27, s19
	s_cselect_b32 s42, s39, s18
	s_cselect_b32 s31, s17, s61
	s_cselect_b32 s30, s59, s60
	v_lshl_add_u64 v[208:209], s[40:41], 0, v[198:199]
	s_add_i32 m0, s45, 0xc000
	ds_read_b128 v[162:165], v241
	ds_read_b128 v[166:169], v241 offset:1024
	ds_read_b128 v[170:173], v241 offset:2048
	ds_read_b128 v[174:177], v241 offset:3072
	ds_read_b128 v[178:181], v241 offset:4096
	ds_read_b128 v[182:185], v241 offset:5120
	ds_read_b128 v[186:189], v241 offset:6144
	ds_read_b128 v[204:207], v241 offset:7168
	global_load_lds_dwordx4 v[208:209], off
	v_lshl_add_u64 v[208:209], s[40:41], 0, v[200:201]
	s_add_i32 m0, s45, 0xe000
	s_nop 0
	global_load_lds_dwordx4 v[208:209], off
	v_lshl_or_b32 v255, s0, 8, v238
	v_lshl_add_u32 v235, s38, 8, v1
	v_lshlrev_b32_e32 v255, 1, v255
	v_lshl_add_u32 v255, v235, 11, v255
	s_mov_b64 s[84:85], s[20:21]
	global_load_dwordx4 v[242:245], v255, s[84:85]
	global_load_dwordx4 v[208:211], v255, s[84:85] offset:256
	s_add_u32 s84, s20, 0x8000
	s_addc_u32 s85, s21, 0
	global_load_dwordx4 v[212:215], v255, s[84:85]
	global_load_dwordx4 v[216:219], v255, s[84:85] offset:256
	s_add_u32 s84, s20, 0x10000
	s_addc_u32 s85, s21, 0
	global_load_dwordx4 v[220:223], v255, s[84:85]
	global_load_dwordx4 v[224:227], v255, s[84:85] offset:256
	s_add_u32 s84, s20, 0x18000
	s_addc_u32 s85, s21, 0
	global_load_dwordx4 v[228:231], v255, s[84:85]
	global_load_dwordx4 v[232:235], v255, s[84:85] offset:256
	s_add_u32 s84, s20, 0x40000
	s_addc_u32 s85, s21, 0
	global_load_dwordx4 v[246:249], v255, s[84:85]
	global_load_dwordx4 v[250:253], v255, s[84:85] offset:256
	s_waitcnt vmcnt(18)
	s_waitcnt lgkmcnt(0)
	s_setprio 1
	s_barrier
; #define PG8_STAGE(bufoff, gbase, voff) do { _Pragma("unroll") for (int _i = 0; _i < 2; ++_i) \
;         __builtin_amdgcn_global_load_lds((const unsigned*)((const char*)(gbase) + (voff)[_i]), (PG8_LAS unsigned*)(lds + (bufoff) + ldsw + _i * 8192), 16, 0, 0); } while (0)
; #define PG8_LDA(dst, b, h) do { _Pragma("unroll") for (int m = 0; m < 4; ++m) _Pragma("unroll") for (int k = 0; k < 2; ++k) dst[m][k] = *(const PG8_LAS bf16x8*)(lds + PG8_SA(b, h) + aoff + m * 2048 + k * 1024); } while (0)
; #define PG8_LDB(dst, b, h) do { _Pragma("unroll") for (int n = 0; n < 2; ++n) _Pragma("unroll") for (int k = 0; k < 2; ++k) dst[n][k] = *(const PG8_LAS bf16x8*)(lds + PG8_SB(b, h) + boff + n * 2048 + k * 1024); } while (0)
; #define PG8_MMA(ai, bj, At, Bt) do { __builtin_amdgcn_s_setprio(1); _Pragma("unroll") for (int m = 0; m < 4; ++m) _Pragma("unroll") for (int n = 0; n < 2; ++n) _Pragma("unroll") for (int k = 0; k < 2; ++k) \
;         acc[ai][bj][m][n] = __builtin_amdgcn_mfma_f32_16x16x32_bf16(Bt[n][k], At[m][k], acc[ai][bj][m][n], 0, 0, 0); __builtin_amdgcn_s_setprio(0); } while (0)
; #define PG8_WAIT_V(n) asm volatile("s_waitcnt vmcnt(" #n ")" ::: "memory")
; #define PG8_WAIT_L(n) asm volatile("s_waitcnt lgkmcnt(" #n ")" ::: "memory")
; #define PG8_BAR __builtin_amdgcn_s_barrier()
; #define PG8_SCHED __builtin_amdgcn_sched_barrier(0)
; template <class Epi, class Sched, bool ALIGN_EPI = false, bool SP2 = false>
; __device__ __forceinline__ void gemm_phase(PG8_LAS unsigned char* lds, const Gemm g, const Sched& S, const Epi& E) {
;     ...
;             PG8_WAIT_V(8); PG8_WAIT_L(0); PG8_BAR; PG8_MMA(0, 0, At, B0); PG8_MMA(0, 1, At, B1); PG8_BAR; PG8_SCHED;
;             PG8_LDA(At, 0, 1); PG8_STAGE(PG8_SB(0, 0), b2, voffB); PG8_STAGE(PG8_SB(0, 1), b2 + hstep, voffB); PG8_STAGE(PG8_SA(0, 0), a2, voffA);
;             PG8_WAIT_V(8); PG8_WAIT_L(0); PG8_BAR; PG8_MMA(1, 0, At, B0); PG8_MMA(1, 1, At, B1); PG8_BAR; PG8_SCHED;
;             PG8_LDB(B0, 1, 0); PG8_LDB(B1, 1, 1); PG8_SCHED; PG8_LDA(At, 1, 0); PG8_STAGE(PG8_SA(0, 1), a2 + hstep, voffA);
;             PG8_WAIT_V(8); PG8_WAIT_L(0); PG8_BAR; PG8_MMA(0, 0, At, B0); PG8_MMA(0, 1, At, B1); PG8_BAR; PG8_SCHED;
	s_waitcnt lgkmcnt(0)
	v_mfma_f32_16x16x32_bf16 v[158:161], v[98:101], v[162:165], v[158:161]
	v_mfma_f32_16x16x32_bf16 v[154:157], v[122:125], v[162:165], v[154:157]
	v_mfma_f32_16x16x32_bf16 v[118:121], v[98:101], v[170:173], v[118:121]
	v_mfma_f32_16x16x32_bf16 v[114:117], v[122:125], v[170:173], v[114:117]
	v_mfma_f32_16x16x32_bf16 v[94:97], v[98:101], v[178:181], v[94:97]
	v_mfma_f32_16x16x32_bf16 v[90:93], v[122:125], v[178:181], v[90:93]
	v_mfma_f32_16x16x32_bf16 v[78:81], v[98:101], v[186:189], v[78:81]
	v_mfma_f32_16x16x32_bf16 v[74:77], v[122:125], v[186:189], v[74:77]
	v_mfma_f32_16x16x32_bf16 v[158:161], v[110:113], v[166:169], v[158:161]
	v_mfma_f32_16x16x32_bf16 v[154:157], v[134:137], v[166:169], v[154:157]
	v_mfma_f32_16x16x32_bf16 v[118:121], v[110:113], v[174:177], v[118:121]
	v_mfma_f32_16x16x32_bf16 v[114:117], v[134:137], v[174:177], v[114:117]
	v_mfma_f32_16x16x32_bf16 v[94:97], v[110:113], v[182:185], v[94:97]
	v_mfma_f32_16x16x32_bf16 v[90:93], v[134:137], v[182:185], v[90:93]
	v_mfma_f32_16x16x32_bf16 v[78:81], v[110:113], v[204:207], v[78:81]
	v_mfma_f32_16x16x32_bf16 v[74:77], v[134:137], v[204:207], v[74:77]
	s_setprio 0
	s_setprio 1
	v_mfma_f32_16x16x32_bf16 v[130:133], v[138:141], v[162:165], v[130:133]
	v_mfma_f32_16x16x32_bf16 v[126:129], v[146:149], v[162:165], v[126:129]
	v_mfma_f32_16x16x32_bf16 v[106:109], v[138:141], v[170:173], v[106:109]
	v_mfma_f32_16x16x32_bf16 v[102:105], v[146:149], v[170:173], v[102:105]
	v_mfma_f32_16x16x32_bf16 v[86:89], v[138:141], v[178:181], v[86:89]
	v_mfma_f32_16x16x32_bf16 v[82:85], v[146:149], v[178:181], v[82:85]
	v_mfma_f32_16x16x32_bf16 v[70:73], v[138:141], v[186:189], v[70:73]
	v_mfma_f32_16x16x32_bf16 v[66:69], v[146:149], v[186:189], v[66:69]
	v_mfma_f32_16x16x32_bf16 v[130:133], v[142:145], v[166:169], v[130:133]
	v_mfma_f32_16x16x32_bf16 v[126:129], v[150:153], v[166:169], v[126:129]
	v_mfma_f32_16x16x32_bf16 v[106:109], v[142:145], v[174:177], v[106:109]
	v_mfma_f32_16x16x32_bf16 v[102:105], v[150:153], v[174:177], v[102:105]
	v_mfma_f32_16x16x32_bf16 v[86:89], v[142:145], v[182:185], v[86:89]
	v_mfma_f32_16x16x32_bf16 v[82:85], v[150:153], v[182:185], v[82:85]
	s_setprio 3
	s_barrier
	v_mfma_f32_16x16x32_bf16 v[70:73], v[142:145], v[204:207], v[70:73]
	v_mfma_f32_16x16x32_bf16 v[66:69], v[150:153], v[204:207], v[66:69]
	s_setprio 0
	s_add_i32 s18, s56, s44
	s_mov_b32 m0, s18
	ds_read_b128 v[162:165], v241 offset:16384
	ds_read_b128 v[166:169], v241 offset:17408
	ds_read_b128 v[170:173], v241 offset:18432
	ds_read_b128 v[174:177], v241 offset:19456
	ds_read_b128 v[178:181], v241 offset:20480
	ds_read_b128 v[182:185], v241 offset:21504
	ds_read_b128 v[186:189], v241 offset:22528
	ds_read_b128 v[204:207], v241 offset:23552
	s_add_i32 m0, s18, 0x2000
	s_add_u32 s18, s30, 0x40000
	s_addc_u32 s19, s31, 0
	s_add_i32 s63, s57, s44
	s_mov_b32 m0, s63
	s_add_i32 m0, s63, 0x2000
	s_nop 0
	s_mov_b32 m0, s45
	s_nop 0
	s_mov_b32 m0, s46
	s_nop 0
	s_waitcnt vmcnt(12)
	s_waitcnt lgkmcnt(0)
	s_setprio 1
	s_barrier
	s_waitcnt lgkmcnt(0)
	v_mfma_f32_16x16x32_bf16 v[62:65], v[98:101], v[162:165], v[62:65]
	v_mfma_f32_16x16x32_bf16 v[58:61], v[122:125], v[162:165], v[58:61]
	v_mfma_f32_16x16x32_bf16 v[46:49], v[98:101], v[170:173], v[46:49]
	v_mfma_f32_16x16x32_bf16 v[42:45], v[122:125], v[170:173], v[42:45]
	v_mfma_f32_16x16x32_bf16 v[30:33], v[98:101], v[178:181], v[30:33]
	v_mfma_f32_16x16x32_bf16 v[26:29], v[122:125], v[178:181], v[26:29]
	v_mfma_f32_16x16x32_bf16 v[14:17], v[98:101], v[186:189], v[14:17]
	v_mfma_f32_16x16x32_bf16 v[10:13], v[122:125], v[186:189], v[10:13]
	v_mfma_f32_16x16x32_bf16 v[62:65], v[110:113], v[166:169], v[62:65]
	v_mfma_f32_16x16x32_bf16 v[58:61], v[134:137], v[166:169], v[58:61]
	v_mfma_f32_16x16x32_bf16 v[46:49], v[110:113], v[174:177], v[46:49]
	v_mfma_f32_16x16x32_bf16 v[42:45], v[134:137], v[174:177], v[42:45]
	v_mfma_f32_16x16x32_bf16 v[30:33], v[110:113], v[182:185], v[30:33]
	v_mfma_f32_16x16x32_bf16 v[26:29], v[134:137], v[182:185], v[26:29]
	v_mfma_f32_16x16x32_bf16 v[14:17], v[110:113], v[204:207], v[14:17]
	v_mfma_f32_16x16x32_bf16 v[10:13], v[134:137], v[204:207], v[10:13]
	s_setprio 0
	s_setprio 1
	v_mfma_f32_16x16x32_bf16 v[54:57], v[138:141], v[162:165], v[54:57]
	v_mfma_f32_16x16x32_bf16 v[50:53], v[146:149], v[162:165], v[50:53]
	v_mfma_f32_16x16x32_bf16 v[38:41], v[138:141], v[170:173], v[38:41]
	v_mfma_f32_16x16x32_bf16 v[34:37], v[146:149], v[170:173], v[34:37]
	v_mfma_f32_16x16x32_bf16 v[22:25], v[138:141], v[178:181], v[22:25]
	v_mfma_f32_16x16x32_bf16 v[18:21], v[146:149], v[178:181], v[18:21]
	v_mfma_f32_16x16x32_bf16 v[6:9], v[138:141], v[186:189], v[6:9]
	v_mfma_f32_16x16x32_bf16 v[2:5], v[146:149], v[186:189], v[2:5]
	v_mfma_f32_16x16x32_bf16 v[54:57], v[142:145], v[166:169], v[54:57]
	v_mfma_f32_16x16x32_bf16 v[50:53], v[150:153], v[166:169], v[50:53]
	v_mfma_f32_16x16x32_bf16 v[38:41], v[142:145], v[174:177], v[38:41]
	v_mfma_f32_16x16x32_bf16 v[34:37], v[150:153], v[174:177], v[34:37]
	v_mfma_f32_16x16x32_bf16 v[22:25], v[142:145], v[182:185], v[22:25]
	v_mfma_f32_16x16x32_bf16 v[18:21], v[150:153], v[182:185], v[18:21]
	s_setprio 3
	s_barrier
; #define PG8_STAGE(bufoff, gbase, voff) do { _Pragma("unroll") for (int _i = 0; _i < 2; ++_i) \
;         __builtin_amdgcn_global_load_lds((const unsigned*)((const char*)(gbase) + (voff)[_i]), (PG8_LAS unsigned*)(lds + (bufoff) + ldsw + _i * 8192), 16, 0, 0); } while (0)
; #define PG8_LDA(dst, b, h) do { _Pragma("unroll") for (int m = 0; m < 4; ++m) _Pragma("unroll") for (int k = 0; k < 2; ++k) dst[m][k] = *(const PG8_LAS bf16x8*)(lds + PG8_SA(b, h) + aoff + m * 2048 + k * 1024); } while (0)
; #define PG8_LDB(dst, b, h) do { _Pragma("unroll") for (int n = 0; n < 2; ++n) _Pragma("unroll") for (int k = 0; k < 2; ++k) dst[n][k] = *(const PG8_LAS bf16x8*)(lds + PG8_SB(b, h) + boff + n * 2048 + k * 1024); } while (0)
; #define PG8_MMA(ai, bj, At, Bt) do { __builtin_amdgcn_s_setprio(1); _Pragma("unroll") for (int m = 0; m < 4; ++m) _Pragma("unroll") for (int n = 0; n < 2; ++n) _Pragma("unroll") for (int k = 0; k < 2; ++k) \
;         acc[ai][bj][m][n] = __builtin_amdgcn_mfma_f32_16x16x32_bf16(Bt[n][k], At[m][k], acc[ai][bj][m][n], 0, 0, 0); __builtin_amdgcn_s_setprio(0); } while (0)
; #define PG8_WAIT_V(n) asm volatile("s_waitcnt vmcnt(" #n ")" ::: "memory")
; #define PG8_WAIT_L(n) asm volatile("s_waitcnt lgkmcnt(" #n ")" ::: "memory")
; #define PG8_BAR __builtin_amdgcn_s_barrier()
; #define PG8_SCHED __builtin_amdgcn_sched_barrier(0)
; template <class Epi, class Sched, bool ALIGN_EPI = false, bool SP2 = false>
; __device__ __forceinline__ void gemm_phase(PG8_LAS unsigned char* lds, const Gemm g, const Sched& S, const Epi& E) {
;     ...
;             PG8_WAIT_V(8); PG8_WAIT_L(0); PG8_BAR; PG8_MMA(1, 0, At, B0); PG8_MMA(1, 1, At, B1); PG8_BAR; PG8_SCHED;
;             PG8_LDB(B0, 1, 0); PG8_LDB(B1, 1, 1); PG8_SCHED; PG8_LDA(At, 1, 0); PG8_STAGE(PG8_SA(0, 1), a2 + hstep, voffA);
;             PG8_WAIT_V(8); PG8_WAIT_L(0); PG8_BAR; PG8_MMA(0, 0, At, B0); PG8_MMA(0, 1, At, B1); PG8_BAR; PG8_SCHED;
;             PG8_LDA(At, 1, 1); PG8_STAGE(PG8_SB(1, 0), b3, voffB); PG8_STAGE(PG8_SB(1, 1), b3 + hstep, voffB); PG8_STAGE(PG8_SA(1, 0), a3, voffA);
;             PG8_WAIT_V(8); PG8_WAIT_L(0); PG8_BAR; PG8_MMA(1, 0, At, B0); PG8_MMA(1, 1, At, B1); PG8_BAR; PG8_SCHED;
	v_mfma_f32_16x16x32_bf16 v[6:9], v[142:145], v[204:207], v[6:9]
	v_mfma_f32_16x16x32_bf16 v[2:5], v[150:153], v[204:207], v[2:5]
	s_setprio 0
	s_add_i32 s63, 0, 0x18000
	s_add_i32 s64, 0, 0x1c000
	v_add_u32_e32 v134, s63, v237
	v_add_u32_e32 v150, s64, v237
	ds_read_b128 v[98:101], v134
	ds_read_b128 v[110:113], v134 offset:1024
	ds_read_b128 v[122:125], v134 offset:2048
	ds_read_b128 v[134:137], v134 offset:3072
	ds_read_b128 v[138:141], v150
	ds_read_b128 v[142:145], v150 offset:1024
	ds_read_b128 v[146:149], v150 offset:2048
	ds_read_b128 v[150:153], v150 offset:3072
	s_add_u32 s18, s42, 0x40000
	s_addc_u32 s19, s43, 0
	s_mov_b32 m0, s47
	ds_read_b128 v[162:165], v241 offset:32768
	ds_read_b128 v[166:169], v241 offset:33792
	ds_read_b128 v[170:173], v241 offset:34816
	ds_read_b128 v[174:177], v241 offset:35840
	ds_read_b128 v[178:181], v241 offset:36864
	ds_read_b128 v[182:185], v241 offset:37888
	ds_read_b128 v[186:189], v241 offset:38912
	ds_read_b128 v[204:207], v241 offset:39936
	s_mov_b32 m0, s48
	s_nop 0
	s_waitcnt vmcnt(10)
	s_waitcnt lgkmcnt(0)
	s_setprio 1
	s_barrier
	s_waitcnt lgkmcnt(0)
	v_mfma_f32_16x16x32_bf16 v[158:161], v[98:101], v[162:165], v[158:161]
	v_mfma_f32_16x16x32_bf16 v[154:157], v[122:125], v[162:165], v[154:157]
	v_mfma_f32_16x16x32_bf16 v[118:121], v[98:101], v[170:173], v[118:121]
	v_mfma_f32_16x16x32_bf16 v[114:117], v[122:125], v[170:173], v[114:117]
	v_mfma_f32_16x16x32_bf16 v[94:97], v[98:101], v[178:181], v[94:97]
	v_mfma_f32_16x16x32_bf16 v[90:93], v[122:125], v[178:181], v[90:93]
	v_mfma_f32_16x16x32_bf16 v[78:81], v[98:101], v[186:189], v[78:81]
	v_mfma_f32_16x16x32_bf16 v[74:77], v[122:125], v[186:189], v[74:77]
	v_mfma_f32_16x16x32_bf16 v[158:161], v[110:113], v[166:169], v[158:161]
	v_mfma_f32_16x16x32_bf16 v[154:157], v[134:137], v[166:169], v[154:157]
	v_mfma_f32_16x16x32_bf16 v[118:121], v[110:113], v[174:177], v[118:121]
	v_mfma_f32_16x16x32_bf16 v[114:117], v[134:137], v[174:177], v[114:117]
	v_mfma_f32_16x16x32_bf16 v[94:97], v[110:113], v[182:185], v[94:97]
	v_mfma_f32_16x16x32_bf16 v[90:93], v[134:137], v[182:185], v[90:93]
	v_mfma_f32_16x16x32_bf16 v[78:81], v[110:113], v[204:207], v[78:81]
	v_mfma_f32_16x16x32_bf16 v[74:77], v[134:137], v[204:207], v[74:77]
	s_setprio 0
	s_setprio 1
	v_mfma_f32_16x16x32_bf16 v[130:133], v[138:141], v[162:165], v[130:133]
	v_mfma_f32_16x16x32_bf16 v[126:129], v[146:149], v[162:165], v[126:129]
	v_mfma_f32_16x16x32_bf16 v[106:109], v[138:141], v[170:173], v[106:109]
	v_mfma_f32_16x16x32_bf16 v[102:105], v[146:149], v[170:173], v[102:105]
	v_mfma_f32_16x16x32_bf16 v[86:89], v[138:141], v[178:181], v[86:89]
	v_mfma_f32_16x16x32_bf16 v[82:85], v[146:149], v[178:181], v[82:85]
	v_mfma_f32_16x16x32_bf16 v[70:73], v[138:141], v[186:189], v[70:73]
	v_mfma_f32_16x16x32_bf16 v[66:69], v[146:149], v[186:189], v[66:69]
	v_mfma_f32_16x16x32_bf16 v[130:133], v[142:145], v[166:169], v[130:133]
	v_mfma_f32_16x16x32_bf16 v[126:129], v[150:153], v[166:169], v[126:129]
	v_mfma_f32_16x16x32_bf16 v[106:109], v[142:145], v[174:177], v[106:109]
	v_mfma_f32_16x16x32_bf16 v[102:105], v[150:153], v[174:177], v[102:105]
	v_mfma_f32_16x16x32_bf16 v[86:89], v[142:145], v[182:185], v[86:89]
	v_mfma_f32_16x16x32_bf16 v[82:85], v[150:153], v[182:185], v[82:85]
	s_setprio 3
	s_barrier
	v_mfma_f32_16x16x32_bf16 v[70:73], v[142:145], v[204:207], v[70:73]
	v_mfma_f32_16x16x32_bf16 v[66:69], v[150:153], v[204:207], v[66:69]
	s_setprio 0
	s_add_i32 s18, s63, s44
	s_mov_b32 m0, s18
	ds_read_b128 v[162:165], v241 offset:49152
	ds_read_b128 v[166:169], v241 offset:50176
	ds_read_b128 v[170:173], v241 offset:51200
	ds_read_b128 v[174:177], v241 offset:52224
	ds_read_b128 v[178:181], v241 offset:53248
	ds_read_b128 v[182:185], v241 offset:54272
	ds_read_b128 v[186:189], v241 offset:55296
	ds_read_b128 v[204:207], v241 offset:56320
	s_add_i32 m0, s18, 0x2000
	s_add_u32 s18, s30, 0x40080
	s_addc_u32 s19, s31, 0
	s_add_i32 s30, s64, s44
	s_mov_b32 m0, s30
	s_nop 0
	s_add_i32 m0, s30, 0x2000
	s_nop 0
	s_mov_b32 m0, s52
	s_nop 0
	s_mov_b32 m0, s53
	s_nop 0
	s_waitcnt vmcnt(10)
	s_waitcnt lgkmcnt(0)
	s_setprio 1
	s_barrier
	s_waitcnt lgkmcnt(0)
	v_mfma_f32_16x16x32_bf16 v[62:65], v[98:101], v[162:165], v[62:65]
	v_mfma_f32_16x16x32_bf16 v[58:61], v[122:125], v[162:165], v[58:61]
	v_mfma_f32_16x16x32_bf16 v[46:49], v[98:101], v[170:173], v[46:49]
	v_mfma_f32_16x16x32_bf16 v[42:45], v[122:125], v[170:173], v[42:45]
	v_mfma_f32_16x16x32_bf16 v[30:33], v[98:101], v[178:181], v[30:33]
	v_mfma_f32_16x16x32_bf16 v[26:29], v[122:125], v[178:181], v[26:29]
	v_mfma_f32_16x16x32_bf16 v[14:17], v[98:101], v[186:189], v[14:17]
	v_mfma_f32_16x16x32_bf16 v[10:13], v[122:125], v[186:189], v[10:13]
	v_mfma_f32_16x16x32_bf16 v[62:65], v[110:113], v[166:169], v[62:65]
	v_mfma_f32_16x16x32_bf16 v[58:61], v[134:137], v[166:169], v[58:61]
	v_mfma_f32_16x16x32_bf16 v[46:49], v[110:113], v[174:177], v[46:49]
	v_mfma_f32_16x16x32_bf16 v[42:45], v[134:137], v[174:177], v[42:45]
	v_mfma_f32_16x16x32_bf16 v[30:33], v[110:113], v[182:185], v[30:33]
	v_mfma_f32_16x16x32_bf16 v[26:29], v[134:137], v[182:185], v[26:29]
	v_mfma_f32_16x16x32_bf16 v[14:17], v[110:113], v[204:207], v[14:17]
	v_mfma_f32_16x16x32_bf16 v[10:13], v[134:137], v[204:207], v[10:13]
	s_setprio 0
	s_setprio 1
	v_mfma_f32_16x16x32_bf16 v[54:57], v[138:141], v[162:165], v[54:57]
	v_mfma_f32_16x16x32_bf16 v[50:53], v[146:149], v[162:165], v[50:53]
	v_mfma_f32_16x16x32_bf16 v[38:41], v[138:141], v[170:173], v[38:41]
	v_mfma_f32_16x16x32_bf16 v[34:37], v[146:149], v[170:173], v[34:37]
	v_mfma_f32_16x16x32_bf16 v[22:25], v[138:141], v[178:181], v[22:25]
	v_mfma_f32_16x16x32_bf16 v[18:21], v[146:149], v[178:181], v[18:21]
	v_mfma_f32_16x16x32_bf16 v[6:9], v[138:141], v[186:189], v[6:9]
	v_mfma_f32_16x16x32_bf16 v[2:5], v[146:149], v[186:189], v[2:5]
	v_mfma_f32_16x16x32_bf16 v[54:57], v[142:145], v[166:169], v[54:57]
	v_mfma_f32_16x16x32_bf16 v[50:53], v[150:153], v[166:169], v[50:53]
	v_mfma_f32_16x16x32_bf16 v[38:41], v[142:145], v[174:177], v[38:41]
	v_mfma_f32_16x16x32_bf16 v[34:37], v[150:153], v[174:177], v[34:37]
	v_mfma_f32_16x16x32_bf16 v[22:25], v[142:145], v[182:185], v[22:25]
	v_mfma_f32_16x16x32_bf16 v[18:21], v[150:153], v[182:185], v[18:21]
	s_setprio 3
	s_barrier
	v_mfma_f32_16x16x32_bf16 v[6:9], v[142:145], v[204:207], v[6:9]
	v_mfma_f32_16x16x32_bf16 v[2:5], v[150:153], v[204:207], v[2:5]
	s_setprio 0
	s_add_i32 s62, s62, 2
	s_add_u32 s40, s40, 0x100
	s_addc_u32 s41, s41, 0
	s_add_u32 s60, s60, 0x100
	s_addc_u32 s61, s61, 0
	s_branch .Lrp_done_p3

; #define PG8_STAGE(bufoff, gbase, voff) do { _Pragma("unroll") for (int _i = 0; _i < 2; ++_i) \
;         __builtin_amdgcn_global_load_lds((const unsigned*)((const char*)(gbase) + (voff)[_i]), (PG8_LAS unsigned*)(lds + (bufoff) + ldsw + _i * 8192), 16, 0, 0); } while (0)
; #define PG8_LDA(dst, b, h) do { _Pragma("unroll") for (int m = 0; m < 4; ++m) _Pragma("unroll") for (int k = 0; k < 2; ++k) dst[m][k] = *(const PG8_LAS bf16x8*)(lds + PG8_SA(b, h) + aoff + m * 2048 + k * 1024); } while (0)
; #define PG8_LDB(dst, b, h) do { _Pragma("unroll") for (int n = 0; n < 2; ++n) _Pragma("unroll") for (int k = 0; k < 2; ++k) dst[n][k] = *(const PG8_LAS bf16x8*)(lds + PG8_SB(b, h) + boff + n * 2048 + k * 1024); } while (0)
; #define PG8_MMA(ai, bj, At, Bt) do { __builtin_amdgcn_s_setprio(1); _Pragma("unroll") for (int m = 0; m < 4; ++m) _Pragma("unroll") for (int n = 0; n < 2; ++n) _Pragma("unroll") for (int k = 0; k < 2; ++k) \
;         acc[ai][bj][m][n] = __builtin_amdgcn_mfma_f32_16x16x32_bf16(Bt[n][k], At[m][k], acc[ai][bj][m][n], 0, 0, 0); __builtin_amdgcn_s_setprio(0); } while (0)
; #define PG8_WAIT_V(n) asm volatile("s_waitcnt vmcnt(" #n ")" ::: "memory")
; #define PG8_WAIT_L(n) asm volatile("s_waitcnt lgkmcnt(" #n ")" ::: "memory")
; #define PG8_BAR __builtin_amdgcn_s_barrier()
; #define PG8_SCHED __builtin_amdgcn_sched_barrier(0)
; template <class Epi, class Sched, bool ALIGN_EPI = false, bool SP2 = false>
; __device__ __forceinline__ void gemm_phase(PG8_LAS unsigned char* lds, const Gemm g, const Sched& S, const Epi& E) {
;     ...
;             PG8_LDB(B0, 0, 0); PG8_LDB(B1, 0, 1); PG8_SCHED; PG8_LDA(At, 0, 0); PG8_STAGE(PG8_SA(1, 1), a1 + hstep, voffA);
;             PG8_WAIT_V(8); PG8_WAIT_L(0); PG8_BAR; PG8_MMA(0, 0, At, B0); PG8_MMA(0, 1, At, B1); PG8_BAR; PG8_SCHED;
;             PG8_LDA(At, 0, 1); PG8_STAGE(PG8_SB(0, 0), b2, voffB); PG8_STAGE(PG8_SB(0, 1), b2 + hstep, voffB); PG8_STAGE(PG8_SA(0, 0), a2, voffA);
;             PG8_WAIT_V(8); PG8_WAIT_L(0); PG8_BAR; PG8_MMA(1, 0, At, B0); PG8_MMA(1, 1, At, B1); PG8_BAR; PG8_SCHED;
.LBB0_738:
	ds_read_b128 v[148:151], v195
	ds_read_b128 v[152:155], v195 offset:1024
	ds_read_b128 v[156:159], v195 offset:2048
	ds_read_b128 v[160:163], v195 offset:3072
	ds_read_b128 v[164:167], v196
	ds_read_b128 v[168:171], v196 offset:1024
	ds_read_b128 v[172:175], v196 offset:2048
	ds_read_b128 v[198:201], v196 offset:3072
	s_add_u32 s6, s4, 0xfffc0080
	s_addc_u32 s7, s5, -1
	s_cmp_eq_u32 s66, 12
	s_cselect_b32 s31, s1, s7
	s_cselect_b32 s30, s41, s6
	s_cselect_b32 s7, s39, s47
	s_cselect_b32 s6, s65, s46
	v_lshl_add_u64 v[176:177], s[4:5], 0, v[140:141]
	s_add_i32 m0, s49, 0xc000
	ds_read_b128 v[202:205], v197
	ds_read_b128 v[206:209], v197 offset:1024
	ds_read_b128 v[210:213], v197 offset:2048
	ds_read_b128 v[214:217], v197 offset:3072
	ds_read_b128 v[218:221], v197 offset:4096
	ds_read_b128 v[222:225], v197 offset:5120
	ds_read_b128 v[226:229], v197 offset:6144
	ds_read_b128 v[230:233], v197 offset:7168
	global_load_lds_dwordx4 v[176:177], off
	v_lshl_add_u64 v[176:177], s[4:5], 0, v[142:143]
	s_add_i32 m0, s49, 0xe000
	s_nop 0
	global_load_lds_dwordx4 v[176:177], off
	s_waitcnt vmcnt(8)
	s_waitcnt lgkmcnt(0)
	s_setprio 1
	s_barrier
	s_waitcnt lgkmcnt(0)
	v_mfma_f32_16x16x32_bf16 v[126:129], v[148:151], v[202:205], v[126:129]
	v_mfma_f32_16x16x32_bf16 v[118:121], v[156:159], v[202:205], v[118:121]
	v_mfma_f32_16x16x32_bf16 v[110:113], v[148:151], v[210:213], v[110:113]
	v_mfma_f32_16x16x32_bf16 v[102:105], v[156:159], v[210:213], v[102:105]
	v_mfma_f32_16x16x32_bf16 v[94:97], v[148:151], v[218:221], v[94:97]
	v_mfma_f32_16x16x32_bf16 v[86:89], v[156:159], v[218:221], v[86:89]
	v_mfma_f32_16x16x32_bf16 v[78:81], v[148:151], v[226:229], v[78:81]
	v_mfma_f32_16x16x32_bf16 v[70:73], v[156:159], v[226:229], v[70:73]
	v_mfma_f32_16x16x32_bf16 v[126:129], v[152:155], v[206:209], v[126:129]
	v_mfma_f32_16x16x32_bf16 v[118:121], v[160:163], v[206:209], v[118:121]
	v_mfma_f32_16x16x32_bf16 v[110:113], v[152:155], v[214:217], v[110:113]
	v_mfma_f32_16x16x32_bf16 v[102:105], v[160:163], v[214:217], v[102:105]
	v_mfma_f32_16x16x32_bf16 v[94:97], v[152:155], v[222:225], v[94:97]
	v_mfma_f32_16x16x32_bf16 v[86:89], v[160:163], v[222:225], v[86:89]
	v_mfma_f32_16x16x32_bf16 v[78:81], v[152:155], v[230:233], v[78:81]
	v_mfma_f32_16x16x32_bf16 v[70:73], v[160:163], v[230:233], v[70:73]
	s_setprio 0
	s_setprio 1
	v_mfma_f32_16x16x32_bf16 v[122:125], v[164:167], v[202:205], v[122:125]
	v_mfma_f32_16x16x32_bf16 v[114:117], v[172:175], v[202:205], v[114:117]
	v_mfma_f32_16x16x32_bf16 v[106:109], v[164:167], v[210:213], v[106:109]
	v_mfma_f32_16x16x32_bf16 v[98:101], v[172:175], v[210:213], v[98:101]
	v_mfma_f32_16x16x32_bf16 v[90:93], v[164:167], v[218:221], v[90:93]
	v_mfma_f32_16x16x32_bf16 v[82:85], v[172:175], v[218:221], v[82:85]
	v_mfma_f32_16x16x32_bf16 v[74:77], v[164:167], v[226:229], v[74:77]
	v_mfma_f32_16x16x32_bf16 v[66:69], v[172:175], v[226:229], v[66:69]
	v_mfma_f32_16x16x32_bf16 v[122:125], v[168:171], v[206:209], v[122:125]
	v_mfma_f32_16x16x32_bf16 v[114:117], v[198:201], v[206:209], v[114:117]
	v_mfma_f32_16x16x32_bf16 v[106:109], v[168:171], v[214:217], v[106:109]
	v_mfma_f32_16x16x32_bf16 v[98:101], v[198:201], v[214:217], v[98:101]
	v_mfma_f32_16x16x32_bf16 v[90:93], v[168:171], v[222:225], v[90:93]
	v_mfma_f32_16x16x32_bf16 v[82:85], v[198:201], v[222:225], v[82:85]
	s_setprio 3
	s_barrier
	v_mfma_f32_16x16x32_bf16 v[74:77], v[168:171], v[230:233], v[74:77]
	v_mfma_f32_16x16x32_bf16 v[66:69], v[198:201], v[230:233], v[66:69]
	s_setprio 0
	s_add_i32 s18, s59, s25
	v_lshl_add_u64 v[176:177], s[6:7], 0, v[134:135]
	s_mov_b32 m0, s18
	ds_read_b128 v[202:205], v197 offset:16384
	ds_read_b128 v[206:209], v197 offset:17408
	ds_read_b128 v[210:213], v197 offset:18432
	ds_read_b128 v[214:217], v197 offset:19456
	ds_read_b128 v[218:221], v197 offset:20480
	ds_read_b128 v[222:225], v197 offset:21504
	ds_read_b128 v[226:229], v197 offset:22528
	ds_read_b128 v[230:233], v197 offset:23552
	global_load_lds_dwordx4 v[176:177], off
	s_add_i32 m0, s18, 0x2000
	s_add_u32 s18, s6, 0x40000
	v_lshl_add_u64 v[234:235], s[6:7], 0, v[130:131]
	s_addc_u32 s19, s7, 0
	s_add_i32 s67, s60, s25
	global_load_lds_dwordx4 v[234:235], off
	v_lshl_add_u64 v[238:239], s[18:19], 0, v[134:135]
	s_mov_b32 m0, s67
	v_lshl_add_u64 v[240:241], s[30:31], 0, v[132:133]
	global_load_lds_dwordx4 v[238:239], off
	v_lshl_add_u64 v[238:239], s[18:19], 0, v[130:131]
	s_add_i32 m0, s67, 0x2000
	s_nop 0
	global_load_lds_dwordx4 v[238:239], off
	v_lshl_add_u64 v[238:239], s[30:31], 0, v[136:137]
	s_mov_b32 m0, s49
	s_nop 0
	global_load_lds_dwordx4 v[238:239], off
	s_mov_b32 m0, s52
	s_nop 0
	global_load_lds_dwordx4 v[240:241], off
	s_waitcnt vmcnt(8)
	s_waitcnt lgkmcnt(0)
	s_setprio 1
	s_barrier
; #define PG8_STAGE(bufoff, gbase, voff) do { _Pragma("unroll") for (int _i = 0; _i < 2; ++_i) \
;         __builtin_amdgcn_global_load_lds((const unsigned*)((const char*)(gbase) + (voff)[_i]), (PG8_LAS unsigned*)(lds + (bufoff) + ldsw + _i * 8192), 16, 0, 0); } while (0)
; #define PG8_LDA(dst, b, h) do { _Pragma("unroll") for (int m = 0; m < 4; ++m) _Pragma("unroll") for (int k = 0; k < 2; ++k) dst[m][k] = *(const PG8_LAS bf16x8*)(lds + PG8_SA(b, h) + aoff + m * 2048 + k * 1024); } while (0)
; #define PG8_LDB(dst, b, h) do { _Pragma("unroll") for (int n = 0; n < 2; ++n) _Pragma("unroll") for (int k = 0; k < 2; ++k) dst[n][k] = *(const PG8_LAS bf16x8*)(lds + PG8_SB(b, h) + boff + n * 2048 + k * 1024); } while (0)
; #define PG8_MMA(ai, bj, At, Bt) do { __builtin_amdgcn_s_setprio(1); _Pragma("unroll") for (int m = 0; m < 4; ++m) _Pragma("unroll") for (int n = 0; n < 2; ++n) _Pragma("unroll") for (int k = 0; k < 2; ++k) \
;         acc[ai][bj][m][n] = __builtin_amdgcn_mfma_f32_16x16x32_bf16(Bt[n][k], At[m][k], acc[ai][bj][m][n], 0, 0, 0); __builtin_amdgcn_s_setprio(0); } while (0)
; #define PG8_WAIT_V(n) asm volatile("s_waitcnt vmcnt(" #n ")" ::: "memory")
; #define PG8_WAIT_L(n) asm volatile("s_waitcnt lgkmcnt(" #n ")" ::: "memory")
; #define PG8_BAR __builtin_amdgcn_s_barrier()
; #define PG8_SCHED __builtin_amdgcn_sched_barrier(0)
; template <class Epi, class Sched, bool ALIGN_EPI = false, bool SP2 = false>
; __device__ __forceinline__ void gemm_phase(PG8_LAS unsigned char* lds, const Gemm g, const Sched& S, const Epi& E) {
;     ...
;             PG8_WAIT_V(8); PG8_WAIT_L(0); PG8_BAR; PG8_MMA(1, 0, At, B0); PG8_MMA(1, 1, At, B1); PG8_BAR; PG8_SCHED;
;             PG8_LDB(B0, 1, 0); PG8_LDB(B1, 1, 1); PG8_SCHED; PG8_LDA(At, 1, 0); PG8_STAGE(PG8_SA(0, 1), a2 + hstep, voffA);
;             PG8_WAIT_V(8); PG8_WAIT_L(0); PG8_BAR; PG8_MMA(0, 0, At, B0); PG8_MMA(0, 1, At, B1); PG8_BAR; PG8_SCHED;
	s_waitcnt lgkmcnt(0)
	v_mfma_f32_16x16x32_bf16 v[62:65], v[148:151], v[202:205], v[62:65]
	v_mfma_f32_16x16x32_bf16 v[54:57], v[156:159], v[202:205], v[54:57]
	v_mfma_f32_16x16x32_bf16 v[46:49], v[148:151], v[210:213], v[46:49]
	v_mfma_f32_16x16x32_bf16 v[38:41], v[156:159], v[210:213], v[38:41]
	v_mfma_f32_16x16x32_bf16 v[30:33], v[148:151], v[218:221], v[30:33]
	v_mfma_f32_16x16x32_bf16 v[22:25], v[156:159], v[218:221], v[22:25]
	v_mfma_f32_16x16x32_bf16 v[14:17], v[148:151], v[226:229], v[14:17]
	v_mfma_f32_16x16x32_bf16 v[6:9], v[156:159], v[226:229], v[6:9]
	v_mfma_f32_16x16x32_bf16 v[62:65], v[152:155], v[206:209], v[62:65]
	v_mfma_f32_16x16x32_bf16 v[54:57], v[160:163], v[206:209], v[54:57]
	v_mfma_f32_16x16x32_bf16 v[46:49], v[152:155], v[214:217], v[46:49]
	v_mfma_f32_16x16x32_bf16 v[38:41], v[160:163], v[214:217], v[38:41]
	v_mfma_f32_16x16x32_bf16 v[30:33], v[152:155], v[222:225], v[30:33]
	v_mfma_f32_16x16x32_bf16 v[22:25], v[160:163], v[222:225], v[22:25]
	v_mfma_f32_16x16x32_bf16 v[14:17], v[152:155], v[230:233], v[14:17]
	v_mfma_f32_16x16x32_bf16 v[6:9], v[160:163], v[230:233], v[6:9]
	s_setprio 0
	s_setprio 1
	v_mfma_f32_16x16x32_bf16 v[58:61], v[164:167], v[202:205], v[58:61]
	v_mfma_f32_16x16x32_bf16 v[50:53], v[172:175], v[202:205], v[50:53]
	v_mfma_f32_16x16x32_bf16 v[42:45], v[164:167], v[210:213], v[42:45]
	v_mfma_f32_16x16x32_bf16 v[34:37], v[172:175], v[210:213], v[34:37]
	v_mfma_f32_16x16x32_bf16 v[26:29], v[164:167], v[218:221], v[26:29]
	v_mfma_f32_16x16x32_bf16 v[18:21], v[172:175], v[218:221], v[18:21]
	v_mfma_f32_16x16x32_bf16 v[10:13], v[164:167], v[226:229], v[10:13]
	v_mfma_f32_16x16x32_bf16 v[2:5], v[172:175], v[226:229], v[2:5]
	v_mfma_f32_16x16x32_bf16 v[58:61], v[168:171], v[206:209], v[58:61]
	v_mfma_f32_16x16x32_bf16 v[50:53], v[198:201], v[206:209], v[50:53]
	v_mfma_f32_16x16x32_bf16 v[42:45], v[168:171], v[214:217], v[42:45]
	v_mfma_f32_16x16x32_bf16 v[34:37], v[198:201], v[214:217], v[34:37]
	v_mfma_f32_16x16x32_bf16 v[26:29], v[168:171], v[222:225], v[26:29]
	v_mfma_f32_16x16x32_bf16 v[18:21], v[198:201], v[222:225], v[18:21]
	s_setprio 3
	s_barrier
	v_mfma_f32_16x16x32_bf16 v[10:13], v[168:171], v[230:233], v[10:13]
	v_mfma_f32_16x16x32_bf16 v[2:5], v[198:201], v[230:233], v[2:5]
	s_setprio 0
	s_add_i32 s67, 0, 0x18000
	s_add_i32 s68, 0, 0x1c000
	v_add_u32_e32 v160, s67, v192
	v_add_u32_e32 v198, s68, v192
	ds_read_b128 v[148:151], v160
	ds_read_b128 v[152:155], v160 offset:1024
	ds_read_b128 v[156:159], v160 offset:2048
	ds_read_b128 v[160:163], v160 offset:3072
	ds_read_b128 v[164:167], v198
	ds_read_b128 v[168:171], v198 offset:1024
	ds_read_b128 v[172:175], v198 offset:2048
	ds_read_b128 v[198:201], v198 offset:3072
	s_add_u32 s18, s30, 0x40000
	s_addc_u32 s19, s31, 0
	s_mov_b32 m0, s53
	v_lshl_add_u64 v[242:243], s[18:19], 0, v[136:137]
	ds_read_b128 v[202:205], v197 offset:32768
	ds_read_b128 v[206:209], v197 offset:33792
	ds_read_b128 v[210:213], v197 offset:34816
	ds_read_b128 v[214:217], v197 offset:35840
	ds_read_b128 v[218:221], v197 offset:36864
	ds_read_b128 v[222:225], v197 offset:37888
	ds_read_b128 v[226:229], v197 offset:38912
	ds_read_b128 v[230:233], v197 offset:39936
	global_load_lds_dwordx4 v[242:243], off
	v_lshl_add_u64 v[242:243], s[18:19], 0, v[132:133]
	s_mov_b32 m0, s54
	s_nop 0
	global_load_lds_dwordx4 v[242:243], off
	s_waitcnt vmcnt(8)
	s_waitcnt lgkmcnt(0)
	s_setprio 1
	s_barrier
	s_waitcnt lgkmcnt(0)
	v_mfma_f32_16x16x32_bf16 v[126:129], v[148:151], v[202:205], v[126:129]
	v_mfma_f32_16x16x32_bf16 v[118:121], v[156:159], v[202:205], v[118:121]
	v_mfma_f32_16x16x32_bf16 v[110:113], v[148:151], v[210:213], v[110:113]
	v_mfma_f32_16x16x32_bf16 v[102:105], v[156:159], v[210:213], v[102:105]
	v_mfma_f32_16x16x32_bf16 v[94:97], v[148:151], v[218:221], v[94:97]
	v_mfma_f32_16x16x32_bf16 v[86:89], v[156:159], v[218:221], v[86:89]
	v_mfma_f32_16x16x32_bf16 v[78:81], v[148:151], v[226:229], v[78:81]
	v_mfma_f32_16x16x32_bf16 v[70:73], v[156:159], v[226:229], v[70:73]
	v_mfma_f32_16x16x32_bf16 v[126:129], v[152:155], v[206:209], v[126:129]
	v_mfma_f32_16x16x32_bf16 v[118:121], v[160:163], v[206:209], v[118:121]
	v_mfma_f32_16x16x32_bf16 v[110:113], v[152:155], v[214:217], v[110:113]
	v_mfma_f32_16x16x32_bf16 v[102:105], v[160:163], v[214:217], v[102:105]
	v_mfma_f32_16x16x32_bf16 v[94:97], v[152:155], v[222:225], v[94:97]
	v_mfma_f32_16x16x32_bf16 v[86:89], v[160:163], v[222:225], v[86:89]
	v_mfma_f32_16x16x32_bf16 v[78:81], v[152:155], v[230:233], v[78:81]
	v_mfma_f32_16x16x32_bf16 v[70:73], v[160:163], v[230:233], v[70:73]
	s_setprio 0
	s_setprio 1
	v_mfma_f32_16x16x32_bf16 v[122:125], v[164:167], v[202:205], v[122:125]
	v_mfma_f32_16x16x32_bf16 v[114:117], v[172:175], v[202:205], v[114:117]
	v_mfma_f32_16x16x32_bf16 v[106:109], v[164:167], v[210:213], v[106:109]
	v_mfma_f32_16x16x32_bf16 v[98:101], v[172:175], v[210:213], v[98:101]
	v_mfma_f32_16x16x32_bf16 v[90:93], v[164:167], v[218:221], v[90:93]
	v_mfma_f32_16x16x32_bf16 v[82:85], v[172:175], v[218:221], v[82:85]
	v_mfma_f32_16x16x32_bf16 v[74:77], v[164:167], v[226:229], v[74:77]
	v_mfma_f32_16x16x32_bf16 v[66:69], v[172:175], v[226:229], v[66:69]
	v_mfma_f32_16x16x32_bf16 v[122:125], v[168:171], v[206:209], v[122:125]
	v_mfma_f32_16x16x32_bf16 v[114:117], v[198:201], v[206:209], v[114:117]
	v_mfma_f32_16x16x32_bf16 v[106:109], v[168:171], v[214:217], v[106:109]
	v_mfma_f32_16x16x32_bf16 v[98:101], v[198:201], v[214:217], v[98:101]
	v_mfma_f32_16x16x32_bf16 v[90:93], v[168:171], v[222:225], v[90:93]
	v_mfma_f32_16x16x32_bf16 v[82:85], v[198:201], v[222:225], v[82:85]
	s_setprio 3
	s_barrier
; #define PG8_STAGE(bufoff, gbase, voff) do { _Pragma("unroll") for (int _i = 0; _i < 2; ++_i) \
;         __builtin_amdgcn_global_load_lds((const unsigned*)((const char*)(gbase) + (voff)[_i]), (PG8_LAS unsigned*)(lds + (bufoff) + ldsw + _i * 8192), 16, 0, 0); } while (0)
; #define PG8_LDA(dst, b, h) do { _Pragma("unroll") for (int m = 0; m < 4; ++m) _Pragma("unroll") for (int k = 0; k < 2; ++k) dst[m][k] = *(const PG8_LAS bf16x8*)(lds + PG8_SA(b, h) + aoff + m * 2048 + k * 1024); } while (0)
; #define PG8_MMA(ai, bj, At, Bt) do { __builtin_amdgcn_s_setprio(1); _Pragma("unroll") for (int m = 0; m < 4; ++m) _Pragma("unroll") for (int n = 0; n < 2; ++n) _Pragma("unroll") for (int k = 0; k < 2; ++k) \
;         acc[ai][bj][m][n] = __builtin_amdgcn_mfma_f32_16x16x32_bf16(Bt[n][k], At[m][k], acc[ai][bj][m][n], 0, 0, 0); __builtin_amdgcn_s_setprio(0); } while (0)
; #define PG8_WAIT_V(n) asm volatile("s_waitcnt vmcnt(" #n ")" ::: "memory")
; #define PG8_WAIT_L(n) asm volatile("s_waitcnt lgkmcnt(" #n ")" ::: "memory")
; #define PG8_BAR __builtin_amdgcn_s_barrier()
; #define PG8_SCHED __builtin_amdgcn_sched_barrier(0)
; template <class Epi, class Sched, bool ALIGN_EPI = false, bool SP2 = false>
; __device__ __forceinline__ void gemm_phase(PG8_LAS unsigned char* lds, const Gemm g, const Sched& S, const Epi& E) {
;     ...
;             PG8_LDA(At, 1, 1); PG8_STAGE(PG8_SB(1, 0), b3, voffB); PG8_STAGE(PG8_SB(1, 1), b3 + hstep, voffB); PG8_STAGE(PG8_SA(1, 0), a3, voffA);
;             PG8_WAIT_V(8); PG8_WAIT_L(0); PG8_BAR; PG8_MMA(1, 0, At, B0); PG8_MMA(1, 1, At, B1); PG8_BAR; PG8_SCHED;
	v_mfma_f32_16x16x32_bf16 v[74:77], v[168:171], v[230:233], v[74:77]
	v_mfma_f32_16x16x32_bf16 v[66:69], v[198:201], v[230:233], v[66:69]
	s_setprio 0
	s_add_i32 s18, s67, s25
	v_lshl_add_u64 v[176:177], v[176:177], 0, s[14:15]
	s_mov_b32 m0, s18
	ds_read_b128 v[202:205], v197 offset:49152
	ds_read_b128 v[206:209], v197 offset:50176
	ds_read_b128 v[210:213], v197 offset:51200
	ds_read_b128 v[214:217], v197 offset:52224
	ds_read_b128 v[218:221], v197 offset:53248
	ds_read_b128 v[222:225], v197 offset:54272
	ds_read_b128 v[226:229], v197 offset:55296
	ds_read_b128 v[230:233], v197 offset:56320
	global_load_lds_dwordx4 v[176:177], off
	s_add_i32 m0, s18, 0x2000
	s_add_u32 s6, s6, 0x40080
	v_lshl_add_u64 v[176:177], v[234:235], 0, s[14:15]
	s_addc_u32 s7, s7, 0
	s_add_i32 s18, s68, s25
	global_load_lds_dwordx4 v[176:177], off
	v_lshl_add_u64 v[176:177], s[6:7], 0, v[134:135]
	s_mov_b32 m0, s18
	s_nop 0
	global_load_lds_dwordx4 v[176:177], off
	v_lshl_add_u64 v[176:177], s[6:7], 0, v[130:131]
	s_add_i32 m0, s18, 0x2000
	s_nop 0
	global_load_lds_dwordx4 v[176:177], off
	v_lshl_add_u64 v[176:177], v[238:239], 0, s[14:15]
	s_mov_b32 m0, s56
	s_nop 0
	global_load_lds_dwordx4 v[176:177], off
	v_lshl_add_u64 v[176:177], v[240:241], 0, s[14:15]
	s_mov_b32 m0, s57
	s_nop 0
	global_load_lds_dwordx4 v[176:177], off
	s_waitcnt vmcnt(8)
	s_waitcnt lgkmcnt(0)
	s_setprio 1
	s_barrier
	s_waitcnt lgkmcnt(0)
	v_mfma_f32_16x16x32_bf16 v[62:65], v[148:151], v[202:205], v[62:65]
	v_mfma_f32_16x16x32_bf16 v[54:57], v[156:159], v[202:205], v[54:57]
	v_mfma_f32_16x16x32_bf16 v[46:49], v[148:151], v[210:213], v[46:49]
	v_mfma_f32_16x16x32_bf16 v[38:41], v[156:159], v[210:213], v[38:41]
	v_mfma_f32_16x16x32_bf16 v[30:33], v[148:151], v[218:221], v[30:33]
	v_mfma_f32_16x16x32_bf16 v[22:25], v[156:159], v[218:221], v[22:25]
	v_mfma_f32_16x16x32_bf16 v[14:17], v[148:151], v[226:229], v[14:17]
	v_mfma_f32_16x16x32_bf16 v[6:9], v[156:159], v[226:229], v[6:9]
	v_mfma_f32_16x16x32_bf16 v[62:65], v[152:155], v[206:209], v[62:65]
	v_mfma_f32_16x16x32_bf16 v[54:57], v[160:163], v[206:209], v[54:57]
	v_mfma_f32_16x16x32_bf16 v[46:49], v[152:155], v[214:217], v[46:49]
	v_mfma_f32_16x16x32_bf16 v[38:41], v[160:163], v[214:217], v[38:41]
	v_mfma_f32_16x16x32_bf16 v[30:33], v[152:155], v[222:225], v[30:33]
	v_mfma_f32_16x16x32_bf16 v[22:25], v[160:163], v[222:225], v[22:25]
	v_mfma_f32_16x16x32_bf16 v[14:17], v[152:155], v[230:233], v[14:17]
	v_mfma_f32_16x16x32_bf16 v[6:9], v[160:163], v[230:233], v[6:9]
	s_setprio 0
	s_setprio 1
	v_mfma_f32_16x16x32_bf16 v[58:61], v[164:167], v[202:205], v[58:61]
	v_mfma_f32_16x16x32_bf16 v[50:53], v[172:175], v[202:205], v[50:53]
	v_mfma_f32_16x16x32_bf16 v[42:45], v[164:167], v[210:213], v[42:45]
	v_mfma_f32_16x16x32_bf16 v[34:37], v[172:175], v[210:213], v[34:37]
	v_mfma_f32_16x16x32_bf16 v[26:29], v[164:167], v[218:221], v[26:29]
	v_mfma_f32_16x16x32_bf16 v[18:21], v[172:175], v[218:221], v[18:21]
	v_mfma_f32_16x16x32_bf16 v[10:13], v[164:167], v[226:229], v[10:13]
	v_mfma_f32_16x16x32_bf16 v[2:5], v[172:175], v[226:229], v[2:5]
	v_mfma_f32_16x16x32_bf16 v[58:61], v[168:171], v[206:209], v[58:61]
	v_mfma_f32_16x16x32_bf16 v[50:53], v[198:201], v[206:209], v[50:53]
	v_mfma_f32_16x16x32_bf16 v[42:45], v[168:171], v[214:217], v[42:45]
	v_mfma_f32_16x16x32_bf16 v[34:37], v[198:201], v[214:217], v[34:37]
	v_mfma_f32_16x16x32_bf16 v[26:29], v[168:171], v[222:225], v[26:29]
	v_mfma_f32_16x16x32_bf16 v[18:21], v[198:201], v[222:225], v[18:21]
	s_setprio 3
	s_barrier
	v_mfma_f32_16x16x32_bf16 v[10:13], v[168:171], v[230:233], v[10:13]
	v_mfma_f32_16x16x32_bf16 v[2:5], v[198:201], v[230:233], v[2:5]
	s_setprio 0
	s_add_i32 s66, s66, 2
	s_add_u32 s4, s4, 0x100
	s_addc_u32 s5, s5, 0
	s_add_u32 s46, s46, 0x100
	s_addc_u32 s47, s47, 0
	s_cmp_gt_u32 s66, 13
	s_cbranch_scc0 .LBB0_738
	s_and_b64 vcc, exec, s[16:17]
	s_cbranch_vccz .LBB0_741
	s_barrier

; #define PG8_STAGE(bufoff, gbase, voff) do { _Pragma("unroll") for (int _i = 0; _i < 2; ++_i) \
;         __builtin_amdgcn_global_load_lds((const unsigned*)((const char*)(gbase) + (voff)[_i]), (PG8_LAS unsigned*)(lds + (bufoff) + ldsw + _i * 8192), 16, 0, 0); } while (0)
; #define PG8_LDA(dst, b, h) do { _Pragma("unroll") for (int m = 0; m < 4; ++m) _Pragma("unroll") for (int k = 0; k < 2; ++k) dst[m][k] = *(const PG8_LAS bf16x8*)(lds + PG8_SA(b, h) + aoff + m * 2048 + k * 1024); } while (0)
; #define PG8_LDB(dst, b, h) do { _Pragma("unroll") for (int n = 0; n < 2; ++n) _Pragma("unroll") for (int k = 0; k < 2; ++k) dst[n][k] = *(const PG8_LAS bf16x8*)(lds + PG8_SB(b, h) + boff + n * 2048 + k * 1024); } while (0)
; template <class Epi, class Sched, bool ALIGN_EPI = false, bool SP2 = false>
; __device__ __forceinline__ void gemm_phase(PG8_LAS unsigned char* lds, const Gemm g, const Sched& S, const Epi& E) {
;     ...
;         for (int t = 0; t < nt; t += 2) {
;             const bool last = (t == nt - 2);
;             const char* a1 = cA + (size_t)(t + 1) * kstep;
;             const char* a2 = last ? nA : cA + (size_t)(t + 2) * kstep; const char* b2 = last ? nB : cB + (size_t)(t + 2) * kstep;
;             const char* a3 = a2 + kstep; const char* b3 = b2 + kstep;
;             if (last && has_next) S.a_ready(nxt);
;             if constexpr (SP2) {
;             PG8_LDB(B0, 0, 0); PG8_LDB(B1, 0, 1); PG8_SCHED; PG8_LDA(At, 0, 0); PG8_STAGE(PG8_SA(1, 1), a1 + hstep, voffA);
;             PG8_WAIT_V(8); PG8_WAIT_L(0); PG8_BAR; PG8_MMA(0, 0, At, B0); PG8_MMA(0, 1, At, B1); PG8_BAR; PG8_SCHED;
;             PG8_LDA(At, 0, 1); PG8_STAGE(PG8_SB(0, 0), b2, voffB); PG8_STAGE(PG8_SB(0, 1), b2 + hstep, voffB); PG8_STAGE(PG8_SA(0, 0), a2, voffA);
;             PG8_WAIT_V(8); PG8_WAIT_L(0); PG8_BAR; PG8_MMA(1, 0, At, B0); PG8_MMA(1, 1, At, B1); PG8_BAR; PG8_SCHED;
;             PG8_LDB(B0, 1, 0); PG8_LDB(B1, 1, 1); PG8_SCHED; PG8_LDA(At, 1, 0); PG8_STAGE(PG8_SA(0, 1), a2 + hstep, voffA);
;             PG8_WAIT_V(8); PG8_WAIT_L(0); PG8_BAR; PG8_MMA(0, 0, At, B0); PG8_MMA(0, 1, At, B1); PG8_BAR; PG8_SCHED;
;             PG8_LDA(At, 1, 1); PG8_STAGE(PG8_SB(1, 0), b3, voffB); PG8_STAGE(PG8_SB(1, 1), b3 + hstep, voffB); PG8_STAGE(PG8_SA(1, 0), a3, voffA);
;             PG8_WAIT_V(8); PG8_WAIT_L(0); PG8_BAR; PG8_MMA(1, 0, At, B0); PG8_MMA(1, 1, At, B1); PG8_BAR; PG8_SCHED;
.LBB0_777:
	ds_read_b128 v[148:151], v1
	ds_read_b128 v[152:155], v1 offset:1024
	ds_read_b128 v[156:159], v1 offset:2048
	ds_read_b128 v[160:163], v1 offset:3072
	ds_read_b128 v[164:167], v145
	ds_read_b128 v[168:171], v145 offset:1024
	ds_read_b128 v[172:175], v145 offset:2048
	ds_read_b128 v[176:179], v145 offset:3072
	s_add_i32 s76, s30, 2
	s_add_u32 s18, s46, 0x80
	s_addc_u32 s19, s47, 0
	s_cmp_eq_u32 s67, s30
	s_cselect_b32 s30, s42, s18
	s_cselect_b32 s31, s43, s19
	s_cselect_b32 s19, s45, s49
	s_cselect_b32 s18, s44, s48
	v_lshl_add_u64 v[212:213], s[46:47], 0, v[138:139]
	s_add_i32 m0, s53, 0xc000
	ds_read_b128 v[180:183], v146
	ds_read_b128 v[184:187], v146 offset:1024
	ds_read_b128 v[188:191], v146 offset:2048
	ds_read_b128 v[192:195], v146 offset:3072
	ds_read_b128 v[196:199], v146 offset:4096
	ds_read_b128 v[200:203], v146 offset:5120
	ds_read_b128 v[204:207], v146 offset:6144
	ds_read_b128 v[208:211], v146 offset:7168
	global_load_lds_dwordx4 v[212:213], off
	v_lshl_add_u64 v[212:213], s[46:47], 0, v[140:141]
	s_add_i32 m0, s53, 0xe000
	s_nop 0
	global_load_lds_dwordx4 v[212:213], off
	s_waitcnt vmcnt(8)
	s_waitcnt lgkmcnt(0)
	s_setprio 1
	s_barrier
	s_waitcnt lgkmcnt(0)
	v_mfma_f32_16x16x32_bf16 v[122:125], v[148:151], v[180:183], v[122:125]
	v_mfma_f32_16x16x32_bf16 v[126:129], v[156:159], v[180:183], v[126:129]
	v_mfma_f32_16x16x32_bf16 v[110:113], v[148:151], v[188:191], v[110:113]
	v_mfma_f32_16x16x32_bf16 v[106:109], v[156:159], v[188:191], v[106:109]
	v_mfma_f32_16x16x32_bf16 v[94:97], v[148:151], v[196:199], v[94:97]
	v_mfma_f32_16x16x32_bf16 v[90:93], v[156:159], v[196:199], v[90:93]
	v_mfma_f32_16x16x32_bf16 v[78:81], v[148:151], v[204:207], v[78:81]
	v_mfma_f32_16x16x32_bf16 v[74:77], v[156:159], v[204:207], v[74:77]
	v_mfma_f32_16x16x32_bf16 v[122:125], v[152:155], v[184:187], v[122:125]
	v_mfma_f32_16x16x32_bf16 v[126:129], v[160:163], v[184:187], v[126:129]
	v_mfma_f32_16x16x32_bf16 v[110:113], v[152:155], v[192:195], v[110:113]
	v_mfma_f32_16x16x32_bf16 v[106:109], v[160:163], v[192:195], v[106:109]
	v_mfma_f32_16x16x32_bf16 v[94:97], v[152:155], v[200:203], v[94:97]
	v_mfma_f32_16x16x32_bf16 v[90:93], v[160:163], v[200:203], v[90:93]
	v_mfma_f32_16x16x32_bf16 v[78:81], v[152:155], v[208:211], v[78:81]
	v_mfma_f32_16x16x32_bf16 v[74:77], v[160:163], v[208:211], v[74:77]
	s_setprio 0
	s_setprio 1
	v_mfma_f32_16x16x32_bf16 v[118:121], v[164:167], v[180:183], v[118:121]
	v_mfma_f32_16x16x32_bf16 v[114:117], v[172:175], v[180:183], v[114:117]
	v_mfma_f32_16x16x32_bf16 v[102:105], v[164:167], v[188:191], v[102:105]
	v_mfma_f32_16x16x32_bf16 v[98:101], v[172:175], v[188:191], v[98:101]
	v_mfma_f32_16x16x32_bf16 v[86:89], v[164:167], v[196:199], v[86:89]
	v_mfma_f32_16x16x32_bf16 v[82:85], v[172:175], v[196:199], v[82:85]
	v_mfma_f32_16x16x32_bf16 v[70:73], v[164:167], v[204:207], v[70:73]
	v_mfma_f32_16x16x32_bf16 v[66:69], v[172:175], v[204:207], v[66:69]
	v_mfma_f32_16x16x32_bf16 v[118:121], v[168:171], v[184:187], v[118:121]
	v_mfma_f32_16x16x32_bf16 v[114:117], v[176:179], v[184:187], v[114:117]
	v_mfma_f32_16x16x32_bf16 v[102:105], v[168:171], v[192:195], v[102:105]
	v_mfma_f32_16x16x32_bf16 v[98:101], v[176:179], v[192:195], v[98:101]
	v_mfma_f32_16x16x32_bf16 v[86:89], v[168:171], v[200:203], v[86:89]
	v_mfma_f32_16x16x32_bf16 v[82:85], v[176:179], v[200:203], v[82:85]
	s_setprio 3
	s_barrier
	v_mfma_f32_16x16x32_bf16 v[70:73], v[168:171], v[208:211], v[70:73]
	v_mfma_f32_16x16x32_bf16 v[66:69], v[176:179], v[208:211], v[66:69]
	s_setprio 0
	s_add_i32 s77, s68, s52
	v_lshl_add_u64 v[212:213], s[18:19], 0, v[132:133]
	s_mov_b32 m0, s77
	ds_read_b128 v[180:183], v146 offset:16384
	ds_read_b128 v[184:187], v146 offset:17408
	ds_read_b128 v[188:191], v146 offset:18432
	ds_read_b128 v[192:195], v146 offset:19456
	ds_read_b128 v[196:199], v146 offset:20480
	ds_read_b128 v[200:203], v146 offset:21504
	ds_read_b128 v[204:207], v146 offset:22528
	ds_read_b128 v[208:211], v146 offset:23552
	global_load_lds_dwordx4 v[212:213], off
	s_add_i32 m0, s77, 0x2000
	v_lshl_add_u64 v[214:215], s[18:19], 0, v[136:137]
	s_add_u32 s18, s18, s4
	s_addc_u32 s19, s19, s5
	s_add_i32 s77, s69, s52
	global_load_lds_dwordx4 v[214:215], off
	v_lshl_add_u64 v[216:217], s[18:19], 0, v[132:133]
	s_mov_b32 m0, s77
	v_lshl_add_u64 v[218:219], s[18:19], 0, v[136:137]
	global_load_lds_dwordx4 v[216:217], off
	s_add_i32 m0, s77, 0x2000
	v_lshl_add_u64 v[220:221], s[30:31], 0, v[130:131]
	global_load_lds_dwordx4 v[218:219], off
	s_mov_b32 m0, s53
	v_lshl_add_u64 v[222:223], s[30:31], 0, v[134:135]
	global_load_lds_dwordx4 v[220:221], off
	s_mov_b32 m0, s54
	s_nop 0
	global_load_lds_dwordx4 v[222:223], off
	s_waitcnt vmcnt(8)
	s_waitcnt lgkmcnt(0)
	s_setprio 1
	s_barrier
; #define PG8_STAGE(bufoff, gbase, voff) do { _Pragma("unroll") for (int _i = 0; _i < 2; ++_i) \
;         __builtin_amdgcn_global_load_lds((const unsigned*)((const char*)(gbase) + (voff)[_i]), (PG8_LAS unsigned*)(lds + (bufoff) + ldsw + _i * 8192), 16, 0, 0); } while (0)
; #define PG8_LDA(dst, b, h) do { _Pragma("unroll") for (int m = 0; m < 4; ++m) _Pragma("unroll") for (int k = 0; k < 2; ++k) dst[m][k] = *(const PG8_LAS bf16x8*)(lds + PG8_SA(b, h) + aoff + m * 2048 + k * 1024); } while (0)
; #define PG8_LDB(dst, b, h) do { _Pragma("unroll") for (int n = 0; n < 2; ++n) _Pragma("unroll") for (int k = 0; k < 2; ++k) dst[n][k] = *(const PG8_LAS bf16x8*)(lds + PG8_SB(b, h) + boff + n * 2048 + k * 1024); } while (0)
; #define PG8_MMA(ai, bj, At, Bt) do { __builtin_amdgcn_s_setprio(1); _Pragma("unroll") for (int m = 0; m < 4; ++m) _Pragma("unroll") for (int n = 0; n < 2; ++n) _Pragma("unroll") for (int k = 0; k < 2; ++k) \
;         acc[ai][bj][m][n] = __builtin_amdgcn_mfma_f32_16x16x32_bf16(Bt[n][k], At[m][k], acc[ai][bj][m][n], 0, 0, 0); __builtin_amdgcn_s_setprio(0); } while (0)
; #define PG8_WAIT_V(n) asm volatile("s_waitcnt vmcnt(" #n ")" ::: "memory")
; template <class Epi, class Sched, bool ALIGN_EPI = false, bool SP2 = false>
; __device__ __forceinline__ void gemm_phase(PG8_LAS unsigned char* lds, const Gemm g, const Sched& S, const Epi& E) {
;     ...
;             PG8_LDB(B0, 0, 0); PG8_LDB(B1, 0, 1); PG8_SCHED; PG8_LDA(At, 0, 0); PG8_STAGE(PG8_SA(1, 1), a1 + hstep, voffA);
;             PG8_WAIT_V(8); PG8_WAIT_L(0); PG8_BAR; PG8_MMA(0, 0, At, B0); PG8_MMA(0, 1, At, B1); PG8_BAR; PG8_SCHED;
;             PG8_LDA(At, 0, 1); PG8_STAGE(PG8_SB(0, 0), b2, voffB); PG8_STAGE(PG8_SB(0, 1), b2 + hstep, voffB); PG8_STAGE(PG8_SA(0, 0), a2, voffA);
;             PG8_WAIT_V(8); PG8_WAIT_L(0); PG8_BAR; PG8_MMA(1, 0, At, B0); PG8_MMA(1, 1, At, B1); PG8_BAR; PG8_SCHED;
;             PG8_LDB(B0, 1, 0); PG8_LDB(B1, 1, 1); PG8_SCHED; PG8_LDA(At, 1, 0); PG8_STAGE(PG8_SA(0, 1), a2 + hstep, voffA);
;             PG8_WAIT_V(8); PG8_WAIT_L(0); PG8_BAR; PG8_MMA(0, 0, At, B0); PG8_MMA(0, 1, At, B1); PG8_BAR; PG8_SCHED;
;             PG8_LDA(At, 1, 1); PG8_STAGE(PG8_SB(1, 0), b3, voffB); PG8_STAGE(PG8_SB(1, 1), b3 + hstep, voffB); PG8_STAGE(PG8_SA(1, 0), a3, voffA);
;             PG8_WAIT_V(8); PG8_WAIT_L(0); PG8_BAR; PG8_MMA(1, 0, At, B0); PG8_MMA(1, 1, At, B1); PG8_BAR; PG8_SCHED;
	s_waitcnt lgkmcnt(0)
	v_mfma_f32_16x16x32_bf16 v[62:65], v[148:151], v[180:183], v[62:65]
	v_mfma_f32_16x16x32_bf16 v[58:61], v[156:159], v[180:183], v[58:61]
	v_mfma_f32_16x16x32_bf16 v[46:49], v[148:151], v[188:191], v[46:49]
	v_mfma_f32_16x16x32_bf16 v[42:45], v[156:159], v[188:191], v[42:45]
	v_mfma_f32_16x16x32_bf16 v[30:33], v[148:151], v[196:199], v[30:33]
	v_mfma_f32_16x16x32_bf16 v[26:29], v[156:159], v[196:199], v[26:29]
	v_mfma_f32_16x16x32_bf16 v[14:17], v[148:151], v[204:207], v[14:17]
	v_mfma_f32_16x16x32_bf16 v[10:13], v[156:159], v[204:207], v[10:13]
	v_mfma_f32_16x16x32_bf16 v[62:65], v[152:155], v[184:187], v[62:65]
	v_mfma_f32_16x16x32_bf16 v[58:61], v[160:163], v[184:187], v[58:61]
	v_mfma_f32_16x16x32_bf16 v[46:49], v[152:155], v[192:195], v[46:49]
	v_mfma_f32_16x16x32_bf16 v[42:45], v[160:163], v[192:195], v[42:45]
	v_mfma_f32_16x16x32_bf16 v[30:33], v[152:155], v[200:203], v[30:33]
	v_mfma_f32_16x16x32_bf16 v[26:29], v[160:163], v[200:203], v[26:29]
	v_mfma_f32_16x16x32_bf16 v[14:17], v[152:155], v[208:211], v[14:17]
	v_mfma_f32_16x16x32_bf16 v[10:13], v[160:163], v[208:211], v[10:13]
	s_setprio 0
	s_setprio 1
	v_mfma_f32_16x16x32_bf16 v[54:57], v[164:167], v[180:183], v[54:57]
	v_mfma_f32_16x16x32_bf16 v[50:53], v[172:175], v[180:183], v[50:53]
	v_mfma_f32_16x16x32_bf16 v[38:41], v[164:167], v[188:191], v[38:41]
	v_mfma_f32_16x16x32_bf16 v[34:37], v[172:175], v[188:191], v[34:37]
	v_mfma_f32_16x16x32_bf16 v[22:25], v[164:167], v[196:199], v[22:25]
	v_mfma_f32_16x16x32_bf16 v[18:21], v[172:175], v[196:199], v[18:21]
	v_mfma_f32_16x16x32_bf16 v[6:9], v[164:167], v[204:207], v[6:9]
	v_mfma_f32_16x16x32_bf16 v[2:5], v[172:175], v[204:207], v[2:5]
	v_mfma_f32_16x16x32_bf16 v[54:57], v[168:171], v[184:187], v[54:57]
	v_mfma_f32_16x16x32_bf16 v[50:53], v[176:179], v[184:187], v[50:53]
	v_mfma_f32_16x16x32_bf16 v[38:41], v[168:171], v[192:195], v[38:41]
	v_mfma_f32_16x16x32_bf16 v[34:37], v[176:179], v[192:195], v[34:37]
	v_mfma_f32_16x16x32_bf16 v[22:25], v[168:171], v[200:203], v[22:25]
	v_mfma_f32_16x16x32_bf16 v[18:21], v[176:179], v[200:203], v[18:21]
	s_setprio 3
	s_barrier
	v_mfma_f32_16x16x32_bf16 v[6:9], v[168:171], v[208:211], v[6:9]
	v_mfma_f32_16x16x32_bf16 v[2:5], v[176:179], v[208:211], v[2:5]
	s_setprio 0
	s_add_i32 s77, 0, 0x18000
	v_add_u32_e32 v147, s77, v143
	s_add_i32 s78, 0, 0x1c000
	ds_read_b128 v[148:151], v147
	ds_read_b128 v[152:155], v147 offset:1024
	ds_read_b128 v[156:159], v147 offset:2048
	ds_read_b128 v[160:163], v147 offset:3072
	v_add_u32_e32 v147, s78, v143
	ds_read_b128 v[164:167], v147
	ds_read_b128 v[168:171], v147 offset:1024
	ds_read_b128 v[172:175], v147 offset:2048
	ds_read_b128 v[176:179], v147 offset:3072
	s_add_u32 s18, s30, s4
	s_addc_u32 s19, s31, s5
	s_mov_b32 m0, s55
	v_lshl_add_u64 v[224:225], s[18:19], 0, v[130:131]
	ds_read_b128 v[180:183], v146 offset:32768
	ds_read_b128 v[184:187], v146 offset:33792
	ds_read_b128 v[188:191], v146 offset:34816
	ds_read_b128 v[192:195], v146 offset:35840
	ds_read_b128 v[196:199], v146 offset:36864
	ds_read_b128 v[200:203], v146 offset:37888
	ds_read_b128 v[204:207], v146 offset:38912
	ds_read_b128 v[208:211], v146 offset:39936
	global_load_lds_dwordx4 v[224:225], off
	v_lshl_add_u64 v[224:225], s[18:19], 0, v[134:135]
	s_mov_b32 m0, s56
	s_nop 0
	global_load_lds_dwordx4 v[224:225], off
	s_waitcnt vmcnt(8)
	s_waitcnt lgkmcnt(0)
	s_setprio 1
	s_barrier
	s_waitcnt lgkmcnt(0)
	v_mfma_f32_16x16x32_bf16 v[122:125], v[148:151], v[180:183], v[122:125]
	v_mfma_f32_16x16x32_bf16 v[126:129], v[156:159], v[180:183], v[126:129]
	v_mfma_f32_16x16x32_bf16 v[110:113], v[148:151], v[188:191], v[110:113]
	v_mfma_f32_16x16x32_bf16 v[106:109], v[156:159], v[188:191], v[106:109]
	v_mfma_f32_16x16x32_bf16 v[94:97], v[148:151], v[196:199], v[94:97]
	v_mfma_f32_16x16x32_bf16 v[90:93], v[156:159], v[196:199], v[90:93]
	v_mfma_f32_16x16x32_bf16 v[78:81], v[148:151], v[204:207], v[78:81]
	v_mfma_f32_16x16x32_bf16 v[74:77], v[156:159], v[204:207], v[74:77]
	v_mfma_f32_16x16x32_bf16 v[122:125], v[152:155], v[184:187], v[122:125]
	v_mfma_f32_16x16x32_bf16 v[126:129], v[160:163], v[184:187], v[126:129]
	v_mfma_f32_16x16x32_bf16 v[110:113], v[152:155], v[192:195], v[110:113]
	v_mfma_f32_16x16x32_bf16 v[106:109], v[160:163], v[192:195], v[106:109]
	v_mfma_f32_16x16x32_bf16 v[94:97], v[152:155], v[200:203], v[94:97]
	v_mfma_f32_16x16x32_bf16 v[90:93], v[160:163], v[200:203], v[90:93]
	v_mfma_f32_16x16x32_bf16 v[78:81], v[152:155], v[208:211], v[78:81]
	v_mfma_f32_16x16x32_bf16 v[74:77], v[160:163], v[208:211], v[74:77]
	s_setprio 0
	s_setprio 1
	v_mfma_f32_16x16x32_bf16 v[118:121], v[164:167], v[180:183], v[118:121]
	v_mfma_f32_16x16x32_bf16 v[114:117], v[172:175], v[180:183], v[114:117]
	v_mfma_f32_16x16x32_bf16 v[102:105], v[164:167], v[188:191], v[102:105]
	v_mfma_f32_16x16x32_bf16 v[98:101], v[172:175], v[188:191], v[98:101]
	v_mfma_f32_16x16x32_bf16 v[86:89], v[164:167], v[196:199], v[86:89]
	v_mfma_f32_16x16x32_bf16 v[82:85], v[172:175], v[196:199], v[82:85]
	v_mfma_f32_16x16x32_bf16 v[70:73], v[164:167], v[204:207], v[70:73]
	v_mfma_f32_16x16x32_bf16 v[66:69], v[172:175], v[204:207], v[66:69]
	v_mfma_f32_16x16x32_bf16 v[118:121], v[168:171], v[184:187], v[118:121]
	v_mfma_f32_16x16x32_bf16 v[114:117], v[176:179], v[184:187], v[114:117]
	v_mfma_f32_16x16x32_bf16 v[102:105], v[168:171], v[192:195], v[102:105]
	v_mfma_f32_16x16x32_bf16 v[98:101], v[176:179], v[192:195], v[98:101]
	v_mfma_f32_16x16x32_bf16 v[86:89], v[168:171], v[200:203], v[86:89]
	v_mfma_f32_16x16x32_bf16 v[82:85], v[176:179], v[200:203], v[82:85]
	s_setprio 3
	s_barrier
; #define PG8_STAGE(bufoff, gbase, voff) do { _Pragma("unroll") for (int _i = 0; _i < 2; ++_i) \
;         __builtin_amdgcn_global_load_lds((const unsigned*)((const char*)(gbase) + (voff)[_i]), (PG8_LAS unsigned*)(lds + (bufoff) + ldsw + _i * 8192), 16, 0, 0); } while (0)
; #define PG8_LDA(dst, b, h) do { _Pragma("unroll") for (int m = 0; m < 4; ++m) _Pragma("unroll") for (int k = 0; k < 2; ++k) dst[m][k] = *(const PG8_LAS bf16x8*)(lds + PG8_SA(b, h) + aoff + m * 2048 + k * 1024); } while (0)
; #define PG8_LDB(dst, b, h) do { _Pragma("unroll") for (int n = 0; n < 2; ++n) _Pragma("unroll") for (int k = 0; k < 2; ++k) dst[n][k] = *(const PG8_LAS bf16x8*)(lds + PG8_SB(b, h) + boff + n * 2048 + k * 1024); } while (0)
; #define PG8_MMA(ai, bj, At, Bt) do { __builtin_amdgcn_s_setprio(1); _Pragma("unroll") for (int m = 0; m < 4; ++m) _Pragma("unroll") for (int n = 0; n < 2; ++n) _Pragma("unroll") for (int k = 0; k < 2; ++k) \
;         acc[ai][bj][m][n] = __builtin_amdgcn_mfma_f32_16x16x32_bf16(Bt[n][k], At[m][k], acc[ai][bj][m][n], 0, 0, 0); __builtin_amdgcn_s_setprio(0); } while (0)
; #define PG8_WAIT_V(n) asm volatile("s_waitcnt vmcnt(" #n ")" ::: "memory")
; template <class Epi, class Sched, bool ALIGN_EPI = false, bool SP2 = false>
; __device__ __forceinline__ void gemm_phase(PG8_LAS unsigned char* lds, const Gemm g, const Sched& S, const Epi& E) {
;     ...
;             PG8_LDB(B0, 0, 0); PG8_LDB(B1, 0, 1); PG8_SCHED; PG8_LDA(At, 0, 0); PG8_STAGE(PG8_SA(1, 1), a1 + hstep, voffA);
;             PG8_WAIT_V(8); PG8_WAIT_L(0); PG8_BAR; PG8_MMA(0, 0, At, B0); PG8_MMA(0, 1, At, B1); PG8_BAR; PG8_SCHED;
;             PG8_LDA(At, 0, 1); PG8_STAGE(PG8_SB(0, 0), b2, voffB); PG8_STAGE(PG8_SB(0, 1), b2 + hstep, voffB); PG8_STAGE(PG8_SA(0, 0), a2, voffA);
;             PG8_WAIT_V(8); PG8_WAIT_L(0); PG8_BAR; PG8_MMA(1, 0, At, B0); PG8_MMA(1, 1, At, B1); PG8_BAR; PG8_SCHED;
;             PG8_LDB(B0, 1, 0); PG8_LDB(B1, 1, 1); PG8_SCHED; PG8_LDA(At, 1, 0); PG8_STAGE(PG8_SA(0, 1), a2 + hstep, voffA);
;             PG8_WAIT_V(8); PG8_WAIT_L(0); PG8_BAR; PG8_MMA(0, 0, At, B0); PG8_MMA(0, 1, At, B1); PG8_BAR; PG8_SCHED;
;             PG8_LDA(At, 1, 1); PG8_STAGE(PG8_SB(1, 0), b3, voffB); PG8_STAGE(PG8_SB(1, 1), b3 + hstep, voffB); PG8_STAGE(PG8_SA(1, 0), a3, voffA);
;             PG8_WAIT_V(8); PG8_WAIT_L(0); PG8_BAR; PG8_MMA(1, 0, At, B0); PG8_MMA(1, 1, At, B1); PG8_BAR; PG8_SCHED;
	v_mfma_f32_16x16x32_bf16 v[70:73], v[168:171], v[208:211], v[70:73]
	v_mfma_f32_16x16x32_bf16 v[66:69], v[176:179], v[208:211], v[66:69]
	s_setprio 0
	s_add_i32 s18, s77, s52
	v_lshl_add_u64 v[212:213], v[212:213], 0, s[14:15]
	s_mov_b32 m0, s18
	ds_read_b128 v[180:183], v146 offset:49152
	ds_read_b128 v[184:187], v146 offset:50176
	ds_read_b128 v[188:191], v146 offset:51200
	ds_read_b128 v[192:195], v146 offset:52224
	ds_read_b128 v[196:199], v146 offset:53248
	ds_read_b128 v[200:203], v146 offset:54272
	ds_read_b128 v[204:207], v146 offset:55296
	ds_read_b128 v[208:211], v146 offset:56320
	global_load_lds_dwordx4 v[212:213], off
	v_lshl_add_u64 v[212:213], v[214:215], 0, s[14:15]
	s_add_i32 m0, s18, 0x2000
	s_add_i32 s18, s78, s52
	global_load_lds_dwordx4 v[212:213], off
	v_lshl_add_u64 v[212:213], v[216:217], 0, s[14:15]
	s_mov_b32 m0, s18
	s_nop 0
	global_load_lds_dwordx4 v[212:213], off
	v_lshl_add_u64 v[212:213], v[218:219], 0, s[14:15]
	s_add_i32 m0, s18, 0x2000
	s_nop 0
	global_load_lds_dwordx4 v[212:213], off
	v_lshl_add_u64 v[212:213], v[220:221], 0, s[14:15]
	s_mov_b32 m0, s58
	s_nop 0
	global_load_lds_dwordx4 v[212:213], off
	v_lshl_add_u64 v[212:213], v[222:223], 0, s[14:15]
	s_mov_b32 m0, s59
	s_nop 0
	global_load_lds_dwordx4 v[212:213], off
	s_waitcnt vmcnt(8)
	s_waitcnt lgkmcnt(0)
	s_setprio 1
	s_barrier
	s_waitcnt lgkmcnt(0)
	v_mfma_f32_16x16x32_bf16 v[62:65], v[148:151], v[180:183], v[62:65]
	v_mfma_f32_16x16x32_bf16 v[58:61], v[156:159], v[180:183], v[58:61]
	v_mfma_f32_16x16x32_bf16 v[46:49], v[148:151], v[188:191], v[46:49]
	v_mfma_f32_16x16x32_bf16 v[42:45], v[156:159], v[188:191], v[42:45]
	v_mfma_f32_16x16x32_bf16 v[30:33], v[148:151], v[196:199], v[30:33]
	v_mfma_f32_16x16x32_bf16 v[26:29], v[156:159], v[196:199], v[26:29]
	v_mfma_f32_16x16x32_bf16 v[14:17], v[148:151], v[204:207], v[14:17]
	v_mfma_f32_16x16x32_bf16 v[10:13], v[156:159], v[204:207], v[10:13]
	v_mfma_f32_16x16x32_bf16 v[62:65], v[152:155], v[184:187], v[62:65]
	v_mfma_f32_16x16x32_bf16 v[58:61], v[160:163], v[184:187], v[58:61]
	v_mfma_f32_16x16x32_bf16 v[46:49], v[152:155], v[192:195], v[46:49]
	v_mfma_f32_16x16x32_bf16 v[42:45], v[160:163], v[192:195], v[42:45]
	v_mfma_f32_16x16x32_bf16 v[30:33], v[152:155], v[200:203], v[30:33]
	v_mfma_f32_16x16x32_bf16 v[26:29], v[160:163], v[200:203], v[26:29]
	v_mfma_f32_16x16x32_bf16 v[14:17], v[152:155], v[208:211], v[14:17]
	v_mfma_f32_16x16x32_bf16 v[10:13], v[160:163], v[208:211], v[10:13]
	s_setprio 0
	s_setprio 1
	v_mfma_f32_16x16x32_bf16 v[54:57], v[164:167], v[180:183], v[54:57]
	v_mfma_f32_16x16x32_bf16 v[50:53], v[172:175], v[180:183], v[50:53]
	v_mfma_f32_16x16x32_bf16 v[38:41], v[164:167], v[188:191], v[38:41]
	v_mfma_f32_16x16x32_bf16 v[34:37], v[172:175], v[188:191], v[34:37]
	v_mfma_f32_16x16x32_bf16 v[22:25], v[164:167], v[196:199], v[22:25]
	v_mfma_f32_16x16x32_bf16 v[18:21], v[172:175], v[196:199], v[18:21]
	v_mfma_f32_16x16x32_bf16 v[6:9], v[164:167], v[204:207], v[6:9]
	v_mfma_f32_16x16x32_bf16 v[2:5], v[172:175], v[204:207], v[2:5]
	v_mfma_f32_16x16x32_bf16 v[54:57], v[168:171], v[184:187], v[54:57]
	v_mfma_f32_16x16x32_bf16 v[50:53], v[176:179], v[184:187], v[50:53]
	v_mfma_f32_16x16x32_bf16 v[38:41], v[168:171], v[192:195], v[38:41]
	v_mfma_f32_16x16x32_bf16 v[34:37], v[176:179], v[192:195], v[34:37]
	v_mfma_f32_16x16x32_bf16 v[22:25], v[168:171], v[200:203], v[22:25]
	v_mfma_f32_16x16x32_bf16 v[18:21], v[176:179], v[200:203], v[18:21]
	s_setprio 3
	s_barrier
	v_mfma_f32_16x16x32_bf16 v[6:9], v[168:171], v[208:211], v[6:9]
	v_mfma_f32_16x16x32_bf16 v[2:5], v[176:179], v[208:211], v[2:5]
	s_setprio 0
	s_add_u32 s46, s46, 0x100
	s_addc_u32 s47, s47, 0
	s_add_u32 s48, s48, 0x100
	s_addc_u32 s49, s49, 0
	s_cmp_ge_i32 s76, s60
	s_mov_b32 s30, s76
	s_cbranch_scc0 .LBB0_777

; #define PG8_STAGE(bufoff, gbase, voff) do { _Pragma("unroll") for (int _i = 0; _i < 2; ++_i) \
;         __builtin_amdgcn_global_load_lds((const unsigned*)((const char*)(gbase) + (voff)[_i]), (PG8_LAS unsigned*)(lds + (bufoff) + ldsw + _i * 8192), 16, 0, 0); } while (0)
; #define PG8_LDA(dst, b, h) do { _Pragma("unroll") for (int m = 0; m < 4; ++m) _Pragma("unroll") for (int k = 0; k < 2; ++k) dst[m][k] = *(const PG8_LAS bf16x8*)(lds + PG8_SA(b, h) + aoff + m * 2048 + k * 1024); } while (0)
; #define PG8_LDB(dst, b, h) do { _Pragma("unroll") for (int n = 0; n < 2; ++n) _Pragma("unroll") for (int k = 0; k < 2; ++k) dst[n][k] = *(const PG8_LAS bf16x8*)(lds + PG8_SB(b, h) + boff + n * 2048 + k * 1024); } while (0)
; #define PG8_MMA(ai, bj, At, Bt) do { __builtin_amdgcn_s_setprio(1); _Pragma("unroll") for (int m = 0; m < 4; ++m) _Pragma("unroll") for (int n = 0; n < 2; ++n) _Pragma("unroll") for (int k = 0; k < 2; ++k) \
;         acc[ai][bj][m][n] = __builtin_amdgcn_mfma_f32_16x16x32_bf16(Bt[n][k], At[m][k], acc[ai][bj][m][n], 0, 0, 0); __builtin_amdgcn_s_setprio(0); } while (0)
; #define PG8_WAIT_V(n) asm volatile("s_waitcnt vmcnt(" #n ")" ::: "memory")
; template <class Epi, class Sched, bool ALIGN_EPI = false, bool SP2 = false>
; __device__ __forceinline__ void gemm_phase(PG8_LAS unsigned char* lds, const Gemm g, const Sched& S, const Epi& E) {
;     ...
;             PG8_LDB(B0, 0, 0); PG8_LDB(B1, 0, 1); PG8_SCHED; PG8_LDA(At, 0, 0); PG8_STAGE(PG8_SA(1, 1), a1 + hstep, voffA);
;             PG8_WAIT_V(8); PG8_WAIT_L(0); PG8_BAR; PG8_MMA(0, 0, At, B0); PG8_MMA(0, 1, At, B1); PG8_BAR; PG8_SCHED;
;             PG8_LDA(At, 0, 1); PG8_STAGE(PG8_SB(0, 0), b2, voffB); PG8_STAGE(PG8_SB(0, 1), b2 + hstep, voffB); PG8_STAGE(PG8_SA(0, 0), a2, voffA);
;             PG8_WAIT_V(8); PG8_WAIT_L(0); PG8_BAR; PG8_MMA(1, 0, At, B0); PG8_MMA(1, 1, At, B1); PG8_BAR; PG8_SCHED;
;             PG8_LDB(B0, 1, 0); PG8_LDB(B1, 1, 1); PG8_SCHED; PG8_LDA(At, 1, 0); PG8_STAGE(PG8_SA(0, 1), a2 + hstep, voffA);
;             PG8_WAIT_V(8); PG8_WAIT_L(0); PG8_BAR; PG8_MMA(0, 0, At, B0); PG8_MMA(0, 1, At, B1); PG8_BAR; PG8_SCHED;
;             PG8_LDA(At, 1, 1); PG8_STAGE(PG8_SB(1, 0), b3, voffB); PG8_STAGE(PG8_SB(1, 1), b3 + hstep, voffB); PG8_STAGE(PG8_SA(1, 0), a3, voffA);
;             PG8_WAIT_V(8); PG8_WAIT_L(0); PG8_BAR; PG8_MMA(1, 0, At, B0); PG8_MMA(1, 1, At, B1); PG8_BAR; PG8_SCHED;
.LBB0_892:
	ds_read_b128 v[98:101], v239
	ds_read_b128 v[110:113], v239 offset:1024
	ds_read_b128 v[122:125], v239 offset:2048
	ds_read_b128 v[134:137], v239 offset:3072
	ds_read_b128 v[138:141], v240
	ds_read_b128 v[142:145], v240 offset:1024
	ds_read_b128 v[146:149], v240 offset:2048
	ds_read_b128 v[150:153], v240 offset:3072
	s_add_u32 s18, s34, 0xfff50080
	s_addc_u32 s19, s35, -1
	s_cmp_eq_u32 s60, 40
	s_cselect_b32 s39, s1, s19
	s_cselect_b32 s38, s0, s18
	s_cselect_b32 s37, s31, s59
	s_cselect_b32 s36, s30, s58
	v_lshl_add_u64 v[208:209], s[34:35], 0, v[198:199]
	s_add_i32 m0, s41, 0xc000
	ds_read_b128 v[162:165], v241
	ds_read_b128 v[166:169], v241 offset:1024
	ds_read_b128 v[170:173], v241 offset:2048
	ds_read_b128 v[174:177], v241 offset:3072
	ds_read_b128 v[178:181], v241 offset:4096
	ds_read_b128 v[182:185], v241 offset:5120
	ds_read_b128 v[186:189], v241 offset:6144
	ds_read_b128 v[204:207], v241 offset:7168
	global_load_lds_dwordx4 v[208:209], off
	v_lshl_add_u64 v[208:209], s[34:35], 0, v[200:201]
	s_add_i32 m0, s41, 0xe000
	s_nop 0
	global_load_lds_dwordx4 v[208:209], off
	s_waitcnt vmcnt(8)
	s_waitcnt lgkmcnt(0)
	s_setprio 1
	s_barrier
	s_waitcnt lgkmcnt(0)
	v_mfma_f32_16x16x32_bf16 v[158:161], v[98:101], v[162:165], v[158:161]
	v_mfma_f32_16x16x32_bf16 v[154:157], v[122:125], v[162:165], v[154:157]
	v_mfma_f32_16x16x32_bf16 v[118:121], v[98:101], v[170:173], v[118:121]
	v_mfma_f32_16x16x32_bf16 v[114:117], v[122:125], v[170:173], v[114:117]
	v_mfma_f32_16x16x32_bf16 v[94:97], v[98:101], v[178:181], v[94:97]
	v_mfma_f32_16x16x32_bf16 v[90:93], v[122:125], v[178:181], v[90:93]
	v_mfma_f32_16x16x32_bf16 v[78:81], v[98:101], v[186:189], v[78:81]
	v_mfma_f32_16x16x32_bf16 v[74:77], v[122:125], v[186:189], v[74:77]
	v_mfma_f32_16x16x32_bf16 v[158:161], v[110:113], v[166:169], v[158:161]
	v_mfma_f32_16x16x32_bf16 v[154:157], v[134:137], v[166:169], v[154:157]
	v_mfma_f32_16x16x32_bf16 v[118:121], v[110:113], v[174:177], v[118:121]
	v_mfma_f32_16x16x32_bf16 v[114:117], v[134:137], v[174:177], v[114:117]
	v_mfma_f32_16x16x32_bf16 v[94:97], v[110:113], v[182:185], v[94:97]
	v_mfma_f32_16x16x32_bf16 v[90:93], v[134:137], v[182:185], v[90:93]
	v_mfma_f32_16x16x32_bf16 v[78:81], v[110:113], v[204:207], v[78:81]
	v_mfma_f32_16x16x32_bf16 v[74:77], v[134:137], v[204:207], v[74:77]
	s_setprio 0
	s_setprio 1
	v_mfma_f32_16x16x32_bf16 v[130:133], v[138:141], v[162:165], v[130:133]
	v_mfma_f32_16x16x32_bf16 v[126:129], v[146:149], v[162:165], v[126:129]
	v_mfma_f32_16x16x32_bf16 v[106:109], v[138:141], v[170:173], v[106:109]
	v_mfma_f32_16x16x32_bf16 v[102:105], v[146:149], v[170:173], v[102:105]
	v_mfma_f32_16x16x32_bf16 v[86:89], v[138:141], v[178:181], v[86:89]
	v_mfma_f32_16x16x32_bf16 v[82:85], v[146:149], v[178:181], v[82:85]
	v_mfma_f32_16x16x32_bf16 v[70:73], v[138:141], v[186:189], v[70:73]
	v_mfma_f32_16x16x32_bf16 v[66:69], v[146:149], v[186:189], v[66:69]
	v_mfma_f32_16x16x32_bf16 v[130:133], v[142:145], v[166:169], v[130:133]
	v_mfma_f32_16x16x32_bf16 v[126:129], v[150:153], v[166:169], v[126:129]
	v_mfma_f32_16x16x32_bf16 v[106:109], v[142:145], v[174:177], v[106:109]
	v_mfma_f32_16x16x32_bf16 v[102:105], v[150:153], v[174:177], v[102:105]
	v_mfma_f32_16x16x32_bf16 v[86:89], v[142:145], v[182:185], v[86:89]
	v_mfma_f32_16x16x32_bf16 v[82:85], v[150:153], v[182:185], v[82:85]
	s_setprio 3
	s_barrier
	v_mfma_f32_16x16x32_bf16 v[70:73], v[142:145], v[204:207], v[70:73]
	v_mfma_f32_16x16x32_bf16 v[66:69], v[150:153], v[204:207], v[66:69]
	s_setprio 0
	s_add_i32 s18, s52, s40
	v_lshl_add_u64 v[208:209], s[36:37], 0, v[192:193]
	s_mov_b32 m0, s18
	ds_read_b128 v[162:165], v241 offset:16384
	ds_read_b128 v[166:169], v241 offset:17408
	ds_read_b128 v[170:173], v241 offset:18432
	ds_read_b128 v[174:177], v241 offset:19456
	ds_read_b128 v[178:181], v241 offset:20480
	ds_read_b128 v[182:185], v241 offset:21504
	ds_read_b128 v[186:189], v241 offset:22528
	ds_read_b128 v[204:207], v241 offset:23552
	global_load_lds_dwordx4 v[208:209], off
	s_add_i32 m0, s18, 0x2000
	s_add_u32 s18, s36, 0xb0000
	v_lshl_add_u64 v[210:211], s[36:37], 0, v[196:197]
	s_addc_u32 s19, s37, 0
	s_add_i32 s61, s53, s40
	global_load_lds_dwordx4 v[210:211], off
	v_lshl_add_u64 v[212:213], s[18:19], 0, v[192:193]
	s_mov_b32 m0, s61
	v_lshl_add_u64 v[214:215], s[38:39], 0, v[194:195]
	global_load_lds_dwordx4 v[212:213], off
	v_lshl_add_u64 v[212:213], s[18:19], 0, v[196:197]
	s_add_i32 m0, s61, 0x2000
	s_nop 0
	global_load_lds_dwordx4 v[212:213], off
	v_lshl_add_u64 v[212:213], s[38:39], 0, v[190:191]
	s_mov_b32 m0, s41
	s_nop 0
	global_load_lds_dwordx4 v[212:213], off
	s_mov_b32 m0, s42
	s_nop 0
	global_load_lds_dwordx4 v[214:215], off
	s_waitcnt vmcnt(8)
	s_waitcnt lgkmcnt(0)
	s_setprio 1
	s_barrier
; #define PG8_STAGE(bufoff, gbase, voff) do { _Pragma("unroll") for (int _i = 0; _i < 2; ++_i) \
;         __builtin_amdgcn_global_load_lds((const unsigned*)((const char*)(gbase) + (voff)[_i]), (PG8_LAS unsigned*)(lds + (bufoff) + ldsw + _i * 8192), 16, 0, 0); } while (0)
; #define PG8_LDA(dst, b, h) do { _Pragma("unroll") for (int m = 0; m < 4; ++m) _Pragma("unroll") for (int k = 0; k < 2; ++k) dst[m][k] = *(const PG8_LAS bf16x8*)(lds + PG8_SA(b, h) + aoff + m * 2048 + k * 1024); } while (0)
; #define PG8_LDB(dst, b, h) do { _Pragma("unroll") for (int n = 0; n < 2; ++n) _Pragma("unroll") for (int k = 0; k < 2; ++k) dst[n][k] = *(const PG8_LAS bf16x8*)(lds + PG8_SB(b, h) + boff + n * 2048 + k * 1024); } while (0)
; #define PG8_MMA(ai, bj, At, Bt) do { __builtin_amdgcn_s_setprio(1); _Pragma("unroll") for (int m = 0; m < 4; ++m) _Pragma("unroll") for (int n = 0; n < 2; ++n) _Pragma("unroll") for (int k = 0; k < 2; ++k) \
;         acc[ai][bj][m][n] = __builtin_amdgcn_mfma_f32_16x16x32_bf16(Bt[n][k], At[m][k], acc[ai][bj][m][n], 0, 0, 0); __builtin_amdgcn_s_setprio(0); } while (0)
; #define PG8_WAIT_V(n) asm volatile("s_waitcnt vmcnt(" #n ")" ::: "memory")
; template <class Epi, class Sched, bool ALIGN_EPI = false, bool SP2 = false>
; __device__ __forceinline__ void gemm_phase(PG8_LAS unsigned char* lds, const Gemm g, const Sched& S, const Epi& E) {
;     ...
;             PG8_LDB(B0, 0, 0); PG8_LDB(B1, 0, 1); PG8_SCHED; PG8_LDA(At, 0, 0); PG8_STAGE(PG8_SA(1, 1), a1 + hstep, voffA);
;             PG8_WAIT_V(8); PG8_WAIT_L(0); PG8_BAR; PG8_MMA(0, 0, At, B0); PG8_MMA(0, 1, At, B1); PG8_BAR; PG8_SCHED;
;             PG8_LDA(At, 0, 1); PG8_STAGE(PG8_SB(0, 0), b2, voffB); PG8_STAGE(PG8_SB(0, 1), b2 + hstep, voffB); PG8_STAGE(PG8_SA(0, 0), a2, voffA);
;             PG8_WAIT_V(8); PG8_WAIT_L(0); PG8_BAR; PG8_MMA(1, 0, At, B0); PG8_MMA(1, 1, At, B1); PG8_BAR; PG8_SCHED;
;             PG8_LDB(B0, 1, 0); PG8_LDB(B1, 1, 1); PG8_SCHED; PG8_LDA(At, 1, 0); PG8_STAGE(PG8_SA(0, 1), a2 + hstep, voffA);
;             PG8_WAIT_V(8); PG8_WAIT_L(0); PG8_BAR; PG8_MMA(0, 0, At, B0); PG8_MMA(0, 1, At, B1); PG8_BAR; PG8_SCHED;
;             PG8_LDA(At, 1, 1); PG8_STAGE(PG8_SB(1, 0), b3, voffB); PG8_STAGE(PG8_SB(1, 1), b3 + hstep, voffB); PG8_STAGE(PG8_SA(1, 0), a3, voffA);
;             PG8_WAIT_V(8); PG8_WAIT_L(0); PG8_BAR; PG8_MMA(1, 0, At, B0); PG8_MMA(1, 1, At, B1); PG8_BAR; PG8_SCHED;
	s_waitcnt lgkmcnt(0)
	v_mfma_f32_16x16x32_bf16 v[62:65], v[98:101], v[162:165], v[62:65]
	v_mfma_f32_16x16x32_bf16 v[58:61], v[122:125], v[162:165], v[58:61]
	v_mfma_f32_16x16x32_bf16 v[46:49], v[98:101], v[170:173], v[46:49]
	v_mfma_f32_16x16x32_bf16 v[42:45], v[122:125], v[170:173], v[42:45]
	v_mfma_f32_16x16x32_bf16 v[30:33], v[98:101], v[178:181], v[30:33]
	v_mfma_f32_16x16x32_bf16 v[26:29], v[122:125], v[178:181], v[26:29]
	v_mfma_f32_16x16x32_bf16 v[14:17], v[98:101], v[186:189], v[14:17]
	v_mfma_f32_16x16x32_bf16 v[10:13], v[122:125], v[186:189], v[10:13]
	v_mfma_f32_16x16x32_bf16 v[62:65], v[110:113], v[166:169], v[62:65]
	v_mfma_f32_16x16x32_bf16 v[58:61], v[134:137], v[166:169], v[58:61]
	v_mfma_f32_16x16x32_bf16 v[46:49], v[110:113], v[174:177], v[46:49]
	v_mfma_f32_16x16x32_bf16 v[42:45], v[134:137], v[174:177], v[42:45]
	v_mfma_f32_16x16x32_bf16 v[30:33], v[110:113], v[182:185], v[30:33]
	v_mfma_f32_16x16x32_bf16 v[26:29], v[134:137], v[182:185], v[26:29]
	v_mfma_f32_16x16x32_bf16 v[14:17], v[110:113], v[204:207], v[14:17]
	v_mfma_f32_16x16x32_bf16 v[10:13], v[134:137], v[204:207], v[10:13]
	s_setprio 0
	s_setprio 1
	v_mfma_f32_16x16x32_bf16 v[54:57], v[138:141], v[162:165], v[54:57]
	v_mfma_f32_16x16x32_bf16 v[50:53], v[146:149], v[162:165], v[50:53]
	v_mfma_f32_16x16x32_bf16 v[38:41], v[138:141], v[170:173], v[38:41]
	v_mfma_f32_16x16x32_bf16 v[34:37], v[146:149], v[170:173], v[34:37]
	v_mfma_f32_16x16x32_bf16 v[22:25], v[138:141], v[178:181], v[22:25]
	v_mfma_f32_16x16x32_bf16 v[18:21], v[146:149], v[178:181], v[18:21]
	v_mfma_f32_16x16x32_bf16 v[6:9], v[138:141], v[186:189], v[6:9]
	v_mfma_f32_16x16x32_bf16 v[2:5], v[146:149], v[186:189], v[2:5]
	v_mfma_f32_16x16x32_bf16 v[54:57], v[142:145], v[166:169], v[54:57]
	v_mfma_f32_16x16x32_bf16 v[50:53], v[150:153], v[166:169], v[50:53]
	v_mfma_f32_16x16x32_bf16 v[38:41], v[142:145], v[174:177], v[38:41]
	v_mfma_f32_16x16x32_bf16 v[34:37], v[150:153], v[174:177], v[34:37]
	v_mfma_f32_16x16x32_bf16 v[22:25], v[142:145], v[182:185], v[22:25]
	v_mfma_f32_16x16x32_bf16 v[18:21], v[150:153], v[182:185], v[18:21]
	s_setprio 3
	s_barrier
	v_mfma_f32_16x16x32_bf16 v[6:9], v[142:145], v[204:207], v[6:9]
	v_mfma_f32_16x16x32_bf16 v[2:5], v[150:153], v[204:207], v[2:5]
	s_setprio 0
	s_add_i32 s61, 0, 0x18000
	s_add_i32 s62, 0, 0x1c000
	v_add_u32_e32 v134, s61, v237
	v_add_u32_e32 v150, s62, v237
	ds_read_b128 v[98:101], v134
	ds_read_b128 v[110:113], v134 offset:1024
	ds_read_b128 v[122:125], v134 offset:2048
	ds_read_b128 v[134:137], v134 offset:3072
	ds_read_b128 v[138:141], v150
	ds_read_b128 v[142:145], v150 offset:1024
	ds_read_b128 v[146:149], v150 offset:2048
	ds_read_b128 v[150:153], v150 offset:3072
	s_add_u32 s18, s38, 0xb0000
	s_addc_u32 s19, s39, 0
	s_mov_b32 m0, s43
	v_lshl_add_u64 v[216:217], s[18:19], 0, v[190:191]
	ds_read_b128 v[162:165], v241 offset:32768
	ds_read_b128 v[166:169], v241 offset:33792
	ds_read_b128 v[170:173], v241 offset:34816
	ds_read_b128 v[174:177], v241 offset:35840
	ds_read_b128 v[178:181], v241 offset:36864
	ds_read_b128 v[182:185], v241 offset:37888
	ds_read_b128 v[186:189], v241 offset:38912
	ds_read_b128 v[204:207], v241 offset:39936
	global_load_lds_dwordx4 v[216:217], off
	v_lshl_add_u64 v[216:217], s[18:19], 0, v[194:195]
	s_mov_b32 m0, s44
	s_nop 0
	global_load_lds_dwordx4 v[216:217], off
	s_waitcnt vmcnt(8)
	s_waitcnt lgkmcnt(0)
	s_setprio 1
	s_barrier
	s_waitcnt lgkmcnt(0)
	v_mfma_f32_16x16x32_bf16 v[158:161], v[98:101], v[162:165], v[158:161]
	v_mfma_f32_16x16x32_bf16 v[154:157], v[122:125], v[162:165], v[154:157]
	v_mfma_f32_16x16x32_bf16 v[118:121], v[98:101], v[170:173], v[118:121]
	v_mfma_f32_16x16x32_bf16 v[114:117], v[122:125], v[170:173], v[114:117]
	v_mfma_f32_16x16x32_bf16 v[94:97], v[98:101], v[178:181], v[94:97]
	v_mfma_f32_16x16x32_bf16 v[90:93], v[122:125], v[178:181], v[90:93]
	v_mfma_f32_16x16x32_bf16 v[78:81], v[98:101], v[186:189], v[78:81]
	v_mfma_f32_16x16x32_bf16 v[74:77], v[122:125], v[186:189], v[74:77]
	v_mfma_f32_16x16x32_bf16 v[158:161], v[110:113], v[166:169], v[158:161]
	v_mfma_f32_16x16x32_bf16 v[154:157], v[134:137], v[166:169], v[154:157]
	v_mfma_f32_16x16x32_bf16 v[118:121], v[110:113], v[174:177], v[118:121]
	v_mfma_f32_16x16x32_bf16 v[114:117], v[134:137], v[174:177], v[114:117]
	v_mfma_f32_16x16x32_bf16 v[94:97], v[110:113], v[182:185], v[94:97]
	v_mfma_f32_16x16x32_bf16 v[90:93], v[134:137], v[182:185], v[90:93]
	v_mfma_f32_16x16x32_bf16 v[78:81], v[110:113], v[204:207], v[78:81]
	v_mfma_f32_16x16x32_bf16 v[74:77], v[134:137], v[204:207], v[74:77]
	s_setprio 0
	s_setprio 1
	v_mfma_f32_16x16x32_bf16 v[130:133], v[138:141], v[162:165], v[130:133]
	v_mfma_f32_16x16x32_bf16 v[126:129], v[146:149], v[162:165], v[126:129]
	v_mfma_f32_16x16x32_bf16 v[106:109], v[138:141], v[170:173], v[106:109]
	v_mfma_f32_16x16x32_bf16 v[102:105], v[146:149], v[170:173], v[102:105]
	v_mfma_f32_16x16x32_bf16 v[86:89], v[138:141], v[178:181], v[86:89]
	v_mfma_f32_16x16x32_bf16 v[82:85], v[146:149], v[178:181], v[82:85]
	v_mfma_f32_16x16x32_bf16 v[70:73], v[138:141], v[186:189], v[70:73]
	v_mfma_f32_16x16x32_bf16 v[66:69], v[146:149], v[186:189], v[66:69]
	v_mfma_f32_16x16x32_bf16 v[130:133], v[142:145], v[166:169], v[130:133]
	v_mfma_f32_16x16x32_bf16 v[126:129], v[150:153], v[166:169], v[126:129]
	v_mfma_f32_16x16x32_bf16 v[106:109], v[142:145], v[174:177], v[106:109]
	v_mfma_f32_16x16x32_bf16 v[102:105], v[150:153], v[174:177], v[102:105]
	v_mfma_f32_16x16x32_bf16 v[86:89], v[142:145], v[182:185], v[86:89]
	v_mfma_f32_16x16x32_bf16 v[82:85], v[150:153], v[182:185], v[82:85]
	s_setprio 3
	s_barrier
; #define PG8_STAGE(bufoff, gbase, voff) do { _Pragma("unroll") for (int _i = 0; _i < 2; ++_i) \
;         __builtin_amdgcn_global_load_lds((const unsigned*)((const char*)(gbase) + (voff)[_i]), (PG8_LAS unsigned*)(lds + (bufoff) + ldsw + _i * 8192), 16, 0, 0); } while (0)
; #define PG8_LDA(dst, b, h) do { _Pragma("unroll") for (int m = 0; m < 4; ++m) _Pragma("unroll") for (int k = 0; k < 2; ++k) dst[m][k] = *(const PG8_LAS bf16x8*)(lds + PG8_SA(b, h) + aoff + m * 2048 + k * 1024); } while (0)
; #define PG8_LDB(dst, b, h) do { _Pragma("unroll") for (int n = 0; n < 2; ++n) _Pragma("unroll") for (int k = 0; k < 2; ++k) dst[n][k] = *(const PG8_LAS bf16x8*)(lds + PG8_SB(b, h) + boff + n * 2048 + k * 1024); } while (0)
; #define PG8_WAIT_V(n) asm volatile("s_waitcnt vmcnt(" #n ")" ::: "memory")
;     __device__ __forceinline__ void operator()(const f32x4 (&acc)[2][2][4][2], const Unit& u, int wr, int wc, int fr, int fq) const {
;     ...
;             for (int m = 0; m < 4; ++m)
; #pragma unroll
;                 for (int bj = 0; bj < 2; ++bj) bva[ai][m][bj] = *(const u32x4*)(Xb + (size_t)(row0 + ai * HALF + m * 16) * DM + col0 + bj * HALF);
; template <class Epi, class Sched, bool ALIGN_EPI = false, bool SP2 = false>
; __device__ __forceinline__ void gemm_phase(PG8_LAS unsigned char* lds, const Gemm g, const Sched& S, const Epi& E) {
;     ...
;             PG8_LDB(B0, 0, 0); PG8_LDB(B1, 0, 1); PG8_SCHED; PG8_LDA(At, 0, 0); PG8_STAGE(PG8_SA(1, 1), a1 + hstep, voffA);
;             PG8_WAIT_V(8); PG8_WAIT_L(0); PG8_BAR; PG8_MMA(0, 0, At, B0); PG8_MMA(0, 1, At, B1); PG8_BAR; PG8_SCHED;
;             PG8_LDA(At, 0, 1); PG8_STAGE(PG8_SB(0, 0), b2, voffB); PG8_STAGE(PG8_SB(0, 1), b2 + hstep, voffB); PG8_STAGE(PG8_SA(0, 0), a2, voffA);
;             PG8_WAIT_V(8); PG8_WAIT_L(0); PG8_BAR; PG8_MMA(1, 0, At, B0); PG8_MMA(1, 1, At, B1); PG8_BAR; PG8_SCHED;
;             PG8_LDB(B0, 1, 0); PG8_LDB(B1, 1, 1); PG8_SCHED; PG8_LDA(At, 1, 0); PG8_STAGE(PG8_SA(0, 1), a2 + hstep, voffA);
;             PG8_WAIT_V(8); PG8_WAIT_L(0); PG8_BAR; PG8_MMA(0, 0, At, B0); PG8_MMA(0, 1, At, B1); PG8_BAR; PG8_SCHED;
;             PG8_LDA(At, 1, 1); PG8_STAGE(PG8_SB(1, 0), b3, voffB); PG8_STAGE(PG8_SB(1, 1), b3 + hstep, voffB); PG8_STAGE(PG8_SA(1, 0), a3, voffA);
;             PG8_WAIT_V(8); PG8_WAIT_L(0); PG8_BAR; PG8_MMA(1, 0, At, B0); PG8_MMA(1, 1, At, B1); PG8_BAR; PG8_SCHED;
	v_mfma_f32_16x16x32_bf16 v[70:73], v[142:145], v[204:207], v[70:73]
	v_mfma_f32_16x16x32_bf16 v[66:69], v[150:153], v[204:207], v[66:69]
	s_setprio 0
	s_add_i32 s18, s61, s40
	v_lshl_add_u64 v[208:209], v[208:209], 0, s[16:17]
	s_mov_b32 m0, s18
	ds_read_b128 v[162:165], v241 offset:49152
	ds_read_b128 v[166:169], v241 offset:50176
	ds_read_b128 v[170:173], v241 offset:51200
	ds_read_b128 v[174:177], v241 offset:52224
	ds_read_b128 v[178:181], v241 offset:53248
	ds_read_b128 v[182:185], v241 offset:54272
	ds_read_b128 v[186:189], v241 offset:55296
	ds_read_b128 v[204:207], v241 offset:56320
	global_load_lds_dwordx4 v[208:209], off
	s_add_i32 m0, s18, 0x2000
	s_add_u32 s18, s36, 0xb0080
	v_lshl_add_u64 v[208:209], v[210:211], 0, s[16:17]
	s_addc_u32 s19, s37, 0
	s_add_i32 s36, s62, s40
	global_load_lds_dwordx4 v[208:209], off
	v_lshl_add_u64 v[208:209], s[18:19], 0, v[192:193]
	s_mov_b32 m0, s36
	s_nop 0
	global_load_lds_dwordx4 v[208:209], off
	v_lshl_add_u64 v[208:209], s[18:19], 0, v[196:197]
	s_add_i32 m0, s36, 0x2000
	s_nop 0
	global_load_lds_dwordx4 v[208:209], off
	v_lshl_add_u64 v[208:209], v[212:213], 0, s[16:17]
	s_mov_b32 m0, s46
	s_nop 0
	global_load_lds_dwordx4 v[208:209], off
	v_lshl_add_u64 v[208:209], v[214:215], 0, s[16:17]
	s_mov_b32 m0, s47
	s_nop 0
	global_load_lds_dwordx4 v[208:209], off
	s_waitcnt vmcnt(8)
	s_waitcnt lgkmcnt(0)
	s_setprio 1
	s_barrier
	s_waitcnt lgkmcnt(0)
	v_mfma_f32_16x16x32_bf16 v[62:65], v[98:101], v[162:165], v[62:65]
	v_mfma_f32_16x16x32_bf16 v[58:61], v[122:125], v[162:165], v[58:61]
	v_mfma_f32_16x16x32_bf16 v[46:49], v[98:101], v[170:173], v[46:49]
	v_mfma_f32_16x16x32_bf16 v[42:45], v[122:125], v[170:173], v[42:45]
	v_mfma_f32_16x16x32_bf16 v[30:33], v[98:101], v[178:181], v[30:33]
	v_mfma_f32_16x16x32_bf16 v[26:29], v[122:125], v[178:181], v[26:29]
	v_mfma_f32_16x16x32_bf16 v[14:17], v[98:101], v[186:189], v[14:17]
	v_mfma_f32_16x16x32_bf16 v[10:13], v[122:125], v[186:189], v[10:13]
	v_mfma_f32_16x16x32_bf16 v[62:65], v[110:113], v[166:169], v[62:65]
	v_mfma_f32_16x16x32_bf16 v[58:61], v[134:137], v[166:169], v[58:61]
	v_mfma_f32_16x16x32_bf16 v[46:49], v[110:113], v[174:177], v[46:49]
	v_mfma_f32_16x16x32_bf16 v[42:45], v[134:137], v[174:177], v[42:45]
	v_mfma_f32_16x16x32_bf16 v[30:33], v[110:113], v[182:185], v[30:33]
	v_mfma_f32_16x16x32_bf16 v[26:29], v[134:137], v[182:185], v[26:29]
	v_mfma_f32_16x16x32_bf16 v[14:17], v[110:113], v[204:207], v[14:17]
	v_mfma_f32_16x16x32_bf16 v[10:13], v[134:137], v[204:207], v[10:13]
	s_setprio 0
	s_setprio 1
	v_mfma_f32_16x16x32_bf16 v[54:57], v[138:141], v[162:165], v[54:57]
	v_mfma_f32_16x16x32_bf16 v[50:53], v[146:149], v[162:165], v[50:53]
	v_mfma_f32_16x16x32_bf16 v[38:41], v[138:141], v[170:173], v[38:41]
	v_mfma_f32_16x16x32_bf16 v[34:37], v[146:149], v[170:173], v[34:37]
	v_mfma_f32_16x16x32_bf16 v[22:25], v[138:141], v[178:181], v[22:25]
	v_mfma_f32_16x16x32_bf16 v[18:21], v[146:149], v[178:181], v[18:21]
	v_mfma_f32_16x16x32_bf16 v[6:9], v[138:141], v[186:189], v[6:9]
	v_mfma_f32_16x16x32_bf16 v[2:5], v[146:149], v[186:189], v[2:5]
	v_mfma_f32_16x16x32_bf16 v[54:57], v[142:145], v[166:169], v[54:57]
	v_mfma_f32_16x16x32_bf16 v[50:53], v[150:153], v[166:169], v[50:53]
	v_mfma_f32_16x16x32_bf16 v[38:41], v[142:145], v[174:177], v[38:41]
	v_mfma_f32_16x16x32_bf16 v[34:37], v[150:153], v[174:177], v[34:37]
	v_mfma_f32_16x16x32_bf16 v[22:25], v[142:145], v[182:185], v[22:25]
	v_mfma_f32_16x16x32_bf16 v[18:21], v[150:153], v[182:185], v[18:21]
	s_setprio 3
	s_barrier
	v_mfma_f32_16x16x32_bf16 v[6:9], v[142:145], v[204:207], v[6:9]
	v_mfma_f32_16x16x32_bf16 v[2:5], v[150:153], v[204:207], v[2:5]
	s_setprio 0
	s_add_i32 s60, s60, 2
	s_add_u32 s34, s34, 0x100
	s_addc_u32 s35, s35, 0
	s_add_u32 s58, s58, 0x100
	s_addc_u32 s59, s59, 0
	s_cmp_gt_u32 s60, 41
	s_cbranch_scc1 .Lrp_gen_p5
	s_cmp_lg_u32 s60, 40
	s_cbranch_scc1 .LBB0_892
	s_cmpk_lg_i32 s33, 0x100
	s_cbranch_scc1 .LBB0_892
	ds_read_b128 v[98:101], v239
	ds_read_b128 v[110:113], v239 offset:1024
	ds_read_b128 v[122:125], v239 offset:2048
	ds_read_b128 v[134:137], v239 offset:3072
	ds_read_b128 v[138:141], v240
	ds_read_b128 v[142:145], v240 offset:1024
	ds_read_b128 v[146:149], v240 offset:2048
	ds_read_b128 v[150:153], v240 offset:3072
	s_add_u32 s18, s34, 0xfff50080
	s_addc_u32 s19, s35, -1
	s_cmp_eq_u32 s60, 40
	s_cselect_b32 s39, s1, s19
	s_cselect_b32 s38, s0, s18
	s_cselect_b32 s37, s31, s59
	s_cselect_b32 s36, s30, s58
	v_lshl_add_u64 v[208:209], s[34:35], 0, v[198:199]
	s_add_i32 m0, s41, 0xc000
	ds_read_b128 v[162:165], v241
	ds_read_b128 v[166:169], v241 offset:1024
	ds_read_b128 v[170:173], v241 offset:2048
	ds_read_b128 v[174:177], v241 offset:3072
	ds_read_b128 v[178:181], v241 offset:4096
	ds_read_b128 v[182:185], v241 offset:5120
	ds_read_b128 v[186:189], v241 offset:6144
	ds_read_b128 v[204:207], v241 offset:7168
	global_load_lds_dwordx4 v[208:209], off
	v_lshl_add_u64 v[208:209], s[34:35], 0, v[200:201]
	s_add_i32 m0, s41, 0xe000
	s_nop 0
	global_load_lds_dwordx4 v[208:209], off
	v_lshl_or_b32 v255, s12, 8, v238
	v_lshl_add_u32 v235, s57, 8, v1
	v_lshlrev_b32_e32 v255, 1, v255
	v_lshl_add_u32 v255, v235, 11, v255
	s_mov_b64 s[84:85], s[20:21]
	global_load_dwordx4 v[242:245], v255, s[84:85]
	global_load_dwordx4 v[208:211], v255, s[84:85] offset:256
	s_add_u32 s84, s20, 0x8000
	s_addc_u32 s85, s21, 0
	global_load_dwordx4 v[212:215], v255, s[84:85]
	global_load_dwordx4 v[216:219], v255, s[84:85] offset:256
	s_add_u32 s84, s20, 0x10000
	s_addc_u32 s85, s21, 0
	global_load_dwordx4 v[220:223], v255, s[84:85]
	global_load_dwordx4 v[224:227], v255, s[84:85] offset:256
	s_add_u32 s84, s20, 0x18000
	s_addc_u32 s85, s21, 0
	global_load_dwordx4 v[228:231], v255, s[84:85]
	global_load_dwordx4 v[232:235], v255, s[84:85] offset:256
	s_add_u32 s84, s20, 0x40000
	s_addc_u32 s85, s21, 0
	global_load_dwordx4 v[246:249], v255, s[84:85]
	global_load_dwordx4 v[250:253], v255, s[84:85] offset:256
	s_waitcnt vmcnt(18)
	s_waitcnt lgkmcnt(0)
	s_setprio 1
	s_barrier
; #define PG8_STAGE(bufoff, gbase, voff) do { _Pragma("unroll") for (int _i = 0; _i < 2; ++_i) \
;         __builtin_amdgcn_global_load_lds((const unsigned*)((const char*)(gbase) + (voff)[_i]), (PG8_LAS unsigned*)(lds + (bufoff) + ldsw + _i * 8192), 16, 0, 0); } while (0)
; #define PG8_LDA(dst, b, h) do { _Pragma("unroll") for (int m = 0; m < 4; ++m) _Pragma("unroll") for (int k = 0; k < 2; ++k) dst[m][k] = *(const PG8_LAS bf16x8*)(lds + PG8_SA(b, h) + aoff + m * 2048 + k * 1024); } while (0)
; #define PG8_LDB(dst, b, h) do { _Pragma("unroll") for (int n = 0; n < 2; ++n) _Pragma("unroll") for (int k = 0; k < 2; ++k) dst[n][k] = *(const PG8_LAS bf16x8*)(lds + PG8_SB(b, h) + boff + n * 2048 + k * 1024); } while (0)
; #define PG8_MMA(ai, bj, At, Bt) do { __builtin_amdgcn_s_setprio(1); _Pragma("unroll") for (int m = 0; m < 4; ++m) _Pragma("unroll") for (int n = 0; n < 2; ++n) _Pragma("unroll") for (int k = 0; k < 2; ++k) \
;         acc[ai][bj][m][n] = __builtin_amdgcn_mfma_f32_16x16x32_bf16(Bt[n][k], At[m][k], acc[ai][bj][m][n], 0, 0, 0); __builtin_amdgcn_s_setprio(0); } while (0)
; #define PG8_WAIT_V(n) asm volatile("s_waitcnt vmcnt(" #n ")" ::: "memory")
; template <class Epi, class Sched, bool ALIGN_EPI = false, bool SP2 = false>
; __device__ __forceinline__ void gemm_phase(PG8_LAS unsigned char* lds, const Gemm g, const Sched& S, const Epi& E) {
;     ...
;             PG8_LDB(B0, 0, 0); PG8_LDB(B1, 0, 1); PG8_SCHED; PG8_LDA(At, 0, 0); PG8_STAGE(PG8_SA(1, 1), a1 + hstep, voffA);
;             PG8_WAIT_V(8); PG8_WAIT_L(0); PG8_BAR; PG8_MMA(0, 0, At, B0); PG8_MMA(0, 1, At, B1); PG8_BAR; PG8_SCHED;
;             PG8_LDA(At, 0, 1); PG8_STAGE(PG8_SB(0, 0), b2, voffB); PG8_STAGE(PG8_SB(0, 1), b2 + hstep, voffB); PG8_STAGE(PG8_SA(0, 0), a2, voffA);
;             PG8_WAIT_V(8); PG8_WAIT_L(0); PG8_BAR; PG8_MMA(1, 0, At, B0); PG8_MMA(1, 1, At, B1); PG8_BAR; PG8_SCHED;
;             PG8_LDB(B0, 1, 0); PG8_LDB(B1, 1, 1); PG8_SCHED; PG8_LDA(At, 1, 0); PG8_STAGE(PG8_SA(0, 1), a2 + hstep, voffA);
;             PG8_WAIT_V(8); PG8_WAIT_L(0); PG8_BAR; PG8_MMA(0, 0, At, B0); PG8_MMA(0, 1, At, B1); PG8_BAR; PG8_SCHED;
;             PG8_LDA(At, 1, 1); PG8_STAGE(PG8_SB(1, 0), b3, voffB); PG8_STAGE(PG8_SB(1, 1), b3 + hstep, voffB); PG8_STAGE(PG8_SA(1, 0), a3, voffA);
;             PG8_WAIT_V(8); PG8_WAIT_L(0); PG8_BAR; PG8_MMA(1, 0, At, B0); PG8_MMA(1, 1, At, B1); PG8_BAR; PG8_SCHED;
	s_waitcnt lgkmcnt(0)
	v_mfma_f32_16x16x32_bf16 v[158:161], v[98:101], v[162:165], v[158:161]
	v_mfma_f32_16x16x32_bf16 v[154:157], v[122:125], v[162:165], v[154:157]
	v_mfma_f32_16x16x32_bf16 v[118:121], v[98:101], v[170:173], v[118:121]
	v_mfma_f32_16x16x32_bf16 v[114:117], v[122:125], v[170:173], v[114:117]
	v_mfma_f32_16x16x32_bf16 v[94:97], v[98:101], v[178:181], v[94:97]
	v_mfma_f32_16x16x32_bf16 v[90:93], v[122:125], v[178:181], v[90:93]
	v_mfma_f32_16x16x32_bf16 v[78:81], v[98:101], v[186:189], v[78:81]
	v_mfma_f32_16x16x32_bf16 v[74:77], v[122:125], v[186:189], v[74:77]
	v_mfma_f32_16x16x32_bf16 v[158:161], v[110:113], v[166:169], v[158:161]
	v_mfma_f32_16x16x32_bf16 v[154:157], v[134:137], v[166:169], v[154:157]
	v_mfma_f32_16x16x32_bf16 v[118:121], v[110:113], v[174:177], v[118:121]
	v_mfma_f32_16x16x32_bf16 v[114:117], v[134:137], v[174:177], v[114:117]
	v_mfma_f32_16x16x32_bf16 v[94:97], v[110:113], v[182:185], v[94:97]
	v_mfma_f32_16x16x32_bf16 v[90:93], v[134:137], v[182:185], v[90:93]
	v_mfma_f32_16x16x32_bf16 v[78:81], v[110:113], v[204:207], v[78:81]
	v_mfma_f32_16x16x32_bf16 v[74:77], v[134:137], v[204:207], v[74:77]
	s_setprio 0
	s_setprio 1
	v_mfma_f32_16x16x32_bf16 v[130:133], v[138:141], v[162:165], v[130:133]
	v_mfma_f32_16x16x32_bf16 v[126:129], v[146:149], v[162:165], v[126:129]
	v_mfma_f32_16x16x32_bf16 v[106:109], v[138:141], v[170:173], v[106:109]
	v_mfma_f32_16x16x32_bf16 v[102:105], v[146:149], v[170:173], v[102:105]
	v_mfma_f32_16x16x32_bf16 v[86:89], v[138:141], v[178:181], v[86:89]
	v_mfma_f32_16x16x32_bf16 v[82:85], v[146:149], v[178:181], v[82:85]
	v_mfma_f32_16x16x32_bf16 v[70:73], v[138:141], v[186:189], v[70:73]
	v_mfma_f32_16x16x32_bf16 v[66:69], v[146:149], v[186:189], v[66:69]
	v_mfma_f32_16x16x32_bf16 v[130:133], v[142:145], v[166:169], v[130:133]
	v_mfma_f32_16x16x32_bf16 v[126:129], v[150:153], v[166:169], v[126:129]
	v_mfma_f32_16x16x32_bf16 v[106:109], v[142:145], v[174:177], v[106:109]
	v_mfma_f32_16x16x32_bf16 v[102:105], v[150:153], v[174:177], v[102:105]
	v_mfma_f32_16x16x32_bf16 v[86:89], v[142:145], v[182:185], v[86:89]
	v_mfma_f32_16x16x32_bf16 v[82:85], v[150:153], v[182:185], v[82:85]
	s_setprio 3
	s_barrier
	v_mfma_f32_16x16x32_bf16 v[70:73], v[142:145], v[204:207], v[70:73]
	v_mfma_f32_16x16x32_bf16 v[66:69], v[150:153], v[204:207], v[66:69]
	s_setprio 0
	s_add_i32 s18, s52, s40
	s_mov_b32 m0, s18
	ds_read_b128 v[162:165], v241 offset:16384
	ds_read_b128 v[166:169], v241 offset:17408
	ds_read_b128 v[170:173], v241 offset:18432
	ds_read_b128 v[174:177], v241 offset:19456
	ds_read_b128 v[178:181], v241 offset:20480
	ds_read_b128 v[182:185], v241 offset:21504
	ds_read_b128 v[186:189], v241 offset:22528
	ds_read_b128 v[204:207], v241 offset:23552
	s_add_i32 m0, s18, 0x2000
	s_add_u32 s18, s36, 0xb0000
	s_addc_u32 s19, s37, 0
	s_add_i32 s61, s53, s40
	s_mov_b32 m0, s61
	s_add_i32 m0, s61, 0x2000
	s_nop 0
	s_mov_b32 m0, s41
	s_nop 0
	s_mov_b32 m0, s42
	s_nop 0
	s_waitcnt vmcnt(12)
	s_waitcnt lgkmcnt(0)
	s_setprio 1
	s_barrier
	s_waitcnt lgkmcnt(0)
	v_mfma_f32_16x16x32_bf16 v[62:65], v[98:101], v[162:165], v[62:65]
	v_mfma_f32_16x16x32_bf16 v[58:61], v[122:125], v[162:165], v[58:61]
	v_mfma_f32_16x16x32_bf16 v[46:49], v[98:101], v[170:173], v[46:49]
	v_mfma_f32_16x16x32_bf16 v[42:45], v[122:125], v[170:173], v[42:45]
	v_mfma_f32_16x16x32_bf16 v[30:33], v[98:101], v[178:181], v[30:33]
	v_mfma_f32_16x16x32_bf16 v[26:29], v[122:125], v[178:181], v[26:29]
	v_mfma_f32_16x16x32_bf16 v[14:17], v[98:101], v[186:189], v[14:17]
	v_mfma_f32_16x16x32_bf16 v[10:13], v[122:125], v[186:189], v[10:13]
	v_mfma_f32_16x16x32_bf16 v[62:65], v[110:113], v[166:169], v[62:65]
	v_mfma_f32_16x16x32_bf16 v[58:61], v[134:137], v[166:169], v[58:61]
	v_mfma_f32_16x16x32_bf16 v[46:49], v[110:113], v[174:177], v[46:49]
	v_mfma_f32_16x16x32_bf16 v[42:45], v[134:137], v[174:177], v[42:45]
	v_mfma_f32_16x16x32_bf16 v[30:33], v[110:113], v[182:185], v[30:33]
	v_mfma_f32_16x16x32_bf16 v[26:29], v[134:137], v[182:185], v[26:29]
	v_mfma_f32_16x16x32_bf16 v[14:17], v[110:113], v[204:207], v[14:17]
	v_mfma_f32_16x16x32_bf16 v[10:13], v[134:137], v[204:207], v[10:13]
	s_setprio 0
	s_setprio 1
	v_mfma_f32_16x16x32_bf16 v[54:57], v[138:141], v[162:165], v[54:57]
	v_mfma_f32_16x16x32_bf16 v[50:53], v[146:149], v[162:165], v[50:53]
	v_mfma_f32_16x16x32_bf16 v[38:41], v[138:141], v[170:173], v[38:41]
	v_mfma_f32_16x16x32_bf16 v[34:37], v[146:149], v[170:173], v[34:37]
	v_mfma_f32_16x16x32_bf16 v[22:25], v[138:141], v[178:181], v[22:25]
	v_mfma_f32_16x16x32_bf16 v[18:21], v[146:149], v[178:181], v[18:21]
	v_mfma_f32_16x16x32_bf16 v[6:9], v[138:141], v[186:189], v[6:9]
	v_mfma_f32_16x16x32_bf16 v[2:5], v[146:149], v[186:189], v[2:5]
	v_mfma_f32_16x16x32_bf16 v[54:57], v[142:145], v[166:169], v[54:57]
	v_mfma_f32_16x16x32_bf16 v[50:53], v[150:153], v[166:169], v[50:53]
	v_mfma_f32_16x16x32_bf16 v[38:41], v[142:145], v[174:177], v[38:41]
	v_mfma_f32_16x16x32_bf16 v[34:37], v[150:153], v[174:177], v[34:37]
	v_mfma_f32_16x16x32_bf16 v[22:25], v[142:145], v[182:185], v[22:25]
	v_mfma_f32_16x16x32_bf16 v[18:21], v[150:153], v[182:185], v[18:21]
	s_setprio 3
	s_barrier
; #define PG8_STAGE(bufoff, gbase, voff) do { _Pragma("unroll") for (int _i = 0; _i < 2; ++_i) \
;         __builtin_amdgcn_global_load_lds((const unsigned*)((const char*)(gbase) + (voff)[_i]), (PG8_LAS unsigned*)(lds + (bufoff) + ldsw + _i * 8192), 16, 0, 0); } while (0)
; #define PG8_LDA(dst, b, h) do { _Pragma("unroll") for (int m = 0; m < 4; ++m) _Pragma("unroll") for (int k = 0; k < 2; ++k) dst[m][k] = *(const PG8_LAS bf16x8*)(lds + PG8_SA(b, h) + aoff + m * 2048 + k * 1024); } while (0)
; #define PG8_LDB(dst, b, h) do { _Pragma("unroll") for (int n = 0; n < 2; ++n) _Pragma("unroll") for (int k = 0; k < 2; ++k) dst[n][k] = *(const PG8_LAS bf16x8*)(lds + PG8_SB(b, h) + boff + n * 2048 + k * 1024); } while (0)
; #define PG8_MMA(ai, bj, At, Bt) do { __builtin_amdgcn_s_setprio(1); _Pragma("unroll") for (int m = 0; m < 4; ++m) _Pragma("unroll") for (int n = 0; n < 2; ++n) _Pragma("unroll") for (int k = 0; k < 2; ++k) \
;         acc[ai][bj][m][n] = __builtin_amdgcn_mfma_f32_16x16x32_bf16(Bt[n][k], At[m][k], acc[ai][bj][m][n], 0, 0, 0); __builtin_amdgcn_s_setprio(0); } while (0)
; #define PG8_WAIT_V(n) asm volatile("s_waitcnt vmcnt(" #n ")" ::: "memory")
; template <class Epi, class Sched, bool ALIGN_EPI = false, bool SP2 = false>
; __device__ __forceinline__ void gemm_phase(PG8_LAS unsigned char* lds, const Gemm g, const Sched& S, const Epi& E) {
;     ...
;             PG8_LDB(B0, 0, 0); PG8_LDB(B1, 0, 1); PG8_SCHED; PG8_LDA(At, 0, 0); PG8_STAGE(PG8_SA(1, 1), a1 + hstep, voffA);
;             PG8_WAIT_V(8); PG8_WAIT_L(0); PG8_BAR; PG8_MMA(0, 0, At, B0); PG8_MMA(0, 1, At, B1); PG8_BAR; PG8_SCHED;
;             PG8_LDA(At, 0, 1); PG8_STAGE(PG8_SB(0, 0), b2, voffB); PG8_STAGE(PG8_SB(0, 1), b2 + hstep, voffB); PG8_STAGE(PG8_SA(0, 0), a2, voffA);
;             PG8_WAIT_V(8); PG8_WAIT_L(0); PG8_BAR; PG8_MMA(1, 0, At, B0); PG8_MMA(1, 1, At, B1); PG8_BAR; PG8_SCHED;
;             PG8_LDB(B0, 1, 0); PG8_LDB(B1, 1, 1); PG8_SCHED; PG8_LDA(At, 1, 0); PG8_STAGE(PG8_SA(0, 1), a2 + hstep, voffA);
;             PG8_WAIT_V(8); PG8_WAIT_L(0); PG8_BAR; PG8_MMA(0, 0, At, B0); PG8_MMA(0, 1, At, B1); PG8_BAR; PG8_SCHED;
;             PG8_LDA(At, 1, 1); PG8_STAGE(PG8_SB(1, 0), b3, voffB); PG8_STAGE(PG8_SB(1, 1), b3 + hstep, voffB); PG8_STAGE(PG8_SA(1, 0), a3, voffA);
;             PG8_WAIT_V(8); PG8_WAIT_L(0); PG8_BAR; PG8_MMA(1, 0, At, B0); PG8_MMA(1, 1, At, B1); PG8_BAR; PG8_SCHED;
	v_mfma_f32_16x16x32_bf16 v[6:9], v[142:145], v[204:207], v[6:9]
	v_mfma_f32_16x16x32_bf16 v[2:5], v[150:153], v[204:207], v[2:5]
	s_setprio 0
	s_add_i32 s61, 0, 0x18000
	s_add_i32 s62, 0, 0x1c000
	v_add_u32_e32 v134, s61, v237
	v_add_u32_e32 v150, s62, v237
	ds_read_b128 v[98:101], v134
	ds_read_b128 v[110:113], v134 offset:1024
	ds_read_b128 v[122:125], v134 offset:2048
	ds_read_b128 v[134:137], v134 offset:3072
	ds_read_b128 v[138:141], v150
	ds_read_b128 v[142:145], v150 offset:1024
	ds_read_b128 v[146:149], v150 offset:2048
	ds_read_b128 v[150:153], v150 offset:3072
	s_add_u32 s18, s38, 0xb0000
	s_addc_u32 s19, s39, 0
	s_mov_b32 m0, s43
	ds_read_b128 v[162:165], v241 offset:32768
	ds_read_b128 v[166:169], v241 offset:33792
	ds_read_b128 v[170:173], v241 offset:34816
	ds_read_b128 v[174:177], v241 offset:35840
	ds_read_b128 v[178:181], v241 offset:36864
	ds_read_b128 v[182:185], v241 offset:37888
	ds_read_b128 v[186:189], v241 offset:38912
	ds_read_b128 v[204:207], v241 offset:39936
	s_mov_b32 m0, s44
	s_nop 0
	s_waitcnt vmcnt(10)
	s_waitcnt lgkmcnt(0)
	s_setprio 1
	s_barrier
	s_waitcnt lgkmcnt(0)
	v_mfma_f32_16x16x32_bf16 v[158:161], v[98:101], v[162:165], v[158:161]
	v_mfma_f32_16x16x32_bf16 v[154:157], v[122:125], v[162:165], v[154:157]
	v_mfma_f32_16x16x32_bf16 v[118:121], v[98:101], v[170:173], v[118:121]
	v_mfma_f32_16x16x32_bf16 v[114:117], v[122:125], v[170:173], v[114:117]
	v_mfma_f32_16x16x32_bf16 v[94:97], v[98:101], v[178:181], v[94:97]
	v_mfma_f32_16x16x32_bf16 v[90:93], v[122:125], v[178:181], v[90:93]
	v_mfma_f32_16x16x32_bf16 v[78:81], v[98:101], v[186:189], v[78:81]
	v_mfma_f32_16x16x32_bf16 v[74:77], v[122:125], v[186:189], v[74:77]
	v_mfma_f32_16x16x32_bf16 v[158:161], v[110:113], v[166:169], v[158:161]
	v_mfma_f32_16x16x32_bf16 v[154:157], v[134:137], v[166:169], v[154:157]
	v_mfma_f32_16x16x32_bf16 v[118:121], v[110:113], v[174:177], v[118:121]
	v_mfma_f32_16x16x32_bf16 v[114:117], v[134:137], v[174:177], v[114:117]
	v_mfma_f32_16x16x32_bf16 v[94:97], v[110:113], v[182:185], v[94:97]
	v_mfma_f32_16x16x32_bf16 v[90:93], v[134:137], v[182:185], v[90:93]
	v_mfma_f32_16x16x32_bf16 v[78:81], v[110:113], v[204:207], v[78:81]
	v_mfma_f32_16x16x32_bf16 v[74:77], v[134:137], v[204:207], v[74:77]
	s_setprio 0
	s_setprio 1
	v_mfma_f32_16x16x32_bf16 v[130:133], v[138:141], v[162:165], v[130:133]
	v_mfma_f32_16x16x32_bf16 v[126:129], v[146:149], v[162:165], v[126:129]
	v_mfma_f32_16x16x32_bf16 v[106:109], v[138:141], v[170:173], v[106:109]
	v_mfma_f32_16x16x32_bf16 v[102:105], v[146:149], v[170:173], v[102:105]
	v_mfma_f32_16x16x32_bf16 v[86:89], v[138:141], v[178:181], v[86:89]
	v_mfma_f32_16x16x32_bf16 v[82:85], v[146:149], v[178:181], v[82:85]
	v_mfma_f32_16x16x32_bf16 v[70:73], v[138:141], v[186:189], v[70:73]
	v_mfma_f32_16x16x32_bf16 v[66:69], v[146:149], v[186:189], v[66:69]
	v_mfma_f32_16x16x32_bf16 v[130:133], v[142:145], v[166:169], v[130:133]
	v_mfma_f32_16x16x32_bf16 v[126:129], v[150:153], v[166:169], v[126:129]
	v_mfma_f32_16x16x32_bf16 v[106:109], v[142:145], v[174:177], v[106:109]
	v_mfma_f32_16x16x32_bf16 v[102:105], v[150:153], v[174:177], v[102:105]
	v_mfma_f32_16x16x32_bf16 v[86:89], v[142:145], v[182:185], v[86:89]
	v_mfma_f32_16x16x32_bf16 v[82:85], v[150:153], v[182:185], v[82:85]
	s_setprio 3
	s_barrier
	v_mfma_f32_16x16x32_bf16 v[70:73], v[142:145], v[204:207], v[70:73]
	v_mfma_f32_16x16x32_bf16 v[66:69], v[150:153], v[204:207], v[66:69]
	s_setprio 0
	s_add_i32 s18, s61, s40
	s_mov_b32 m0, s18
	ds_read_b128 v[162:165], v241 offset:49152
	ds_read_b128 v[166:169], v241 offset:50176
	ds_read_b128 v[170:173], v241 offset:51200
	ds_read_b128 v[174:177], v241 offset:52224
	ds_read_b128 v[178:181], v241 offset:53248
	ds_read_b128 v[182:185], v241 offset:54272
	ds_read_b128 v[186:189], v241 offset:55296
	ds_read_b128 v[204:207], v241 offset:56320
	s_add_i32 m0, s18, 0x2000
	s_add_u32 s18, s36, 0xb0080
	s_addc_u32 s19, s37, 0
	s_add_i32 s36, s62, s40
	s_mov_b32 m0, s36
	s_nop 0
	s_add_i32 m0, s36, 0x2000
	s_nop 0
	s_mov_b32 m0, s46
	s_nop 0
	s_mov_b32 m0, s47
	s_nop 0
	s_waitcnt vmcnt(10)
	s_waitcnt lgkmcnt(0)
	s_setprio 1
	s_barrier
	s_waitcnt lgkmcnt(0)
	v_mfma_f32_16x16x32_bf16 v[62:65], v[98:101], v[162:165], v[62:65]
	v_mfma_f32_16x16x32_bf16 v[58:61], v[122:125], v[162:165], v[58:61]
	v_mfma_f32_16x16x32_bf16 v[46:49], v[98:101], v[170:173], v[46:49]
	v_mfma_f32_16x16x32_bf16 v[42:45], v[122:125], v[170:173], v[42:45]
	v_mfma_f32_16x16x32_bf16 v[30:33], v[98:101], v[178:181], v[30:33]
	v_mfma_f32_16x16x32_bf16 v[26:29], v[122:125], v[178:181], v[26:29]
	v_mfma_f32_16x16x32_bf16 v[14:17], v[98:101], v[186:189], v[14:17]
	v_mfma_f32_16x16x32_bf16 v[10:13], v[122:125], v[186:189], v[10:13]
	v_mfma_f32_16x16x32_bf16 v[62:65], v[110:113], v[166:169], v[62:65]
	v_mfma_f32_16x16x32_bf16 v[58:61], v[134:137], v[166:169], v[58:61]
	v_mfma_f32_16x16x32_bf16 v[46:49], v[110:113], v[174:177], v[46:49]
	v_mfma_f32_16x16x32_bf16 v[42:45], v[134:137], v[174:177], v[42:45]
	v_mfma_f32_16x16x32_bf16 v[30:33], v[110:113], v[182:185], v[30:33]
	v_mfma_f32_16x16x32_bf16 v[26:29], v[134:137], v[182:185], v[26:29]
	v_mfma_f32_16x16x32_bf16 v[14:17], v[110:113], v[204:207], v[14:17]
	v_mfma_f32_16x16x32_bf16 v[10:13], v[134:137], v[204:207], v[10:13]
	s_setprio 0
	s_setprio 1
	v_mfma_f32_16x16x32_bf16 v[54:57], v[138:141], v[162:165], v[54:57]
	v_mfma_f32_16x16x32_bf16 v[50:53], v[146:149], v[162:165], v[50:53]
	v_mfma_f32_16x16x32_bf16 v[38:41], v[138:141], v[170:173], v[38:41]
	v_mfma_f32_16x16x32_bf16 v[34:37], v[146:149], v[170:173], v[34:37]
	v_mfma_f32_16x16x32_bf16 v[22:25], v[138:141], v[178:181], v[22:25]
	v_mfma_f32_16x16x32_bf16 v[18:21], v[146:149], v[178:181], v[18:21]
	v_mfma_f32_16x16x32_bf16 v[6:9], v[138:141], v[186:189], v[6:9]
	v_mfma_f32_16x16x32_bf16 v[2:5], v[146:149], v[186:189], v[2:5]
	v_mfma_f32_16x16x32_bf16 v[54:57], v[142:145], v[166:169], v[54:57]
	v_mfma_f32_16x16x32_bf16 v[50:53], v[150:153], v[166:169], v[50:53]
	v_mfma_f32_16x16x32_bf16 v[38:41], v[142:145], v[174:177], v[38:41]
	v_mfma_f32_16x16x32_bf16 v[34:37], v[150:153], v[174:177], v[34:37]
	v_mfma_f32_16x16x32_bf16 v[22:25], v[142:145], v[182:185], v[22:25]
	v_mfma_f32_16x16x32_bf16 v[18:21], v[150:153], v[182:185], v[18:21]
	s_setprio 3
	s_barrier
	v_mfma_f32_16x16x32_bf16 v[6:9], v[142:145], v[204:207], v[6:9]
	v_mfma_f32_16x16x32_bf16 v[2:5], v[150:153], v[204:207], v[2:5]
	s_setprio 0
	s_add_i32 s60, s60, 2
	s_add_u32 s34, s34, 0x100
	s_addc_u32 s35, s35, 0
	s_add_u32 s58, s58, 0x100
	s_addc_u32 s59, s59, 0
	s_branch .Lrp_done_p5

; #define PG8_STAGE(bufoff, gbase, voff) do { _Pragma("unroll") for (int _i = 0; _i < 2; ++_i) \
;         __builtin_amdgcn_global_load_lds((const unsigned*)((const char*)(gbase) + (voff)[_i]), (PG8_LAS unsigned*)(lds + (bufoff) + ldsw + _i * 8192), 16, 0, 0); } while (0)
; #define PG8_LDA(dst, b, h) do { _Pragma("unroll") for (int m = 0; m < 4; ++m) _Pragma("unroll") for (int k = 0; k < 2; ++k) dst[m][k] = *(const PG8_LAS bf16x8*)(lds + PG8_SA(b, h) + aoff + m * 2048 + k * 1024); } while (0)
; #define PG8_LDB(dst, b, h) do { _Pragma("unroll") for (int n = 0; n < 2; ++n) _Pragma("unroll") for (int k = 0; k < 2; ++k) dst[n][k] = *(const PG8_LAS bf16x8*)(lds + PG8_SB(b, h) + boff + n * 2048 + k * 1024); } while (0)
; #define PG8_MMA(ai, bj, At, Bt) do { __builtin_amdgcn_s_setprio(1); _Pragma("unroll") for (int m = 0; m < 4; ++m) _Pragma("unroll") for (int n = 0; n < 2; ++n) _Pragma("unroll") for (int k = 0; k < 2; ++k) \
;         acc[ai][bj][m][n] = __builtin_amdgcn_mfma_f32_16x16x32_bf16(Bt[n][k], At[m][k], acc[ai][bj][m][n], 0, 0, 0); __builtin_amdgcn_s_setprio(0); } while (0)
; #define PG8_WAIT_V(n) asm volatile("s_waitcnt vmcnt(" #n ")" ::: "memory")
; template <class Epi, class Sched, bool ALIGN_EPI = false, bool SP2 = false>
; __device__ __forceinline__ void gemm_phase(PG8_LAS unsigned char* lds, const Gemm g, const Sched& S, const Epi& E) {
;     ...
;             PG8_LDB(B0, 0, 0); PG8_LDB(B1, 0, 1); PG8_SCHED; PG8_LDA(At, 0, 0); PG8_STAGE(PG8_SA(1, 1), a1 + hstep, voffA);
;             PG8_WAIT_V(8); PG8_WAIT_L(0); PG8_BAR; PG8_MMA(0, 0, At, B0); PG8_MMA(0, 1, At, B1); PG8_BAR; PG8_SCHED;
;             PG8_LDA(At, 0, 1); PG8_STAGE(PG8_SB(0, 0), b2, voffB); PG8_STAGE(PG8_SB(0, 1), b2 + hstep, voffB); PG8_STAGE(PG8_SA(0, 0), a2, voffA);
;             PG8_WAIT_V(8); PG8_WAIT_L(0); PG8_BAR; PG8_MMA(1, 0, At, B0); PG8_MMA(1, 1, At, B1); PG8_BAR; PG8_SCHED;
;             PG8_LDB(B0, 1, 0); PG8_LDB(B1, 1, 1); PG8_SCHED; PG8_LDA(At, 1, 0); PG8_STAGE(PG8_SA(0, 1), a2 + hstep, voffA);
;             PG8_WAIT_V(8); PG8_WAIT_L(0); PG8_BAR; PG8_MMA(0, 0, At, B0); PG8_MMA(0, 1, At, B1); PG8_BAR; PG8_SCHED;
;             PG8_LDA(At, 1, 1); PG8_STAGE(PG8_SB(1, 0), b3, voffB); PG8_STAGE(PG8_SB(1, 1), b3 + hstep, voffB); PG8_STAGE(PG8_SA(1, 0), a3, voffA);
;             PG8_WAIT_V(8); PG8_WAIT_L(0); PG8_BAR; PG8_MMA(1, 0, At, B0); PG8_MMA(1, 1, At, B1); PG8_BAR; PG8_SCHED;
.LBB0_1033:
	ds_read_b128 v[128:131], v202
	ds_read_b128 v[132:135], v202 offset:1024
	ds_read_b128 v[136:139], v202 offset:2048
	ds_read_b128 v[140:143], v202 offset:3072
	ds_read_b128 v[144:147], v203
	ds_read_b128 v[148:151], v203 offset:1024
	ds_read_b128 v[152:155], v203 offset:2048
	ds_read_b128 v[156:159], v203 offset:3072
	s_add_u32 s6, s4, 0xfffc0080
	s_addc_u32 s7, s5, -1
	s_cmp_eq_u32 s62, 12
	s_cselect_b32 s41, s3, s7
	s_cselect_b32 s40, s35, s6
	s_cselect_b32 s7, s31, s61
	s_cselect_b32 s6, s59, s60
	v_lshl_add_u64 v[218:219], s[4:5], 0, v[170:171]
	s_add_i32 m0, s44, 0xc000
	ds_read_b128 v[178:181], v204
	ds_read_b128 v[182:185], v204 offset:1024
	ds_read_b128 v[186:189], v204 offset:2048
	ds_read_b128 v[190:193], v204 offset:3072
	ds_read_b128 v[194:197], v204 offset:4096
	ds_read_b128 v[206:209], v204 offset:5120
	ds_read_b128 v[210:213], v204 offset:6144
	ds_read_b128 v[214:217], v204 offset:7168
	global_load_lds_dwordx4 v[218:219], off
	v_lshl_add_u64 v[218:219], s[4:5], 0, v[172:173]
	s_add_i32 m0, s44, 0xe000
	s_nop 0
	global_load_lds_dwordx4 v[218:219], off
	s_waitcnt vmcnt(8)
	s_waitcnt lgkmcnt(0)
	s_setprio 1
	s_barrier
	s_waitcnt lgkmcnt(0)
	v_mfma_f32_16x16x32_bf16 v[124:127], v[128:131], v[178:181], v[124:127]
	v_mfma_f32_16x16x32_bf16 v[120:123], v[136:139], v[178:181], v[120:123]
	v_mfma_f32_16x16x32_bf16 v[108:111], v[128:131], v[186:189], v[108:111]
	v_mfma_f32_16x16x32_bf16 v[104:107], v[136:139], v[186:189], v[104:107]
	v_mfma_f32_16x16x32_bf16 v[92:95], v[128:131], v[194:197], v[92:95]
	v_mfma_f32_16x16x32_bf16 v[88:91], v[136:139], v[194:197], v[88:91]
	v_mfma_f32_16x16x32_bf16 v[76:79], v[128:131], v[210:213], v[76:79]
	v_mfma_f32_16x16x32_bf16 v[72:75], v[136:139], v[210:213], v[72:75]
	v_mfma_f32_16x16x32_bf16 v[124:127], v[132:135], v[182:185], v[124:127]
	v_mfma_f32_16x16x32_bf16 v[120:123], v[140:143], v[182:185], v[120:123]
	v_mfma_f32_16x16x32_bf16 v[108:111], v[132:135], v[190:193], v[108:111]
	v_mfma_f32_16x16x32_bf16 v[104:107], v[140:143], v[190:193], v[104:107]
	v_mfma_f32_16x16x32_bf16 v[92:95], v[132:135], v[206:209], v[92:95]
	v_mfma_f32_16x16x32_bf16 v[88:91], v[140:143], v[206:209], v[88:91]
	v_mfma_f32_16x16x32_bf16 v[76:79], v[132:135], v[214:217], v[76:79]
	v_mfma_f32_16x16x32_bf16 v[72:75], v[140:143], v[214:217], v[72:75]
	s_setprio 0
	s_setprio 1
	v_mfma_f32_16x16x32_bf16 v[116:119], v[144:147], v[178:181], v[116:119]
	v_mfma_f32_16x16x32_bf16 v[112:115], v[152:155], v[178:181], v[112:115]
	v_mfma_f32_16x16x32_bf16 v[100:103], v[144:147], v[186:189], v[100:103]
	v_mfma_f32_16x16x32_bf16 v[96:99], v[152:155], v[186:189], v[96:99]
	v_mfma_f32_16x16x32_bf16 v[84:87], v[144:147], v[194:197], v[84:87]
	v_mfma_f32_16x16x32_bf16 v[80:83], v[152:155], v[194:197], v[80:83]
	v_mfma_f32_16x16x32_bf16 v[68:71], v[144:147], v[210:213], v[68:71]
	v_mfma_f32_16x16x32_bf16 v[64:67], v[152:155], v[210:213], v[64:67]
	v_mfma_f32_16x16x32_bf16 v[116:119], v[148:151], v[182:185], v[116:119]
	v_mfma_f32_16x16x32_bf16 v[112:115], v[156:159], v[182:185], v[112:115]
	v_mfma_f32_16x16x32_bf16 v[100:103], v[148:151], v[190:193], v[100:103]
	v_mfma_f32_16x16x32_bf16 v[96:99], v[156:159], v[190:193], v[96:99]
	v_mfma_f32_16x16x32_bf16 v[84:87], v[148:151], v[206:209], v[84:87]
	v_mfma_f32_16x16x32_bf16 v[80:83], v[156:159], v[206:209], v[80:83]
	s_setprio 3
	s_barrier
	v_mfma_f32_16x16x32_bf16 v[68:71], v[148:151], v[214:217], v[68:71]
	v_mfma_f32_16x16x32_bf16 v[64:67], v[156:159], v[214:217], v[64:67]
	s_setprio 0
	s_add_i32 s63, s55, s42
	v_lshl_add_u64 v[218:219], s[6:7], 0, v[162:163]
	s_mov_b32 m0, s63
	ds_read_b128 v[178:181], v204 offset:16384
	ds_read_b128 v[182:185], v204 offset:17408
	ds_read_b128 v[186:189], v204 offset:18432
	ds_read_b128 v[190:193], v204 offset:19456
	ds_read_b128 v[194:197], v204 offset:20480
	ds_read_b128 v[206:209], v204 offset:21504
	ds_read_b128 v[210:213], v204 offset:22528
	ds_read_b128 v[214:217], v204 offset:23552
	global_load_lds_dwordx4 v[218:219], off
	s_add_i32 m0, s63, 0x2000
	s_add_u32 s64, s6, 0x40000
	v_lshl_add_u64 v[220:221], s[6:7], 0, v[166:167]
	s_addc_u32 s65, s7, 0
	s_add_i32 s63, s56, s42
	global_load_lds_dwordx4 v[220:221], off
	v_lshl_add_u64 v[222:223], s[64:65], 0, v[162:163]
	s_mov_b32 m0, s63
	v_lshl_add_u64 v[224:225], s[40:41], 0, v[164:165]
	global_load_lds_dwordx4 v[222:223], off
	v_lshl_add_u64 v[222:223], s[64:65], 0, v[166:167]
	s_add_i32 m0, s63, 0x2000
	s_nop 0
	global_load_lds_dwordx4 v[222:223], off
	v_lshl_add_u64 v[222:223], s[40:41], 0, v[160:161]
	s_mov_b32 m0, s44
	s_nop 0
	global_load_lds_dwordx4 v[222:223], off
	s_mov_b32 m0, s45
	s_nop 0
	global_load_lds_dwordx4 v[224:225], off
	s_waitcnt vmcnt(8)
	s_waitcnt lgkmcnt(0)
	s_setprio 1
	s_barrier
; #define PG8_STAGE(bufoff, gbase, voff) do { _Pragma("unroll") for (int _i = 0; _i < 2; ++_i) \
;         __builtin_amdgcn_global_load_lds((const unsigned*)((const char*)(gbase) + (voff)[_i]), (PG8_LAS unsigned*)(lds + (bufoff) + ldsw + _i * 8192), 16, 0, 0); } while (0)
; #define PG8_LDA(dst, b, h) do { _Pragma("unroll") for (int m = 0; m < 4; ++m) _Pragma("unroll") for (int k = 0; k < 2; ++k) dst[m][k] = *(const PG8_LAS bf16x8*)(lds + PG8_SA(b, h) + aoff + m * 2048 + k * 1024); } while (0)
; #define PG8_LDB(dst, b, h) do { _Pragma("unroll") for (int n = 0; n < 2; ++n) _Pragma("unroll") for (int k = 0; k < 2; ++k) dst[n][k] = *(const PG8_LAS bf16x8*)(lds + PG8_SB(b, h) + boff + n * 2048 + k * 1024); } while (0)
; #define PG8_MMA(ai, bj, At, Bt) do { __builtin_amdgcn_s_setprio(1); _Pragma("unroll") for (int m = 0; m < 4; ++m) _Pragma("unroll") for (int n = 0; n < 2; ++n) _Pragma("unroll") for (int k = 0; k < 2; ++k) \
;         acc[ai][bj][m][n] = __builtin_amdgcn_mfma_f32_16x16x32_bf16(Bt[n][k], At[m][k], acc[ai][bj][m][n], 0, 0, 0); __builtin_amdgcn_s_setprio(0); } while (0)
; #define PG8_WAIT_V(n) asm volatile("s_waitcnt vmcnt(" #n ")" ::: "memory")
; template <class Epi, class Sched, bool ALIGN_EPI = false, bool SP2 = false>
; __device__ __forceinline__ void gemm_phase(PG8_LAS unsigned char* lds, const Gemm g, const Sched& S, const Epi& E) {
;     ...
;             PG8_LDB(B0, 0, 0); PG8_LDB(B1, 0, 1); PG8_SCHED; PG8_LDA(At, 0, 0); PG8_STAGE(PG8_SA(1, 1), a1 + hstep, voffA);
;             PG8_WAIT_V(8); PG8_WAIT_L(0); PG8_BAR; PG8_MMA(0, 0, At, B0); PG8_MMA(0, 1, At, B1); PG8_BAR; PG8_SCHED;
;             PG8_LDA(At, 0, 1); PG8_STAGE(PG8_SB(0, 0), b2, voffB); PG8_STAGE(PG8_SB(0, 1), b2 + hstep, voffB); PG8_STAGE(PG8_SA(0, 0), a2, voffA);
;             PG8_WAIT_V(8); PG8_WAIT_L(0); PG8_BAR; PG8_MMA(1, 0, At, B0); PG8_MMA(1, 1, At, B1); PG8_BAR; PG8_SCHED;
;             PG8_LDB(B0, 1, 0); PG8_LDB(B1, 1, 1); PG8_SCHED; PG8_LDA(At, 1, 0); PG8_STAGE(PG8_SA(0, 1), a2 + hstep, voffA);
;             PG8_WAIT_V(8); PG8_WAIT_L(0); PG8_BAR; PG8_MMA(0, 0, At, B0); PG8_MMA(0, 1, At, B1); PG8_BAR; PG8_SCHED;
;             PG8_LDA(At, 1, 1); PG8_STAGE(PG8_SB(1, 0), b3, voffB); PG8_STAGE(PG8_SB(1, 1), b3 + hstep, voffB); PG8_STAGE(PG8_SA(1, 0), a3, voffA);
;             PG8_WAIT_V(8); PG8_WAIT_L(0); PG8_BAR; PG8_MMA(1, 0, At, B0); PG8_MMA(1, 1, At, B1); PG8_BAR; PG8_SCHED;
	s_waitcnt lgkmcnt(0)
	v_mfma_f32_16x16x32_bf16 v[60:63], v[128:131], v[178:181], v[60:63]
	v_mfma_f32_16x16x32_bf16 v[56:59], v[136:139], v[178:181], v[56:59]
	v_mfma_f32_16x16x32_bf16 v[44:47], v[128:131], v[186:189], v[44:47]
	v_mfma_f32_16x16x32_bf16 v[40:43], v[136:139], v[186:189], v[40:43]
	v_mfma_f32_16x16x32_bf16 v[28:31], v[128:131], v[194:197], v[28:31]
	v_mfma_f32_16x16x32_bf16 v[24:27], v[136:139], v[194:197], v[24:27]
	v_mfma_f32_16x16x32_bf16 v[12:15], v[128:131], v[210:213], v[12:15]
	v_mfma_f32_16x16x32_bf16 v[8:11], v[136:139], v[210:213], v[8:11]
	v_mfma_f32_16x16x32_bf16 v[60:63], v[132:135], v[182:185], v[60:63]
	v_mfma_f32_16x16x32_bf16 v[56:59], v[140:143], v[182:185], v[56:59]
	v_mfma_f32_16x16x32_bf16 v[44:47], v[132:135], v[190:193], v[44:47]
	v_mfma_f32_16x16x32_bf16 v[40:43], v[140:143], v[190:193], v[40:43]
	v_mfma_f32_16x16x32_bf16 v[28:31], v[132:135], v[206:209], v[28:31]
	v_mfma_f32_16x16x32_bf16 v[24:27], v[140:143], v[206:209], v[24:27]
	v_mfma_f32_16x16x32_bf16 v[12:15], v[132:135], v[214:217], v[12:15]
	v_mfma_f32_16x16x32_bf16 v[8:11], v[140:143], v[214:217], v[8:11]
	s_setprio 0
	s_setprio 1
	v_mfma_f32_16x16x32_bf16 v[52:55], v[144:147], v[178:181], v[52:55]
	v_mfma_f32_16x16x32_bf16 v[48:51], v[152:155], v[178:181], v[48:51]
	v_mfma_f32_16x16x32_bf16 v[36:39], v[144:147], v[186:189], v[36:39]
	v_mfma_f32_16x16x32_bf16 v[32:35], v[152:155], v[186:189], v[32:35]
	v_mfma_f32_16x16x32_bf16 v[20:23], v[144:147], v[194:197], v[20:23]
	v_mfma_f32_16x16x32_bf16 v[16:19], v[152:155], v[194:197], v[16:19]
	v_mfma_f32_16x16x32_bf16 v[4:7], v[144:147], v[210:213], v[4:7]
	v_mfma_f32_16x16x32_bf16 v[0:3], v[152:155], v[210:213], v[0:3]
	v_mfma_f32_16x16x32_bf16 v[52:55], v[148:151], v[182:185], v[52:55]
	v_mfma_f32_16x16x32_bf16 v[48:51], v[156:159], v[182:185], v[48:51]
	v_mfma_f32_16x16x32_bf16 v[36:39], v[148:151], v[190:193], v[36:39]
	v_mfma_f32_16x16x32_bf16 v[32:35], v[156:159], v[190:193], v[32:35]
	v_mfma_f32_16x16x32_bf16 v[20:23], v[148:151], v[206:209], v[20:23]
	v_mfma_f32_16x16x32_bf16 v[16:19], v[156:159], v[206:209], v[16:19]
	s_setprio 3
	s_barrier
	v_mfma_f32_16x16x32_bf16 v[4:7], v[148:151], v[214:217], v[4:7]
	v_mfma_f32_16x16x32_bf16 v[0:3], v[156:159], v[214:217], v[0:3]
	s_setprio 0
	s_add_i32 s63, 0, 0x18000
	s_add_i32 s64, 0, 0x1c000
	v_add_u32_e32 v140, s63, v199
	v_add_u32_e32 v156, s64, v199
	ds_read_b128 v[128:131], v140
	ds_read_b128 v[132:135], v140 offset:1024
	ds_read_b128 v[136:139], v140 offset:2048
	ds_read_b128 v[140:143], v140 offset:3072
	ds_read_b128 v[144:147], v156
	ds_read_b128 v[148:151], v156 offset:1024
	ds_read_b128 v[152:155], v156 offset:2048
	ds_read_b128 v[156:159], v156 offset:3072
	s_add_u32 s40, s40, 0x40000
	s_addc_u32 s41, s41, 0
	s_mov_b32 m0, s46
	v_lshl_add_u64 v[226:227], s[40:41], 0, v[160:161]
	ds_read_b128 v[178:181], v204 offset:32768
	ds_read_b128 v[182:185], v204 offset:33792
	ds_read_b128 v[186:189], v204 offset:34816
	ds_read_b128 v[190:193], v204 offset:35840
	ds_read_b128 v[194:197], v204 offset:36864
	ds_read_b128 v[206:209], v204 offset:37888
	ds_read_b128 v[210:213], v204 offset:38912
	ds_read_b128 v[214:217], v204 offset:39936
	global_load_lds_dwordx4 v[226:227], off
	v_lshl_add_u64 v[226:227], s[40:41], 0, v[164:165]
	s_mov_b32 m0, s47
	s_nop 0
	global_load_lds_dwordx4 v[226:227], off
	s_waitcnt vmcnt(8)
	s_waitcnt lgkmcnt(0)
	s_setprio 1
	s_barrier
	s_waitcnt lgkmcnt(0)
	v_mfma_f32_16x16x32_bf16 v[124:127], v[128:131], v[178:181], v[124:127]
	v_mfma_f32_16x16x32_bf16 v[120:123], v[136:139], v[178:181], v[120:123]
	v_mfma_f32_16x16x32_bf16 v[108:111], v[128:131], v[186:189], v[108:111]
	v_mfma_f32_16x16x32_bf16 v[104:107], v[136:139], v[186:189], v[104:107]
	v_mfma_f32_16x16x32_bf16 v[92:95], v[128:131], v[194:197], v[92:95]
	v_mfma_f32_16x16x32_bf16 v[88:91], v[136:139], v[194:197], v[88:91]
	v_mfma_f32_16x16x32_bf16 v[76:79], v[128:131], v[210:213], v[76:79]
	v_mfma_f32_16x16x32_bf16 v[72:75], v[136:139], v[210:213], v[72:75]
	v_mfma_f32_16x16x32_bf16 v[124:127], v[132:135], v[182:185], v[124:127]
	v_mfma_f32_16x16x32_bf16 v[120:123], v[140:143], v[182:185], v[120:123]
	v_mfma_f32_16x16x32_bf16 v[108:111], v[132:135], v[190:193], v[108:111]
	v_mfma_f32_16x16x32_bf16 v[104:107], v[140:143], v[190:193], v[104:107]
	v_mfma_f32_16x16x32_bf16 v[92:95], v[132:135], v[206:209], v[92:95]
	v_mfma_f32_16x16x32_bf16 v[88:91], v[140:143], v[206:209], v[88:91]
	v_mfma_f32_16x16x32_bf16 v[76:79], v[132:135], v[214:217], v[76:79]
	v_mfma_f32_16x16x32_bf16 v[72:75], v[140:143], v[214:217], v[72:75]
	s_setprio 0
	s_setprio 1
	v_mfma_f32_16x16x32_bf16 v[116:119], v[144:147], v[178:181], v[116:119]
	v_mfma_f32_16x16x32_bf16 v[112:115], v[152:155], v[178:181], v[112:115]
	v_mfma_f32_16x16x32_bf16 v[100:103], v[144:147], v[186:189], v[100:103]
	v_mfma_f32_16x16x32_bf16 v[96:99], v[152:155], v[186:189], v[96:99]
	v_mfma_f32_16x16x32_bf16 v[84:87], v[144:147], v[194:197], v[84:87]
	v_mfma_f32_16x16x32_bf16 v[80:83], v[152:155], v[194:197], v[80:83]
	v_mfma_f32_16x16x32_bf16 v[68:71], v[144:147], v[210:213], v[68:71]
	v_mfma_f32_16x16x32_bf16 v[64:67], v[152:155], v[210:213], v[64:67]
	v_mfma_f32_16x16x32_bf16 v[116:119], v[148:151], v[182:185], v[116:119]
	v_mfma_f32_16x16x32_bf16 v[112:115], v[156:159], v[182:185], v[112:115]
	v_mfma_f32_16x16x32_bf16 v[100:103], v[148:151], v[190:193], v[100:103]
	v_mfma_f32_16x16x32_bf16 v[96:99], v[156:159], v[190:193], v[96:99]
	v_mfma_f32_16x16x32_bf16 v[84:87], v[148:151], v[206:209], v[84:87]
	v_mfma_f32_16x16x32_bf16 v[80:83], v[156:159], v[206:209], v[80:83]
	s_setprio 3
	s_barrier
; #define PG8_STAGE(bufoff, gbase, voff) do { _Pragma("unroll") for (int _i = 0; _i < 2; ++_i) \
;         __builtin_amdgcn_global_load_lds((const unsigned*)((const char*)(gbase) + (voff)[_i]), (PG8_LAS unsigned*)(lds + (bufoff) + ldsw + _i * 8192), 16, 0, 0); } while (0)
; #define PG8_LDA(dst, b, h) do { _Pragma("unroll") for (int m = 0; m < 4; ++m) _Pragma("unroll") for (int k = 0; k < 2; ++k) dst[m][k] = *(const PG8_LAS bf16x8*)(lds + PG8_SA(b, h) + aoff + m * 2048 + k * 1024); } while (0)
; #define PG8_LDB(dst, b, h) do { _Pragma("unroll") for (int n = 0; n < 2; ++n) _Pragma("unroll") for (int k = 0; k < 2; ++k) dst[n][k] = *(const PG8_LAS bf16x8*)(lds + PG8_SB(b, h) + boff + n * 2048 + k * 1024); } while (0)
; #define PG8_MMA(ai, bj, At, Bt) do { __builtin_amdgcn_s_setprio(1); _Pragma("unroll") for (int m = 0; m < 4; ++m) _Pragma("unroll") for (int n = 0; n < 2; ++n) _Pragma("unroll") for (int k = 0; k < 2; ++k) \
;         acc[ai][bj][m][n] = __builtin_amdgcn_mfma_f32_16x16x32_bf16(Bt[n][k], At[m][k], acc[ai][bj][m][n], 0, 0, 0); __builtin_amdgcn_s_setprio(0); } while (0)
; template <class Epi, class Sched, bool ALIGN_EPI = false, bool SP2 = false>
; __device__ __forceinline__ void gemm_phase(PG8_LAS unsigned char* lds, const Gemm g, const Sched& S, const Epi& E) {
;     ...
;             PG8_LDB(B0, 0, 0); PG8_LDB(B1, 0, 1); PG8_SCHED; PG8_LDA(At, 0, 0); PG8_STAGE(PG8_SA(1, 1), a1 + hstep, voffA);
;             PG8_WAIT_V(8); PG8_WAIT_L(0); PG8_BAR; PG8_MMA(0, 0, At, B0); PG8_MMA(0, 1, At, B1); PG8_BAR; PG8_SCHED;
;             PG8_LDA(At, 0, 1); PG8_STAGE(PG8_SB(0, 0), b2, voffB); PG8_STAGE(PG8_SB(0, 1), b2 + hstep, voffB); PG8_STAGE(PG8_SA(0, 0), a2, voffA);
;             PG8_WAIT_V(8); PG8_WAIT_L(0); PG8_BAR; PG8_MMA(1, 0, At, B0); PG8_MMA(1, 1, At, B1); PG8_BAR; PG8_SCHED;
;             PG8_LDB(B0, 1, 0); PG8_LDB(B1, 1, 1); PG8_SCHED; PG8_LDA(At, 1, 0); PG8_STAGE(PG8_SA(0, 1), a2 + hstep, voffA);
;             PG8_WAIT_V(8); PG8_WAIT_L(0); PG8_BAR; PG8_MMA(0, 0, At, B0); PG8_MMA(0, 1, At, B1); PG8_BAR; PG8_SCHED;
;             PG8_LDA(At, 1, 1); PG8_STAGE(PG8_SB(1, 0), b3, voffB); PG8_STAGE(PG8_SB(1, 1), b3 + hstep, voffB); PG8_STAGE(PG8_SA(1, 0), a3, voffA);
;             PG8_WAIT_V(8); PG8_WAIT_L(0); PG8_BAR; PG8_MMA(1, 0, At, B0); PG8_MMA(1, 1, At, B1); PG8_BAR; PG8_SCHED;
;     ...
;         if constexpr (ALIGN_EPI) { if (wr == 0) PG8_BAR; }
	v_mfma_f32_16x16x32_bf16 v[68:71], v[148:151], v[214:217], v[68:71]
	v_mfma_f32_16x16x32_bf16 v[64:67], v[156:159], v[214:217], v[64:67]
	s_setprio 0
	s_add_i32 s40, s63, s42
	v_lshl_add_u64 v[218:219], v[218:219], 0, s[12:13]
	s_mov_b32 m0, s40
	ds_read_b128 v[178:181], v204 offset:49152
	ds_read_b128 v[182:185], v204 offset:50176
	ds_read_b128 v[186:189], v204 offset:51200
	ds_read_b128 v[190:193], v204 offset:52224
	ds_read_b128 v[194:197], v204 offset:53248
	ds_read_b128 v[206:209], v204 offset:54272
	ds_read_b128 v[210:213], v204 offset:55296
	ds_read_b128 v[214:217], v204 offset:56320
	global_load_lds_dwordx4 v[218:219], off
	s_add_i32 m0, s40, 0x2000
	s_add_u32 s6, s6, 0x40080
	v_lshl_add_u64 v[218:219], v[220:221], 0, s[12:13]
	s_addc_u32 s7, s7, 0
	s_add_i32 s40, s64, s42
	global_load_lds_dwordx4 v[218:219], off
	v_lshl_add_u64 v[218:219], s[6:7], 0, v[162:163]
	s_mov_b32 m0, s40
	s_nop 0
	global_load_lds_dwordx4 v[218:219], off
	v_lshl_add_u64 v[218:219], s[6:7], 0, v[166:167]
	s_add_i32 m0, s40, 0x2000
	s_nop 0
	global_load_lds_dwordx4 v[218:219], off
	v_lshl_add_u64 v[218:219], v[222:223], 0, s[12:13]
	s_mov_b32 m0, s52
	s_nop 0
	global_load_lds_dwordx4 v[218:219], off
	v_lshl_add_u64 v[218:219], v[224:225], 0, s[12:13]
	s_mov_b32 m0, s53
	s_nop 0
	global_load_lds_dwordx4 v[218:219], off
	s_waitcnt vmcnt(8)
	s_waitcnt lgkmcnt(0)
	s_setprio 1
	s_barrier
	s_waitcnt lgkmcnt(0)
	v_mfma_f32_16x16x32_bf16 v[60:63], v[128:131], v[178:181], v[60:63]
	v_mfma_f32_16x16x32_bf16 v[56:59], v[136:139], v[178:181], v[56:59]
	v_mfma_f32_16x16x32_bf16 v[44:47], v[128:131], v[186:189], v[44:47]
	v_mfma_f32_16x16x32_bf16 v[40:43], v[136:139], v[186:189], v[40:43]
	v_mfma_f32_16x16x32_bf16 v[28:31], v[128:131], v[194:197], v[28:31]
	v_mfma_f32_16x16x32_bf16 v[24:27], v[136:139], v[194:197], v[24:27]
	v_mfma_f32_16x16x32_bf16 v[12:15], v[128:131], v[210:213], v[12:15]
	v_mfma_f32_16x16x32_bf16 v[8:11], v[136:139], v[210:213], v[8:11]
	v_mfma_f32_16x16x32_bf16 v[60:63], v[132:135], v[182:185], v[60:63]
	v_mfma_f32_16x16x32_bf16 v[56:59], v[140:143], v[182:185], v[56:59]
	v_mfma_f32_16x16x32_bf16 v[44:47], v[132:135], v[190:193], v[44:47]
	v_mfma_f32_16x16x32_bf16 v[40:43], v[140:143], v[190:193], v[40:43]
	v_mfma_f32_16x16x32_bf16 v[28:31], v[132:135], v[206:209], v[28:31]
	v_mfma_f32_16x16x32_bf16 v[24:27], v[140:143], v[206:209], v[24:27]
	v_mfma_f32_16x16x32_bf16 v[12:15], v[132:135], v[214:217], v[12:15]
	v_mfma_f32_16x16x32_bf16 v[8:11], v[140:143], v[214:217], v[8:11]
	s_setprio 0
	s_setprio 1
	v_mfma_f32_16x16x32_bf16 v[52:55], v[144:147], v[178:181], v[52:55]
	v_mfma_f32_16x16x32_bf16 v[48:51], v[152:155], v[178:181], v[48:51]
	v_mfma_f32_16x16x32_bf16 v[36:39], v[144:147], v[186:189], v[36:39]
	v_mfma_f32_16x16x32_bf16 v[32:35], v[152:155], v[186:189], v[32:35]
	v_mfma_f32_16x16x32_bf16 v[20:23], v[144:147], v[194:197], v[20:23]
	v_mfma_f32_16x16x32_bf16 v[16:19], v[152:155], v[194:197], v[16:19]
	v_mfma_f32_16x16x32_bf16 v[4:7], v[144:147], v[210:213], v[4:7]
	v_mfma_f32_16x16x32_bf16 v[0:3], v[152:155], v[210:213], v[0:3]
	v_mfma_f32_16x16x32_bf16 v[52:55], v[148:151], v[182:185], v[52:55]
	v_mfma_f32_16x16x32_bf16 v[48:51], v[156:159], v[182:185], v[48:51]
	v_mfma_f32_16x16x32_bf16 v[36:39], v[148:151], v[190:193], v[36:39]
	v_mfma_f32_16x16x32_bf16 v[32:35], v[156:159], v[190:193], v[32:35]
	v_mfma_f32_16x16x32_bf16 v[20:23], v[148:151], v[206:209], v[20:23]
	v_mfma_f32_16x16x32_bf16 v[16:19], v[156:159], v[206:209], v[16:19]
	s_setprio 3
	s_barrier
	v_mfma_f32_16x16x32_bf16 v[4:7], v[148:151], v[214:217], v[4:7]
	v_mfma_f32_16x16x32_bf16 v[0:3], v[156:159], v[214:217], v[0:3]
	s_setprio 0
	s_add_i32 s62, s62, 2
	s_add_u32 s4, s4, 0x100
	s_addc_u32 s5, s5, 0
	s_add_u32 s60, s60, 0x100
	s_addc_u32 s61, s61, 0
	s_cmp_gt_u32 s62, 13
	s_cbranch_scc0 .LBB0_1033
	s_and_b64 vcc, exec, s[14:15]
	s_cbranch_vccz .LBB0_1036
	s_barrier
